# added: weight-copy phases of layers 1-3 issue 16 loads per trip behind counted waits (were 2 at a time with full waits)
# speedup vs baseline: 1.0123x; 1.0084x over previous
.LBB0_916:
	s_lshl_b32 s69, s64, 1
	s_lshl_b32 s70, s65, 1
	v_or_b32_e32 v56, s69, v1
	v_or_b32_e32 v57, s70, v0
	v_add_lshl_u32 v4, v56, v3, 10
	v_add_lshl_u32 v53, v57, v48, 10
	v_or_b32_e32 v52, v49, v4
	v_or_b32_e32 v4, v50, v53
	v_lshl_add_u64 v[54:55], v[4:5], 2, s[88:89]
	v_mov_b32_e32 v53, v5
	v_lshl_add_u64 v[52:53], v[52:53], 2, s[88:89]
	global_load_dword v126, v[54:55], off
	global_load_dword v127, v[52:53], off
	v_mad_u64_u32 v[52:53], s[72:73], v57, s40, v[2:3]
	v_mad_u64_u32 v[54:55], s[72:73], v56, s40, v[2:3]
	s_add_i32 s71, s69, 4
	s_add_i32 s72, s70, 4
	v_or_b32_e32 v56, s71, v1
	v_or_b32_e32 v57, s72, v0
	v_add_lshl_u32 v53, v57, v48, 10
	s_add_i32 s71, s69, 8
	s_add_i32 s65, s65, 16
	s_add_i32 s64, s64, 16
	s_add_i32 s68, s68, -16
	v_mov_b32_e32 v142, v52
	v_mov_b32_e32 v143, v54
	v_add_lshl_u32 v4, v56, v3, 10
	v_or_b32_e32 v52, v49, v4
	v_or_b32_e32 v4, v50, v53
	v_lshl_add_u64 v[54:55], v[4:5], 2, s[88:89]
	v_mov_b32_e32 v53, v5
	v_lshl_add_u64 v[52:53], v[52:53], 2, s[88:89]
	global_load_dword v128, v[54:55], off
	global_load_dword v129, v[52:53], off
	v_mad_u64_u32 v[52:53], s[72:73], v57, s40, v[2:3]
	v_mad_u64_u32 v[54:55], s[72:73], v56, s40, v[2:3]
	s_add_i32 s72, s70, 8
	v_or_b32_e32 v56, s71, v1
	v_or_b32_e32 v57, s72, v0
	v_add_lshl_u32 v53, v57, v48, 10
	s_add_i32 s71, s69, 12
	v_mov_b32_e32 v144, v52
	v_mov_b32_e32 v145, v54
	v_add_lshl_u32 v4, v56, v3, 10
	v_or_b32_e32 v52, v49, v4
	v_or_b32_e32 v4, v50, v53
	v_lshl_add_u64 v[54:55], v[4:5], 2, s[88:89]
	v_mov_b32_e32 v53, v5
	v_lshl_add_u64 v[52:53], v[52:53], 2, s[88:89]
	global_load_dword v130, v[54:55], off
	global_load_dword v131, v[52:53], off
	v_mad_u64_u32 v[52:53], s[72:73], v57, s40, v[2:3]
	v_mad_u64_u32 v[54:55], s[72:73], v56, s40, v[2:3]
	s_add_i32 s72, s70, 12
	v_or_b32_e32 v56, s71, v1
	v_or_b32_e32 v57, s72, v0
	v_add_lshl_u32 v53, v57, v48, 10
	s_add_i32 s71, s69, 16
	v_mov_b32_e32 v146, v52
	v_mov_b32_e32 v147, v54
	v_add_lshl_u32 v4, v56, v3, 10
	v_or_b32_e32 v52, v49, v4
	v_or_b32_e32 v4, v50, v53
	v_lshl_add_u64 v[54:55], v[4:5], 2, s[88:89]
	v_mov_b32_e32 v53, v5
	v_lshl_add_u64 v[52:53], v[52:53], 2, s[88:89]
	global_load_dword v132, v[54:55], off
	global_load_dword v133, v[52:53], off
	v_mad_u64_u32 v[52:53], s[72:73], v57, s40, v[2:3]
	v_mad_u64_u32 v[54:55], s[72:73], v56, s40, v[2:3]
	s_add_i32 s72, s70, 16
	v_or_b32_e32 v56, s71, v1
	v_or_b32_e32 v57, s72, v0
	v_add_lshl_u32 v53, v57, v48, 10
	s_add_i32 s71, s69, 20
	v_mov_b32_e32 v148, v52
	v_mov_b32_e32 v149, v54
	v_add_lshl_u32 v4, v56, v3, 10
	v_or_b32_e32 v52, v49, v4
	v_or_b32_e32 v4, v50, v53
	v_lshl_add_u64 v[54:55], v[4:5], 2, s[88:89]
	v_mov_b32_e32 v53, v5
	v_lshl_add_u64 v[52:53], v[52:53], 2, s[88:89]
	global_load_dword v134, v[54:55], off
	global_load_dword v135, v[52:53], off
	v_mad_u64_u32 v[52:53], s[72:73], v57, s40, v[2:3]
	v_mad_u64_u32 v[54:55], s[72:73], v56, s40, v[2:3]
	s_add_i32 s72, s70, 20
	v_or_b32_e32 v56, s71, v1
	v_or_b32_e32 v57, s72, v0
	v_add_lshl_u32 v53, v57, v48, 10
	s_add_i32 s71, s69, 24
	s_add_i32 s69, s69, 28
	v_mov_b32_e32 v150, v52
	v_mov_b32_e32 v151, v54
	v_add_lshl_u32 v4, v56, v3, 10
	v_or_b32_e32 v52, v49, v4
	v_or_b32_e32 v4, v50, v53
	v_lshl_add_u64 v[54:55], v[4:5], 2, s[88:89]
	v_mov_b32_e32 v53, v5
	v_lshl_add_u64 v[52:53], v[52:53], 2, s[88:89]
	global_load_dword v136, v[54:55], off
	global_load_dword v137, v[52:53], off
	v_mad_u64_u32 v[52:53], s[72:73], v57, s40, v[2:3]
	v_mad_u64_u32 v[54:55], s[72:73], v56, s40, v[2:3]
	s_add_i32 s72, s70, 24
	v_or_b32_e32 v56, s71, v1
	v_or_b32_e32 v57, s72, v0
	v_add_lshl_u32 v53, v57, v48, 10
	s_add_i32 s70, s70, 28
	s_cmp_lg_u32 s68, 0
	v_mov_b32_e32 v152, v52
	v_mov_b32_e32 v153, v54
	v_add_lshl_u32 v4, v56, v3, 10
	v_or_b32_e32 v52, v49, v4
	v_or_b32_e32 v4, v50, v53
	v_lshl_add_u64 v[54:55], v[4:5], 2, s[88:89]
	v_mov_b32_e32 v53, v5
	v_lshl_add_u64 v[52:53], v[52:53], 2, s[88:89]
	global_load_dword v138, v[54:55], off
	global_load_dword v139, v[52:53], off
	v_mad_u64_u32 v[52:53], s[72:73], v57, s40, v[2:3]
	v_mad_u64_u32 v[54:55], s[72:73], v56, s40, v[2:3]
	v_or_b32_e32 v56, s69, v1
	v_or_b32_e32 v57, s70, v0
	v_mov_b32_e32 v55, v5
	v_mov_b32_e32 v154, v52
	v_mov_b32_e32 v155, v54
	v_add_lshl_u32 v4, v56, v3, 10
	v_add_lshl_u32 v52, v57, v48, 10
	v_or_b32_e32 v54, v49, v4
	v_or_b32_e32 v4, v50, v52
	v_lshl_add_u64 v[52:53], v[4:5], 2, s[88:89]
	v_lshl_add_u64 v[54:55], v[54:55], 2, s[88:89]
	global_load_dword v140, v[52:53], off
	global_load_dword v141, v[54:55], off
	v_mad_u64_u32 v[52:53], s[70:71], v57, s40, v[2:3]
	v_mad_u64_u32 v[54:55], s[70:71], v56, s40, v[2:3]
	v_mov_b32_e32 v156, v52
	v_mov_b32_e32 v157, v54
	s_waitcnt vmcnt(15)
	ds_write_b32 v142, v126
	s_waitcnt vmcnt(14)
	ds_write_b32 v143, v127
	s_waitcnt vmcnt(13)
	ds_write_b32 v144, v128
	s_waitcnt vmcnt(12)
	ds_write_b32 v145, v129
	s_waitcnt vmcnt(11)
	ds_write_b32 v146, v130
	s_waitcnt vmcnt(10)
	ds_write_b32 v147, v131
	s_waitcnt vmcnt(9)
	ds_write_b32 v148, v132
	s_waitcnt vmcnt(8)
	ds_write_b32 v149, v133
	s_waitcnt vmcnt(7)
	ds_write_b32 v150, v134
	s_waitcnt vmcnt(6)
	ds_write_b32 v151, v135
	s_waitcnt vmcnt(5)
	ds_write_b32 v152, v136
	s_waitcnt vmcnt(4)
	ds_write_b32 v153, v137
	s_waitcnt vmcnt(3)
	ds_write_b32 v154, v138
	s_waitcnt vmcnt(2)
	ds_write_b32 v155, v139
	s_waitcnt vmcnt(1)
	ds_write_b32 v156, v140
	s_waitcnt vmcnt(0)
	ds_write_b32 v157, v141
	s_cbranch_scc1 .LBB0_916
	v_or_b32_e32 v3, v51, v96
	v_lshlrev_b32_e32 v4, 2, v3
	v_or_b32_e32 v49, 0x5000, v4
	global_load_dword v90, v49, s[12:13]
	global_load_dword v80, v49, s[92:93]
	v_or_b32_e32 v49, 0x5020, v4
	global_load_dword v62, v49, s[12:13]
	global_load_dword v60, v49, s[92:93]
	v_or_b32_e32 v49, 0x5040, v4
	global_load_dword v58, v49, s[12:13]
	global_load_dword v56, v49, s[92:93]
	v_or_b32_e32 v4, 0x5060, v4
	global_load_dword v52, v4, s[12:13]
	global_load_dword v50, v4, s[92:93]
	s_waitcnt lgkmcnt(0)
	ds_read2_b32 v[74:75], v97 offset0:33 offset1:41
	ds_read2_b32 v[66:67], v97 offset0:66 offset1:74
	ds_read2_b32 v[64:65], v97 offset0:99 offset1:107
	ds_read2_b32 v[76:77], v97 offset0:132 offset1:140
	ds_read2_b32 v[72:73], v97 offset0:165 offset1:173
	ds_read2_b32 v[70:71], v97 offset0:198 offset1:206
	ds_read2_b32 v[68:69], v97 offset0:231 offset1:239
	ds_read2_b32 v[78:79], v97 offset1:8
	s_waitcnt lgkmcnt(4)
	v_mov_b32_e32 v86, v76
	v_mov_b32_e32 v83, v66
	s_waitcnt lgkmcnt(2)
	v_mov_b32_e32 v87, v70
	v_mov_b32_e32 v84, v74
	s_waitcnt lgkmcnt(0)
	v_mov_b32_e32 v82, v78
	v_mov_b32_e32 v85, v64
	v_mov_b32_e32 v88, v72
	v_mov_b32_e32 v89, v68
	v_lshlrev_b32_e32 v4, 1, v48
	v_lshl_add_u64 v[54:55], v[6:7], 0, v[4:5]
	v_lshl_add_u64 v[48:49], v[22:23], 0, v[4:5]
	v_mul_u32_u24_e32 v3, 0xb00, v3
	v_mov_b32_e32 v70, v77
	v_mov_b32_e32 v68, v73
	s_waitcnt vmcnt(7)
	v_pk_mul_f32 v[112:113], v[90:91], v[86:87] op_sel_hi:[0,1]
	v_pk_mul_f32 v[92:93], v[90:91], v[82:83] op_sel_hi:[0,1]
	v_pk_mul_f32 v[110:111], v[90:91], v[84:85] op_sel_hi:[0,1]
	v_pk_mul_f32 v[90:91], v[90:91], v[88:89] op_sel_hi:[0,1]
	v_bfe_u32 v64, v112, 16, 1
	v_bfe_u32 v66, v113, 16, 1
	v_bfe_u32 v4, v91, 16, 1
	v_bfe_u32 v53, v90, 16, 1
	v_bfe_u32 v63, v93, 16, 1
	v_add3_u32 v66, v113, v66, s46
	v_add3_u32 v64, v112, v64, s46
	v_bfe_u32 v57, v111, 16, 1
	v_add3_u32 v53, v90, v53, s46
	v_add3_u32 v4, v91, v4, s46
	v_bfe_u32 v61, v92, 16, 1
	v_add3_u32 v63, v93, v63, s46
	v_lshrrev_b32_e32 v64, 16, v64
	v_lshrrev_b32_e32 v66, 16, v66
	s_waitcnt vmcnt(6)
	v_pk_mul_f32 v[86:87], v[80:81], v[86:87] op_sel_hi:[0,1]
	v_bfe_u32 v59, v110, 16, 1
	v_add3_u32 v57, v111, v57, s46
	v_add3_u32 v61, v92, v61, s46
	v_lshrrev_b32_e32 v63, 16, v63
	v_and_or_b32 v93, v4, s47, v66
	v_and_or_b32 v92, v53, s47, v64
	v_pk_mul_f32 v[82:83], v[80:81], v[82:83] op_sel_hi:[0,1]
	v_pk_mul_f32 v[84:85], v[80:81], v[84:85] op_sel_hi:[0,1]
	v_pk_mul_f32 v[80:81], v[80:81], v[88:89] op_sel_hi:[0,1]
	v_bfe_u32 v64, v86, 16, 1
	v_bfe_u32 v66, v87, 16, 1
	v_add3_u32 v59, v110, v59, s46
	v_lshrrev_b32_e32 v61, 16, v61
	v_and_or_b32 v91, v57, s47, v63
	v_lshlrev_b32_e32 v4, 1, v3
	v_bfe_u32 v3, v81, 16, 1
	v_bfe_u32 v53, v80, 16, 1
	v_bfe_u32 v63, v83, 16, 1
	v_add3_u32 v66, v87, v66, s46
	v_add3_u32 v64, v86, v64, s46
	v_and_or_b32 v90, v59, s47, v61
	v_bfe_u32 v57, v85, 16, 1
	v_add3_u32 v53, v80, v53, s46
	v_add3_u32 v3, v81, v3, s46
	v_bfe_u32 v61, v82, 16, 1
	v_add3_u32 v63, v83, v63, s46
	v_lshrrev_b32_e32 v64, 16, v64
	v_lshrrev_b32_e32 v66, 16, v66
	v_add3_u32 v57, v85, v57, s46
	v_add3_u32 v61, v82, v61, s46
	v_lshrrev_b32_e32 v63, 16, v63
	v_and_or_b32 v83, v3, s47, v66
	v_and_or_b32 v82, v53, s47, v64
	v_mov_b32_e32 v66, v79
	v_mov_b32_e32 v64, v75
	v_and_or_b32 v81, v57, s47, v63
	s_waitcnt vmcnt(5)
	v_pk_mul_f32 v[78:79], v[62:63], v[66:67] op_sel_hi:[0,1]
	v_pk_mul_f32 v[74:75], v[62:63], v[64:65] op_sel_hi:[0,1]
	v_pk_mul_f32 v[76:77], v[62:63], v[70:71] op_sel_hi:[0,1]
	v_pk_mul_f32 v[62:63], v[62:63], v[68:69] op_sel_hi:[0,1]
	v_bfe_u32 v3, v63, 16, 1
	v_bfe_u32 v59, v84, 16, 1
	v_add3_u32 v3, v63, v3, s46
	v_bfe_u32 v63, v77, 16, 1
	v_lshl_add_u64 v[110:111], v[54:55], 0, v[4:5]
	v_add3_u32 v59, v84, v59, s46
	v_lshl_add_u64 v[84:85], v[48:49], 0, v[4:5]
	v_bfe_u32 v4, v62, 16, 1
	v_add3_u32 v63, v77, v63, s46
	v_lshrrev_b32_e32 v61, 16, v61
	v_bfe_u32 v53, v75, 16, 1
	v_add3_u32 v4, v62, v4, s46
	v_bfe_u32 v62, v76, 16, 1
	v_lshrrev_b32_e32 v63, 16, v63
	v_and_or_b32 v80, v59, s47, v61
	v_add3_u32 v53, v75, v53, s46
	v_bfe_u32 v59, v78, 16, 1
	v_bfe_u32 v61, v79, 16, 1
	v_add3_u32 v62, v76, v62, s46
	v_and_or_b32 v75, v3, s47, v63
	v_or_b32_e32 v3, v51, v98
	v_bfe_u32 v57, v74, 16, 1
	v_add3_u32 v61, v79, v61, s46
	v_add3_u32 v59, v78, v59, s46
	v_lshrrev_b32_e32 v62, 16, v62
	v_mul_u32_u24_e32 v3, 0xb00, v3
	v_add3_u32 v57, v74, v57, s46
	v_lshrrev_b32_e32 v59, 16, v59
	v_lshrrev_b32_e32 v61, 16, v61
	v_and_or_b32 v74, v4, s47, v62
	v_lshlrev_b32_e32 v4, 1, v3
	v_and_or_b32 v73, v53, s47, v61
	v_and_or_b32 v72, v57, s47, v59
	v_lshl_add_u64 v[62:63], v[54:55], 0, v[4:5]
	global_store_dwordx4 v[110:111], v[90:93], off
	global_store_dwordx4 v[84:85], v[80:83], off
	global_store_dwordx4 v[62:63], v[72:75], off
	s_waitcnt vmcnt(7)
	v_pk_mul_f32 v[62:63], v[60:61], v[66:67] op_sel_hi:[0,1]
	v_pk_mul_f32 v[64:65], v[60:61], v[64:65] op_sel_hi:[0,1]
	v_pk_mul_f32 v[66:67], v[60:61], v[70:71] op_sel_hi:[0,1]
	v_pk_mul_f32 v[60:61], v[60:61], v[68:69] op_sel_hi:[0,1]
	v_bfe_u32 v3, v61, 16, 1
	v_bfe_u32 v53, v60, 16, 1
	v_bfe_u32 v57, v65, 16, 1
	v_bfe_u32 v59, v64, 16, 1
	v_add3_u32 v59, v64, v59, s46
	v_add3_u32 v57, v65, v57, s46
	v_add3_u32 v53, v60, v53, s46
	v_add3_u32 v3, v61, v3, s46
	v_bfe_u32 v60, v62, 16, 1
	v_bfe_u32 v61, v63, 16, 1
	v_bfe_u32 v64, v66, 16, 1
	v_bfe_u32 v65, v67, 16, 1
	v_add3_u32 v65, v67, v65, s46
	v_add3_u32 v64, v66, v64, s46
	v_add3_u32 v61, v63, v61, s46
	v_add3_u32 v60, v62, v60, s46
	v_lshrrev_b32_e32 v60, 16, v60
	v_lshrrev_b32_e32 v61, 16, v61
	v_lshrrev_b32_e32 v62, 16, v64
	v_lshrrev_b32_e32 v63, 16, v65
	v_and_or_b32 v63, v3, s47, v63
	v_and_or_b32 v62, v53, s47, v62
	v_and_or_b32 v61, v57, s47, v61
	v_and_or_b32 v60, v59, s47, v60
	v_lshl_add_u64 v[64:65], v[48:49], 0, v[4:5]
	global_store_dwordx4 v[64:65], v[60:63], off
	ds_read2_b32 v[62:63], v97 offset0:16 offset1:24
	ds_read2_b32 v[64:65], v97 offset0:49 offset1:57
	ds_read2_b32 v[66:67], v97 offset0:82 offset1:90
	ds_read2_b32 v[68:69], v97 offset0:115 offset1:123
	ds_read2_b32 v[70:71], v97 offset0:148 offset1:156
	ds_read2_b32 v[72:73], v97 offset0:181 offset1:189
	ds_read2_b32 v[74:75], v97 offset0:214 offset1:222
	ds_read2_b32 v[76:77], v97 offset0:247 offset1:255
	s_waitcnt lgkmcnt(7)
	v_mov_b32_e32 v78, v62
	s_waitcnt lgkmcnt(5)
	v_mov_b32_e32 v79, v66
	v_mov_b32_e32 v80, v64
	s_waitcnt lgkmcnt(4)
	v_mov_b32_e32 v81, v68
	s_waitcnt lgkmcnt(3)
	v_mov_b32_e32 v84, v70
	s_waitcnt lgkmcnt(1)
	v_mov_b32_e32 v85, v74
	v_mov_b32_e32 v88, v72
	s_waitcnt lgkmcnt(0)
	v_mov_b32_e32 v89, v76
	s_waitcnt vmcnt(7)
	v_pk_mul_f32 v[60:61], v[58:59], v[78:79] op_sel_hi:[0,1]
	v_pk_mul_f32 v[82:83], v[58:59], v[80:81] op_sel_hi:[0,1]
	v_pk_mul_f32 v[86:87], v[58:59], v[84:85] op_sel_hi:[0,1]
	v_pk_mul_f32 v[58:59], v[58:59], v[88:89] op_sel_hi:[0,1]
	v_bfe_u32 v3, v59, 16, 1
	v_bfe_u32 v64, v87, 16, 1
	v_add3_u32 v3, v59, v3, s46
	v_bfe_u32 v59, v61, 16, 1
	v_add3_u32 v64, v87, v64, s46
	v_bfe_u32 v4, v58, 16, 1
	v_bfe_u32 v62, v86, 16, 1
	v_add3_u32 v59, v61, v59, s46
	v_lshrrev_b32_e32 v61, 16, v64
	v_add3_u32 v4, v58, v4, s46
	v_bfe_u32 v58, v60, 16, 1
	v_add3_u32 v62, v86, v62, s46
	v_and_or_b32 v61, v3, s47, v61
	v_or_b32_e32 v3, v51, v99
	v_bfe_u32 v53, v83, 16, 1
	v_bfe_u32 v57, v82, 16, 1
	v_add3_u32 v58, v60, v58, s46
	v_lshrrev_b32_e32 v60, 16, v62
	v_mul_u32_u24_e32 v3, 0xb00, v3
	v_add3_u32 v57, v82, v57, s46
	v_add3_u32 v53, v83, v53, s46
	v_lshrrev_b32_e32 v58, 16, v58
	v_lshrrev_b32_e32 v59, 16, v59
	v_and_or_b32 v60, v4, s47, v60
	v_lshlrev_b32_e32 v4, 1, v3
	v_and_or_b32 v59, v53, s47, v59
	v_and_or_b32 v58, v57, s47, v58
	v_lshl_add_u64 v[82:83], v[54:55], 0, v[4:5]
	global_store_dwordx4 v[82:83], v[58:61], off
	v_mov_b32_e32 v68, v65
	v_mov_b32_e32 v66, v63
	s_waitcnt vmcnt(7)
	v_pk_mul_f32 v[58:59], v[56:57], v[78:79] op_sel_hi:[0,1]
	v_pk_mul_f32 v[60:61], v[56:57], v[80:81] op_sel_hi:[0,1]
	v_pk_mul_f32 v[78:79], v[56:57], v[84:85] op_sel_hi:[0,1]
	v_pk_mul_f32 v[56:57], v[56:57], v[88:89] op_sel_hi:[0,1]
	v_bfe_u32 v3, v57, 16, 1
	v_bfe_u32 v53, v56, 16, 1
	v_bfe_u32 v62, v61, 16, 1
	v_bfe_u32 v64, v60, 16, 1
	v_add3_u32 v60, v60, v64, s46
	v_add3_u32 v61, v61, v62, s46
	v_add3_u32 v53, v56, v53, s46
	v_add3_u32 v3, v57, v3, s46
	v_bfe_u32 v56, v58, 16, 1
	v_bfe_u32 v57, v59, 16, 1
	v_bfe_u32 v62, v78, 16, 1
	v_bfe_u32 v64, v79, 16, 1
	v_add3_u32 v64, v79, v64, s46
	v_add3_u32 v62, v78, v62, s46
	v_add3_u32 v57, v59, v57, s46
	v_add3_u32 v56, v58, v56, s46
	v_lshrrev_b32_e32 v56, 16, v56
	v_lshrrev_b32_e32 v57, 16, v57
	v_lshrrev_b32_e32 v58, 16, v62
	v_lshrrev_b32_e32 v59, 16, v64
	v_and_or_b32 v59, v3, s47, v59
	v_and_or_b32 v58, v53, s47, v58
	v_and_or_b32 v57, v61, s47, v57
	v_and_or_b32 v56, v60, s47, v56
	v_lshl_add_u64 v[60:61], v[48:49], 0, v[4:5]
	global_store_dwordx4 v[60:61], v[56:59], off
	v_mov_b32_e32 v74, v71
	v_mov_b32_e32 v76, v73
	s_waitcnt vmcnt(7)
	v_pk_mul_f32 v[58:59], v[52:53], v[68:69] op_sel_hi:[0,1]
	v_pk_mul_f32 v[56:57], v[52:53], v[66:67] op_sel_hi:[0,1]
	v_pk_mul_f32 v[60:61], v[52:53], v[74:75] op_sel_hi:[0,1]
	v_pk_mul_f32 v[52:53], v[52:53], v[76:77] op_sel_hi:[0,1]
	v_bfe_u32 v62, v59, 16, 1
	v_bfe_u32 v3, v53, 16, 1
	v_add3_u32 v62, v59, v62, s46
	v_bfe_u32 v59, v61, 16, 1
	v_bfe_u32 v63, v58, 16, 1
	v_add3_u32 v3, v53, v3, s46
	v_bfe_u32 v53, v57, 16, 1
	v_add3_u32 v59, v61, v59, s46
	v_bfe_u32 v4, v52, 16, 1
	v_add3_u32 v63, v58, v63, s46
	v_bfe_u32 v58, v60, 16, 1
	v_add3_u32 v53, v57, v53, s46
	v_lshrrev_b32_e32 v57, 16, v59
	v_add3_u32 v4, v52, v4, s46
	v_bfe_u32 v52, v56, 16, 1
	v_add3_u32 v58, v60, v58, s46
	v_and_or_b32 v59, v3, s47, v57
	v_or_b32_e32 v3, v51, v100
	v_add3_u32 v52, v56, v52, s46
	v_lshrrev_b32_e32 v56, 16, v58
	v_mul_u32_u24_e32 v3, 0xb00, v3
	v_lshrrev_b32_e32 v52, 16, v52
	v_lshrrev_b32_e32 v53, 16, v53
	v_and_or_b32 v58, v4, s47, v56
	v_lshlrev_b32_e32 v4, 1, v3
	v_and_or_b32 v57, v62, s47, v53
	v_and_or_b32 v56, v63, s47, v52
	v_lshl_add_u64 v[52:53], v[54:55], 0, v[4:5]
	global_store_dwordx4 v[52:53], v[56:59], off
	s_waitcnt vmcnt(7)
	v_pk_mul_f32 v[52:53], v[50:51], v[66:67] op_sel_hi:[0,1]
	v_pk_mul_f32 v[54:55], v[50:51], v[68:69] op_sel_hi:[0,1]
	v_pk_mul_f32 v[56:57], v[50:51], v[74:75] op_sel_hi:[0,1]
	v_pk_mul_f32 v[50:51], v[50:51], v[76:77] op_sel_hi:[0,1]
	v_bfe_u32 v3, v51, 16, 1
	v_bfe_u32 v58, v50, 16, 1
	v_bfe_u32 v59, v55, 16, 1
	v_bfe_u32 v60, v54, 16, 1
	v_add3_u32 v54, v54, v60, s46
	v_add3_u32 v55, v55, v59, s46
	v_add3_u32 v50, v50, v58, s46
	v_add3_u32 v3, v51, v3, s46
	v_bfe_u32 v51, v52, 16, 1
	v_bfe_u32 v58, v53, 16, 1
	v_bfe_u32 v59, v56, 16, 1
	v_bfe_u32 v60, v57, 16, 1
	v_add3_u32 v57, v57, v60, s46
	v_add3_u32 v56, v56, v59, s46
	v_add3_u32 v53, v53, v58, s46
	v_add3_u32 v51, v52, v51, s46
	v_lshrrev_b32_e32 v58, 16, v51
	v_lshrrev_b32_e32 v51, 16, v53
	v_lshrrev_b32_e32 v52, 16, v56
	v_lshrrev_b32_e32 v53, 16, v57
	v_and_or_b32 v53, v3, s47, v53
	v_and_or_b32 v52, v50, s47, v52
	v_and_or_b32 v51, v55, s47, v51
	v_and_or_b32 v50, v54, s47, v58
	v_lshl_add_u64 v[48:49], v[48:49], 0, v[4:5]
	global_store_dwordx4 v[48:49], v[50:53], off
	s_waitcnt lgkmcnt(0)

.LBB0_920:
	s_lshl_b32 s69, s64, 1
	s_lshl_b32 s70, s65, 1
	v_or_b32_e32 v56, s69, v1
	v_or_b32_e32 v57, s70, v0
	v_add_lshl_u32 v4, v56, v3, 10
	v_add_lshl_u32 v53, v57, v48, 10
	v_or_b32_e32 v52, v49, v4
	v_or_b32_e32 v4, v50, v53
	v_lshl_add_u64 v[54:55], v[4:5], 2, s[60:61]
	v_mov_b32_e32 v53, v5
	v_lshl_add_u64 v[52:53], v[52:53], 2, s[60:61]
	global_load_dword v126, v[54:55], off
	global_load_dword v127, v[52:53], off
	v_mad_u64_u32 v[52:53], s[72:73], v57, s40, v[2:3]
	v_mad_u64_u32 v[54:55], s[72:73], v56, s40, v[2:3]
	s_add_i32 s71, s69, 4
	s_add_i32 s72, s70, 4
	v_or_b32_e32 v56, s71, v1
	v_or_b32_e32 v57, s72, v0
	v_add_lshl_u32 v53, v57, v48, 10
	s_add_i32 s71, s69, 8
	s_add_i32 s65, s65, 16
	s_add_i32 s64, s64, 16
	s_add_i32 s68, s68, -16
	v_mov_b32_e32 v142, v52
	v_mov_b32_e32 v143, v54
	v_add_lshl_u32 v4, v56, v3, 10
	v_or_b32_e32 v52, v49, v4
	v_or_b32_e32 v4, v50, v53
	v_lshl_add_u64 v[54:55], v[4:5], 2, s[60:61]
	v_mov_b32_e32 v53, v5
	v_lshl_add_u64 v[52:53], v[52:53], 2, s[60:61]
	global_load_dword v128, v[54:55], off
	global_load_dword v129, v[52:53], off
	v_mad_u64_u32 v[52:53], s[72:73], v57, s40, v[2:3]
	v_mad_u64_u32 v[54:55], s[72:73], v56, s40, v[2:3]
	s_add_i32 s72, s70, 8
	v_or_b32_e32 v56, s71, v1
	v_or_b32_e32 v57, s72, v0
	v_add_lshl_u32 v53, v57, v48, 10
	s_add_i32 s71, s69, 12
	v_mov_b32_e32 v144, v52
	v_mov_b32_e32 v145, v54
	v_add_lshl_u32 v4, v56, v3, 10
	v_or_b32_e32 v52, v49, v4
	v_or_b32_e32 v4, v50, v53
	v_lshl_add_u64 v[54:55], v[4:5], 2, s[60:61]
	v_mov_b32_e32 v53, v5
	v_lshl_add_u64 v[52:53], v[52:53], 2, s[60:61]
	global_load_dword v130, v[54:55], off
	global_load_dword v131, v[52:53], off
	v_mad_u64_u32 v[52:53], s[72:73], v57, s40, v[2:3]
	v_mad_u64_u32 v[54:55], s[72:73], v56, s40, v[2:3]
	s_add_i32 s72, s70, 12
	v_or_b32_e32 v56, s71, v1
	v_or_b32_e32 v57, s72, v0
	v_add_lshl_u32 v53, v57, v48, 10
	s_add_i32 s71, s69, 16
	v_mov_b32_e32 v146, v52
	v_mov_b32_e32 v147, v54
	v_add_lshl_u32 v4, v56, v3, 10
	v_or_b32_e32 v52, v49, v4
	v_or_b32_e32 v4, v50, v53
	v_lshl_add_u64 v[54:55], v[4:5], 2, s[60:61]
	v_mov_b32_e32 v53, v5
	v_lshl_add_u64 v[52:53], v[52:53], 2, s[60:61]
	global_load_dword v132, v[54:55], off
	global_load_dword v133, v[52:53], off
	v_mad_u64_u32 v[52:53], s[72:73], v57, s40, v[2:3]
	v_mad_u64_u32 v[54:55], s[72:73], v56, s40, v[2:3]
	s_add_i32 s72, s70, 16
	v_or_b32_e32 v56, s71, v1
	v_or_b32_e32 v57, s72, v0
	v_add_lshl_u32 v53, v57, v48, 10
	s_add_i32 s71, s69, 20
	v_mov_b32_e32 v148, v52
	v_mov_b32_e32 v149, v54
	v_add_lshl_u32 v4, v56, v3, 10
	v_or_b32_e32 v52, v49, v4
	v_or_b32_e32 v4, v50, v53
	v_lshl_add_u64 v[54:55], v[4:5], 2, s[60:61]
	v_mov_b32_e32 v53, v5
	v_lshl_add_u64 v[52:53], v[52:53], 2, s[60:61]
	global_load_dword v134, v[54:55], off
	global_load_dword v135, v[52:53], off
	v_mad_u64_u32 v[52:53], s[72:73], v57, s40, v[2:3]
	v_mad_u64_u32 v[54:55], s[72:73], v56, s40, v[2:3]
	s_add_i32 s72, s70, 20
	v_or_b32_e32 v56, s71, v1
	v_or_b32_e32 v57, s72, v0
	v_add_lshl_u32 v53, v57, v48, 10
	s_add_i32 s71, s69, 24
	s_add_i32 s69, s69, 28
	v_mov_b32_e32 v150, v52
	v_mov_b32_e32 v151, v54
	v_add_lshl_u32 v4, v56, v3, 10
	v_or_b32_e32 v52, v49, v4
	v_or_b32_e32 v4, v50, v53
	v_lshl_add_u64 v[54:55], v[4:5], 2, s[60:61]
	v_mov_b32_e32 v53, v5
	v_lshl_add_u64 v[52:53], v[52:53], 2, s[60:61]
	global_load_dword v136, v[54:55], off
	global_load_dword v137, v[52:53], off
	v_mad_u64_u32 v[52:53], s[72:73], v57, s40, v[2:3]
	v_mad_u64_u32 v[54:55], s[72:73], v56, s40, v[2:3]
	s_add_i32 s72, s70, 24
	v_or_b32_e32 v56, s71, v1
	v_or_b32_e32 v57, s72, v0
	v_add_lshl_u32 v53, v57, v48, 10
	s_add_i32 s70, s70, 28
	s_cmp_lg_u32 s68, 0
	v_mov_b32_e32 v152, v52
	v_mov_b32_e32 v153, v54
	v_add_lshl_u32 v4, v56, v3, 10
	v_or_b32_e32 v52, v49, v4
	v_or_b32_e32 v4, v50, v53
	v_lshl_add_u64 v[54:55], v[4:5], 2, s[60:61]
	v_mov_b32_e32 v53, v5
	v_lshl_add_u64 v[52:53], v[52:53], 2, s[60:61]
	global_load_dword v138, v[54:55], off
	global_load_dword v139, v[52:53], off
	v_mad_u64_u32 v[52:53], s[72:73], v57, s40, v[2:3]
	v_mad_u64_u32 v[54:55], s[72:73], v56, s40, v[2:3]
	v_or_b32_e32 v56, s69, v1
	v_or_b32_e32 v57, s70, v0
	v_mov_b32_e32 v55, v5
	v_mov_b32_e32 v154, v52
	v_mov_b32_e32 v155, v54
	v_add_lshl_u32 v4, v56, v3, 10
	v_add_lshl_u32 v52, v57, v48, 10
	v_or_b32_e32 v54, v49, v4
	v_or_b32_e32 v4, v50, v52
	v_lshl_add_u64 v[52:53], v[4:5], 2, s[60:61]
	v_lshl_add_u64 v[54:55], v[54:55], 2, s[60:61]
	global_load_dword v140, v[52:53], off
	global_load_dword v141, v[54:55], off
	v_mad_u64_u32 v[52:53], s[70:71], v57, s40, v[2:3]
	v_mad_u64_u32 v[54:55], s[70:71], v56, s40, v[2:3]
	v_mov_b32_e32 v156, v52
	v_mov_b32_e32 v157, v54
	s_waitcnt vmcnt(15)
	ds_write_b32 v142, v126
	s_waitcnt vmcnt(14)
	ds_write_b32 v143, v127
	s_waitcnt vmcnt(13)
	ds_write_b32 v144, v128
	s_waitcnt vmcnt(12)
	ds_write_b32 v145, v129
	s_waitcnt vmcnt(11)
	ds_write_b32 v146, v130
	s_waitcnt vmcnt(10)
	ds_write_b32 v147, v131
	s_waitcnt vmcnt(9)
	ds_write_b32 v148, v132
	s_waitcnt vmcnt(8)
	ds_write_b32 v149, v133
	s_waitcnt vmcnt(7)
	ds_write_b32 v150, v134
	s_waitcnt vmcnt(6)
	ds_write_b32 v151, v135
	s_waitcnt vmcnt(5)
	ds_write_b32 v152, v136
	s_waitcnt vmcnt(4)
	ds_write_b32 v153, v137
	s_waitcnt vmcnt(3)
	ds_write_b32 v154, v138
	s_waitcnt vmcnt(2)
	ds_write_b32 v155, v139
	s_waitcnt vmcnt(1)
	ds_write_b32 v156, v140
	s_waitcnt vmcnt(0)
	ds_write_b32 v157, v141
	s_cbranch_scc1 .LBB0_920
	v_or_b32_e32 v3, v51, v96
	v_lshlrev_b32_e32 v4, 2, v3
	v_or_b32_e32 v49, 0x2000, v4
	global_load_dword v90, v49, s[12:13]
	global_load_dword v80, v49, s[92:93]
	v_or_b32_e32 v49, 0x2020, v4
	global_load_dword v62, v49, s[12:13]
	global_load_dword v60, v49, s[92:93]
	v_or_b32_e32 v49, 0x2040, v4
	global_load_dword v58, v49, s[12:13]
	global_load_dword v56, v49, s[92:93]
	v_or_b32_e32 v4, 0x2060, v4
	global_load_dword v52, v4, s[12:13]
	global_load_dword v50, v4, s[92:93]
	s_waitcnt lgkmcnt(0)
	ds_read2_b32 v[74:75], v97 offset0:33 offset1:41
	ds_read2_b32 v[66:67], v97 offset0:66 offset1:74
	ds_read2_b32 v[64:65], v97 offset0:99 offset1:107
	ds_read2_b32 v[76:77], v97 offset0:132 offset1:140
	ds_read2_b32 v[72:73], v97 offset0:165 offset1:173
	ds_read2_b32 v[70:71], v97 offset0:198 offset1:206
	ds_read2_b32 v[68:69], v97 offset0:231 offset1:239
	ds_read2_b32 v[78:79], v97 offset1:8
	s_waitcnt lgkmcnt(4)
	v_mov_b32_e32 v86, v76
	v_mov_b32_e32 v83, v66
	s_waitcnt lgkmcnt(2)
	v_mov_b32_e32 v87, v70
	v_mov_b32_e32 v84, v74
	s_waitcnt lgkmcnt(0)
	v_mov_b32_e32 v82, v78
	v_mov_b32_e32 v85, v64
	v_mov_b32_e32 v88, v72
	v_mov_b32_e32 v89, v68
	v_lshlrev_b32_e32 v4, 1, v48
	v_lshl_add_u64 v[54:55], v[8:9], 0, v[4:5]
	v_lshl_add_u64 v[48:49], v[24:25], 0, v[4:5]
	v_mov_b32_e32 v70, v77
	v_mov_b32_e32 v68, v73
	s_waitcnt vmcnt(7)
	v_pk_mul_f32 v[112:113], v[90:91], v[86:87] op_sel_hi:[0,1]
	v_pk_mul_f32 v[92:93], v[90:91], v[82:83] op_sel_hi:[0,1]
	v_pk_mul_f32 v[110:111], v[90:91], v[84:85] op_sel_hi:[0,1]
	v_pk_mul_f32 v[90:91], v[90:91], v[88:89] op_sel_hi:[0,1]
	v_bfe_u32 v64, v112, 16, 1
	v_bfe_u32 v66, v113, 16, 1
	v_bfe_u32 v4, v91, 16, 1
	v_bfe_u32 v53, v90, 16, 1
	v_bfe_u32 v63, v93, 16, 1
	v_add3_u32 v66, v113, v66, s46
	v_add3_u32 v64, v112, v64, s46
	v_bfe_u32 v57, v111, 16, 1
	v_add3_u32 v53, v90, v53, s46
	v_add3_u32 v4, v91, v4, s46
	v_bfe_u32 v61, v92, 16, 1
	v_add3_u32 v63, v93, v63, s46
	v_lshrrev_b32_e32 v64, 16, v64
	v_lshrrev_b32_e32 v66, 16, v66
	s_waitcnt vmcnt(6)
	v_pk_mul_f32 v[86:87], v[80:81], v[86:87] op_sel_hi:[0,1]
	v_bfe_u32 v59, v110, 16, 1
	v_add3_u32 v57, v111, v57, s46
	v_add3_u32 v61, v92, v61, s46
	v_lshrrev_b32_e32 v63, 16, v63
	v_and_or_b32 v93, v4, s47, v66
	v_and_or_b32 v92, v53, s47, v64
	v_pk_mul_f32 v[82:83], v[80:81], v[82:83] op_sel_hi:[0,1]
	v_pk_mul_f32 v[84:85], v[80:81], v[84:85] op_sel_hi:[0,1]
	v_pk_mul_f32 v[80:81], v[80:81], v[88:89] op_sel_hi:[0,1]
	v_bfe_u32 v64, v86, 16, 1
	v_bfe_u32 v66, v87, 16, 1
	v_add3_u32 v59, v110, v59, s46
	v_lshrrev_b32_e32 v61, 16, v61
	v_and_or_b32 v91, v57, s47, v63
	v_lshlrev_b32_e32 v4, 11, v3
	v_bfe_u32 v3, v81, 16, 1
	v_bfe_u32 v53, v80, 16, 1
	v_bfe_u32 v63, v83, 16, 1
	v_add3_u32 v66, v87, v66, s46
	v_add3_u32 v64, v86, v64, s46
	v_and_or_b32 v90, v59, s47, v61
	v_bfe_u32 v57, v85, 16, 1
	v_add3_u32 v53, v80, v53, s46
	v_add3_u32 v3, v81, v3, s46
	v_bfe_u32 v61, v82, 16, 1
	v_add3_u32 v63, v83, v63, s46
	v_lshrrev_b32_e32 v64, 16, v64
	v_lshrrev_b32_e32 v66, 16, v66
	v_add3_u32 v57, v85, v57, s46
	v_add3_u32 v61, v82, v61, s46
	v_lshrrev_b32_e32 v63, 16, v63
	v_and_or_b32 v83, v3, s47, v66
	v_and_or_b32 v82, v53, s47, v64
	v_mov_b32_e32 v66, v79
	v_mov_b32_e32 v64, v75
	v_and_or_b32 v81, v57, s47, v63
	s_waitcnt vmcnt(5)
	v_pk_mul_f32 v[78:79], v[62:63], v[66:67] op_sel_hi:[0,1]
	v_pk_mul_f32 v[74:75], v[62:63], v[64:65] op_sel_hi:[0,1]
	v_pk_mul_f32 v[76:77], v[62:63], v[70:71] op_sel_hi:[0,1]
	v_pk_mul_f32 v[62:63], v[62:63], v[68:69] op_sel_hi:[0,1]
	v_bfe_u32 v59, v84, 16, 1
	v_bfe_u32 v3, v63, 16, 1
	v_lshl_add_u64 v[110:111], v[54:55], 0, v[4:5]
	v_add3_u32 v59, v84, v59, s46
	v_lshl_add_u64 v[84:85], v[48:49], 0, v[4:5]
	v_bfe_u32 v4, v62, 16, 1
	v_add3_u32 v3, v63, v3, s46
	v_bfe_u32 v63, v77, 16, 1
	v_lshrrev_b32_e32 v61, 16, v61
	v_add3_u32 v4, v62, v4, s46
	v_bfe_u32 v62, v76, 16, 1
	v_add3_u32 v63, v77, v63, s46
	v_and_or_b32 v80, v59, s47, v61
	v_bfe_u32 v53, v75, 16, 1
	v_bfe_u32 v59, v78, 16, 1
	v_bfe_u32 v61, v79, 16, 1
	v_add3_u32 v62, v76, v62, s46
	v_lshrrev_b32_e32 v63, 16, v63
	v_bfe_u32 v57, v74, 16, 1
	v_add3_u32 v53, v75, v53, s46
	v_add3_u32 v61, v79, v61, s46
	v_add3_u32 v59, v78, v59, s46
	v_lshrrev_b32_e32 v62, 16, v62
	v_and_or_b32 v75, v3, s47, v63
	v_or_b32_e32 v3, v51, v98
	v_add3_u32 v57, v74, v57, s46
	v_lshrrev_b32_e32 v59, 16, v59
	v_lshrrev_b32_e32 v61, 16, v61
	v_and_or_b32 v74, v4, s47, v62
	v_lshlrev_b32_e32 v4, 11, v3
	v_and_or_b32 v73, v53, s47, v61
	v_and_or_b32 v72, v57, s47, v59
	v_lshl_add_u64 v[62:63], v[54:55], 0, v[4:5]
	global_store_dwordx4 v[62:63], v[72:75], off
	s_waitcnt vmcnt(5)
	v_pk_mul_f32 v[62:63], v[60:61], v[66:67] op_sel_hi:[0,1]
	v_pk_mul_f32 v[64:65], v[60:61], v[64:65] op_sel_hi:[0,1]
	v_pk_mul_f32 v[66:67], v[60:61], v[70:71] op_sel_hi:[0,1]
	v_pk_mul_f32 v[60:61], v[60:61], v[68:69] op_sel_hi:[0,1]
	v_bfe_u32 v3, v61, 16, 1
	v_bfe_u32 v53, v60, 16, 1
	v_bfe_u32 v57, v65, 16, 1
	v_bfe_u32 v59, v64, 16, 1
	v_add3_u32 v59, v64, v59, s46
	v_add3_u32 v57, v65, v57, s46
	v_add3_u32 v53, v60, v53, s46
	v_add3_u32 v3, v61, v3, s46
	v_bfe_u32 v60, v62, 16, 1
	v_bfe_u32 v61, v63, 16, 1
	v_bfe_u32 v64, v66, 16, 1
	v_bfe_u32 v65, v67, 16, 1
	v_add3_u32 v65, v67, v65, s46
	v_add3_u32 v64, v66, v64, s46
	v_add3_u32 v61, v63, v61, s46
	v_add3_u32 v60, v62, v60, s46
	v_lshrrev_b32_e32 v60, 16, v60
	v_lshrrev_b32_e32 v61, 16, v61
	v_lshrrev_b32_e32 v62, 16, v64
	v_lshrrev_b32_e32 v63, 16, v65
	v_and_or_b32 v63, v3, s47, v63
	v_and_or_b32 v62, v53, s47, v62
	v_and_or_b32 v61, v57, s47, v61
	v_and_or_b32 v60, v59, s47, v60
	v_lshl_add_u64 v[64:65], v[48:49], 0, v[4:5]
	global_store_dwordx4 v[110:111], v[90:93], off
	global_store_dwordx4 v[84:85], v[80:83], off
	global_store_dwordx4 v[64:65], v[60:63], off
	ds_read2_b32 v[62:63], v97 offset0:49 offset1:57
	ds_read2_b32 v[64:65], v97 offset0:82 offset1:90
	ds_read2_b32 v[66:67], v97 offset0:115 offset1:123
	ds_read2_b32 v[68:69], v97 offset0:148 offset1:156
	ds_read2_b32 v[70:71], v97 offset0:181 offset1:189
	ds_read2_b32 v[72:73], v97 offset0:214 offset1:222
	ds_read2_b32 v[74:75], v97 offset0:247 offset1:255
	ds_read2_b32 v[76:77], v97 offset0:16 offset1:24
	s_waitcnt lgkmcnt(6)
	v_mov_b32_e32 v79, v64
	v_mov_b32_e32 v80, v62
	s_waitcnt lgkmcnt(5)
	v_mov_b32_e32 v81, v66
	s_waitcnt lgkmcnt(4)
	v_mov_b32_e32 v84, v68
	s_waitcnt lgkmcnt(0)
	v_mov_b32_e32 v78, v76
	v_mov_b32_e32 v85, v72
	v_mov_b32_e32 v88, v70
	v_mov_b32_e32 v89, v74
	s_waitcnt vmcnt(7)
	v_pk_mul_f32 v[60:61], v[58:59], v[78:79] op_sel_hi:[0,1]
	v_pk_mul_f32 v[82:83], v[58:59], v[80:81] op_sel_hi:[0,1]
	v_pk_mul_f32 v[86:87], v[58:59], v[84:85] op_sel_hi:[0,1]
	v_pk_mul_f32 v[58:59], v[58:59], v[88:89] op_sel_hi:[0,1]
	v_bfe_u32 v3, v59, 16, 1
	v_bfe_u32 v64, v87, 16, 1
	v_bfe_u32 v4, v58, 16, 1
	v_add3_u32 v3, v59, v3, s46
	v_bfe_u32 v59, v61, 16, 1
	v_bfe_u32 v62, v86, 16, 1
	v_add3_u32 v64, v87, v64, s46
	v_add3_u32 v4, v58, v4, s46
	v_bfe_u32 v58, v60, 16, 1
	v_add3_u32 v62, v86, v62, s46
	v_add3_u32 v59, v61, v59, s46
	v_lshrrev_b32_e32 v61, 16, v64
	v_bfe_u32 v53, v83, 16, 1
	v_bfe_u32 v57, v82, 16, 1
	v_add3_u32 v58, v60, v58, s46
	v_lshrrev_b32_e32 v60, 16, v62
	v_and_or_b32 v61, v3, s47, v61
	v_or_b32_e32 v3, v51, v99
	v_add3_u32 v57, v82, v57, s46
	v_add3_u32 v53, v83, v53, s46
	v_lshrrev_b32_e32 v58, 16, v58
	v_lshrrev_b32_e32 v59, 16, v59
	v_and_or_b32 v60, v4, s47, v60
	v_lshlrev_b32_e32 v4, 11, v3
	v_and_or_b32 v59, v53, s47, v59
	v_and_or_b32 v58, v57, s47, v58
	v_lshl_add_u64 v[82:83], v[54:55], 0, v[4:5]
	global_store_dwordx4 v[82:83], v[58:61], off
	v_mov_b32_e32 v66, v63
	v_mov_b32_e32 v72, v69
	s_waitcnt vmcnt(7)
	v_pk_mul_f32 v[58:59], v[56:57], v[78:79] op_sel_hi:[0,1]
	v_pk_mul_f32 v[60:61], v[56:57], v[80:81] op_sel_hi:[0,1]
	v_pk_mul_f32 v[78:79], v[56:57], v[84:85] op_sel_hi:[0,1]
	v_pk_mul_f32 v[56:57], v[56:57], v[88:89] op_sel_hi:[0,1]
	v_bfe_u32 v3, v57, 16, 1
	v_bfe_u32 v53, v56, 16, 1
	v_bfe_u32 v62, v61, 16, 1
	v_bfe_u32 v64, v60, 16, 1
	v_add3_u32 v60, v60, v64, s46
	v_add3_u32 v61, v61, v62, s46
	v_add3_u32 v53, v56, v53, s46
	v_add3_u32 v3, v57, v3, s46
	v_bfe_u32 v56, v58, 16, 1
	v_bfe_u32 v57, v59, 16, 1
	v_bfe_u32 v62, v78, 16, 1
	v_bfe_u32 v64, v79, 16, 1
	v_add3_u32 v64, v79, v64, s46
	v_add3_u32 v62, v78, v62, s46
	v_add3_u32 v57, v59, v57, s46
	v_add3_u32 v56, v58, v56, s46
	v_lshrrev_b32_e32 v56, 16, v56
	v_lshrrev_b32_e32 v57, 16, v57
	v_lshrrev_b32_e32 v58, 16, v62
	v_lshrrev_b32_e32 v59, 16, v64
	v_and_or_b32 v59, v3, s47, v59
	v_and_or_b32 v58, v53, s47, v58
	v_and_or_b32 v57, v61, s47, v57
	v_and_or_b32 v56, v60, s47, v56
	v_lshl_add_u64 v[60:61], v[48:49], 0, v[4:5]
	global_store_dwordx4 v[60:61], v[56:59], off
	v_mov_b32_e32 v64, v77
	v_mov_b32_e32 v74, v71
	s_waitcnt vmcnt(7)
	v_pk_mul_f32 v[58:59], v[52:53], v[66:67] op_sel_hi:[0,1]
	v_pk_mul_f32 v[56:57], v[52:53], v[64:65] op_sel_hi:[0,1]
	v_pk_mul_f32 v[60:61], v[52:53], v[72:73] op_sel_hi:[0,1]
	v_pk_mul_f32 v[52:53], v[52:53], v[74:75] op_sel_hi:[0,1]
	v_bfe_u32 v62, v59, 16, 1
	v_bfe_u32 v3, v53, 16, 1
	v_bfe_u32 v63, v58, 16, 1
	v_add3_u32 v62, v59, v62, s46
	v_bfe_u32 v59, v61, 16, 1
	v_bfe_u32 v4, v52, 16, 1
	v_add3_u32 v63, v58, v63, s46
	v_add3_u32 v3, v53, v3, s46
	v_bfe_u32 v53, v57, 16, 1
	v_bfe_u32 v58, v60, 16, 1
	v_add3_u32 v59, v61, v59, s46
	v_add3_u32 v4, v52, v4, s46
	v_bfe_u32 v52, v56, 16, 1
	v_add3_u32 v58, v60, v58, s46
	v_add3_u32 v53, v57, v53, s46
	v_lshrrev_b32_e32 v57, 16, v59
	v_add3_u32 v52, v56, v52, s46
	v_lshrrev_b32_e32 v56, 16, v58
	v_and_or_b32 v59, v3, s47, v57
	v_or_b32_e32 v3, v51, v100
	v_lshrrev_b32_e32 v52, 16, v52
	v_lshrrev_b32_e32 v53, 16, v53
	v_and_or_b32 v58, v4, s47, v56
	v_lshlrev_b32_e32 v4, 11, v3
	v_and_or_b32 v57, v62, s47, v53
	v_and_or_b32 v56, v63, s47, v52
	v_lshl_add_u64 v[52:53], v[54:55], 0, v[4:5]
	global_store_dwordx4 v[52:53], v[56:59], off
	s_waitcnt vmcnt(7)
	v_pk_mul_f32 v[52:53], v[50:51], v[64:65] op_sel_hi:[0,1]
	v_pk_mul_f32 v[54:55], v[50:51], v[66:67] op_sel_hi:[0,1]
	v_pk_mul_f32 v[56:57], v[50:51], v[72:73] op_sel_hi:[0,1]
	v_pk_mul_f32 v[50:51], v[50:51], v[74:75] op_sel_hi:[0,1]
	v_bfe_u32 v3, v51, 16, 1
	v_bfe_u32 v58, v50, 16, 1
	v_bfe_u32 v59, v55, 16, 1
	v_bfe_u32 v60, v54, 16, 1
	v_add3_u32 v54, v54, v60, s46
	v_add3_u32 v55, v55, v59, s46
	v_add3_u32 v50, v50, v58, s46
	v_add3_u32 v3, v51, v3, s46
	v_bfe_u32 v51, v52, 16, 1
	v_bfe_u32 v58, v53, 16, 1
	v_bfe_u32 v59, v56, 16, 1
	v_bfe_u32 v60, v57, 16, 1
	v_add3_u32 v57, v57, v60, s46
	v_add3_u32 v56, v56, v59, s46
	v_add3_u32 v53, v53, v58, s46
	v_add3_u32 v51, v52, v51, s46
	v_lshrrev_b32_e32 v58, 16, v51
	v_lshrrev_b32_e32 v51, 16, v53
	v_lshrrev_b32_e32 v52, 16, v56
	v_lshrrev_b32_e32 v53, 16, v57
	v_and_or_b32 v53, v3, s47, v53
	v_and_or_b32 v52, v50, s47, v52
	v_and_or_b32 v51, v55, s47, v51
	v_and_or_b32 v50, v54, s47, v58
	v_lshl_add_u64 v[48:49], v[48:49], 0, v[4:5]
	global_store_dwordx4 v[48:49], v[50:53], off
	s_waitcnt lgkmcnt(0)

.LBB0_925:
	s_lshl_b32 s69, s64, 1
	s_lshl_b32 s70, s65, 1
	v_or_b32_e32 v56, s69, v1
	v_or_b32_e32 v57, s70, v0
	v_add_lshl_u32 v4, v56, v3, 10
	v_add_lshl_u32 v53, v57, v48, 10
	v_or_b32_e32 v52, v49, v4
	v_or_b32_e32 v4, v50, v53
	v_lshl_add_u64 v[54:55], v[4:5], 2, s[6:7]
	v_mov_b32_e32 v53, v5
	v_lshl_add_u64 v[52:53], v[52:53], 2, s[6:7]
	global_load_dword v126, v[54:55], off
	global_load_dword v127, v[52:53], off
	v_mad_u64_u32 v[52:53], s[72:73], v57, s40, v[2:3]
	v_mad_u64_u32 v[54:55], s[72:73], v56, s40, v[2:3]
	s_add_i32 s71, s69, 4
	s_add_i32 s72, s70, 4
	v_or_b32_e32 v56, s71, v1
	v_or_b32_e32 v57, s72, v0
	v_add_lshl_u32 v53, v57, v48, 10
	s_add_i32 s71, s69, 8
	s_add_i32 s65, s65, 16
	s_add_i32 s64, s64, 16
	s_add_i32 s68, s68, -16
	v_mov_b32_e32 v142, v52
	v_mov_b32_e32 v143, v54
	v_add_lshl_u32 v4, v56, v3, 10
	v_or_b32_e32 v52, v49, v4
	v_or_b32_e32 v4, v50, v53
	v_lshl_add_u64 v[54:55], v[4:5], 2, s[6:7]
	v_mov_b32_e32 v53, v5
	v_lshl_add_u64 v[52:53], v[52:53], 2, s[6:7]
	global_load_dword v128, v[54:55], off
	global_load_dword v129, v[52:53], off
	v_mad_u64_u32 v[52:53], s[72:73], v57, s40, v[2:3]
	v_mad_u64_u32 v[54:55], s[72:73], v56, s40, v[2:3]
	s_add_i32 s72, s70, 8
	v_or_b32_e32 v56, s71, v1
	v_or_b32_e32 v57, s72, v0
	v_add_lshl_u32 v53, v57, v48, 10
	s_add_i32 s71, s69, 12
	v_mov_b32_e32 v144, v52
	v_mov_b32_e32 v145, v54
	v_add_lshl_u32 v4, v56, v3, 10
	v_or_b32_e32 v52, v49, v4
	v_or_b32_e32 v4, v50, v53
	v_lshl_add_u64 v[54:55], v[4:5], 2, s[6:7]
	v_mov_b32_e32 v53, v5
	v_lshl_add_u64 v[52:53], v[52:53], 2, s[6:7]
	global_load_dword v130, v[54:55], off
	global_load_dword v131, v[52:53], off
	v_mad_u64_u32 v[52:53], s[72:73], v57, s40, v[2:3]
	v_mad_u64_u32 v[54:55], s[72:73], v56, s40, v[2:3]
	s_add_i32 s72, s70, 12
	v_or_b32_e32 v56, s71, v1
	v_or_b32_e32 v57, s72, v0
	v_add_lshl_u32 v53, v57, v48, 10
	s_add_i32 s71, s69, 16
	v_mov_b32_e32 v146, v52
	v_mov_b32_e32 v147, v54
	v_add_lshl_u32 v4, v56, v3, 10
	v_or_b32_e32 v52, v49, v4
	v_or_b32_e32 v4, v50, v53
	v_lshl_add_u64 v[54:55], v[4:5], 2, s[6:7]
	v_mov_b32_e32 v53, v5
	v_lshl_add_u64 v[52:53], v[52:53], 2, s[6:7]
	global_load_dword v132, v[54:55], off
	global_load_dword v133, v[52:53], off
	v_mad_u64_u32 v[52:53], s[72:73], v57, s40, v[2:3]
	v_mad_u64_u32 v[54:55], s[72:73], v56, s40, v[2:3]
	s_add_i32 s72, s70, 16
	v_or_b32_e32 v56, s71, v1
	v_or_b32_e32 v57, s72, v0
	v_add_lshl_u32 v53, v57, v48, 10
	s_add_i32 s71, s69, 20
	v_mov_b32_e32 v148, v52
	v_mov_b32_e32 v149, v54
	v_add_lshl_u32 v4, v56, v3, 10
	v_or_b32_e32 v52, v49, v4
	v_or_b32_e32 v4, v50, v53
	v_lshl_add_u64 v[54:55], v[4:5], 2, s[6:7]
	v_mov_b32_e32 v53, v5
	v_lshl_add_u64 v[52:53], v[52:53], 2, s[6:7]
	global_load_dword v134, v[54:55], off
	global_load_dword v135, v[52:53], off
	v_mad_u64_u32 v[52:53], s[72:73], v57, s40, v[2:3]
	v_mad_u64_u32 v[54:55], s[72:73], v56, s40, v[2:3]
	s_add_i32 s72, s70, 20
	v_or_b32_e32 v56, s71, v1
	v_or_b32_e32 v57, s72, v0
	v_add_lshl_u32 v53, v57, v48, 10
	s_add_i32 s71, s69, 24
	s_add_i32 s69, s69, 28
	v_mov_b32_e32 v150, v52
	v_mov_b32_e32 v151, v54
	v_add_lshl_u32 v4, v56, v3, 10
	v_or_b32_e32 v52, v49, v4
	v_or_b32_e32 v4, v50, v53
	v_lshl_add_u64 v[54:55], v[4:5], 2, s[6:7]
	v_mov_b32_e32 v53, v5
	v_lshl_add_u64 v[52:53], v[52:53], 2, s[6:7]
	global_load_dword v136, v[54:55], off
	global_load_dword v137, v[52:53], off
	v_mad_u64_u32 v[52:53], s[72:73], v57, s40, v[2:3]
	v_mad_u64_u32 v[54:55], s[72:73], v56, s40, v[2:3]
	s_add_i32 s72, s70, 24
	v_or_b32_e32 v56, s71, v1
	v_or_b32_e32 v57, s72, v0
	v_add_lshl_u32 v53, v57, v48, 10
	s_add_i32 s70, s70, 28
	s_cmp_lg_u32 s68, 0
	v_mov_b32_e32 v152, v52
	v_mov_b32_e32 v153, v54
	v_add_lshl_u32 v4, v56, v3, 10
	v_or_b32_e32 v52, v49, v4
	v_or_b32_e32 v4, v50, v53
	v_lshl_add_u64 v[54:55], v[4:5], 2, s[6:7]
	v_mov_b32_e32 v53, v5
	v_lshl_add_u64 v[52:53], v[52:53], 2, s[6:7]
	global_load_dword v138, v[54:55], off
	global_load_dword v139, v[52:53], off
	v_mad_u64_u32 v[52:53], s[72:73], v57, s40, v[2:3]
	v_mad_u64_u32 v[54:55], s[72:73], v56, s40, v[2:3]
	v_or_b32_e32 v56, s69, v1
	v_or_b32_e32 v57, s70, v0
	v_mov_b32_e32 v55, v5
	v_mov_b32_e32 v154, v52
	v_mov_b32_e32 v155, v54
	v_add_lshl_u32 v4, v56, v3, 10
	v_add_lshl_u32 v52, v57, v48, 10
	v_or_b32_e32 v54, v49, v4
	v_or_b32_e32 v4, v50, v52
	v_lshl_add_u64 v[52:53], v[4:5], 2, s[6:7]
	v_lshl_add_u64 v[54:55], v[54:55], 2, s[6:7]
	global_load_dword v140, v[52:53], off
	global_load_dword v141, v[54:55], off
	v_mad_u64_u32 v[52:53], s[70:71], v57, s40, v[2:3]
	v_mad_u64_u32 v[54:55], s[70:71], v56, s40, v[2:3]
	v_mov_b32_e32 v156, v52
	v_mov_b32_e32 v157, v54
	s_waitcnt vmcnt(15)
	ds_write_b32 v142, v126
	s_waitcnt vmcnt(14)
	ds_write_b32 v143, v127
	s_waitcnt vmcnt(13)
	ds_write_b32 v144, v128
	s_waitcnt vmcnt(12)
	ds_write_b32 v145, v129
	s_waitcnt vmcnt(11)
	ds_write_b32 v146, v130
	s_waitcnt vmcnt(10)
	ds_write_b32 v147, v131
	s_waitcnt vmcnt(9)
	ds_write_b32 v148, v132
	s_waitcnt vmcnt(8)
	ds_write_b32 v149, v133
	s_waitcnt vmcnt(7)
	ds_write_b32 v150, v134
	s_waitcnt vmcnt(6)
	ds_write_b32 v151, v135
	s_waitcnt vmcnt(5)
	ds_write_b32 v152, v136
	s_waitcnt vmcnt(4)
	ds_write_b32 v153, v137
	s_waitcnt vmcnt(3)
	ds_write_b32 v154, v138
	s_waitcnt vmcnt(2)
	ds_write_b32 v155, v139
	s_waitcnt vmcnt(1)
	ds_write_b32 v156, v140
	s_waitcnt vmcnt(0)
	ds_write_b32 v157, v141
	s_cbranch_scc1 .LBB0_925
	s_waitcnt lgkmcnt(0)
	ds_read2_b32 v[56:57], v97 offset0:33 offset1:41
	ds_read2_b32 v[58:59], v97 offset0:66 offset1:74
	ds_read2_b32 v[60:61], v97 offset0:99 offset1:107
	ds_read2_b32 v[62:63], v97 offset1:8
	ds_read2_b32 v[64:65], v97 offset0:132 offset1:140
	ds_read2_b32 v[66:67], v97 offset0:165 offset1:173
	ds_read2_b32 v[68:69], v97 offset0:198 offset1:206
	ds_read2_b32 v[70:71], v97 offset0:231 offset1:239
	v_lshlrev_b32_e32 v4, 1, v48
	s_waitcnt lgkmcnt(4)
	v_bfe_u32 v3, v62, 16, 1
	v_lshl_add_u64 v[48:49], v[10:11], 0, v[4:5]
	v_add3_u32 v3, v62, v3, s46
	v_bfe_u32 v4, v56, 16, 1
	v_lshrrev_b32_e32 v3, 16, v3
	v_add3_u32 v4, v56, v4, s46
	v_and_or_b32 v52, v4, s47, v3
	v_bfe_u32 v3, v58, 16, 1
	v_add3_u32 v3, v58, v3, s46
	v_bfe_u32 v4, v60, 16, 1
	v_lshrrev_b32_e32 v3, 16, v3
	v_add3_u32 v4, v60, v4, s46
	v_and_or_b32 v53, v4, s47, v3
	s_waitcnt lgkmcnt(3)
	v_bfe_u32 v3, v64, 16, 1
	v_add3_u32 v3, v64, v3, s46
	s_waitcnt lgkmcnt(2)
	v_bfe_u32 v4, v66, 16, 1
	v_lshrrev_b32_e32 v3, 16, v3
	v_add3_u32 v4, v66, v4, s46
	v_and_or_b32 v54, v4, s47, v3
	s_waitcnt lgkmcnt(1)
	v_bfe_u32 v3, v68, 16, 1
	v_add3_u32 v3, v68, v3, s46
	s_waitcnt lgkmcnt(0)
	v_bfe_u32 v4, v70, 16, 1
	v_lshrrev_b32_e32 v3, 16, v3
	v_add3_u32 v4, v70, v4, s46
	v_and_or_b32 v55, v4, s47, v3
	v_or_b32_e32 v3, v51, v96
	v_lshlrev_b32_e32 v4, 9, v3
	v_bfe_u32 v3, v63, 16, 1
	v_lshl_add_u64 v[72:73], v[48:49], 0, v[4:5]
	v_add3_u32 v3, v63, v3, s46
	v_bfe_u32 v4, v57, 16, 1
	v_lshrrev_b32_e32 v3, 16, v3
	v_add3_u32 v4, v57, v4, s46
	global_store_dwordx4 v[72:73], v[52:55], off
	s_nop 1
	v_and_or_b32 v52, v4, s47, v3
	v_bfe_u32 v3, v59, 16, 1
	v_add3_u32 v3, v59, v3, s46
	v_bfe_u32 v4, v61, 16, 1
	v_lshrrev_b32_e32 v3, 16, v3
	v_add3_u32 v4, v61, v4, s46
	v_and_or_b32 v53, v4, s47, v3
	v_bfe_u32 v3, v65, 16, 1
	v_add3_u32 v3, v65, v3, s46
	v_bfe_u32 v4, v67, 16, 1
	v_lshrrev_b32_e32 v3, 16, v3
	v_add3_u32 v4, v67, v4, s46
	v_and_or_b32 v54, v4, s47, v3
	v_bfe_u32 v3, v69, 16, 1
	v_add3_u32 v3, v69, v3, s46
	v_bfe_u32 v4, v71, 16, 1
	v_lshrrev_b32_e32 v3, 16, v3
	v_add3_u32 v4, v71, v4, s46
	v_and_or_b32 v55, v4, s47, v3
	v_or_b32_e32 v3, v51, v98
	v_lshlrev_b32_e32 v4, 9, v3
	v_lshl_add_u64 v[56:57], v[48:49], 0, v[4:5]
	global_store_dwordx4 v[56:57], v[52:55], off
	ds_read2_b32 v[56:57], v97 offset0:49 offset1:57
	ds_read2_b32 v[58:59], v97 offset0:82 offset1:90
	ds_read2_b32 v[60:61], v97 offset0:115 offset1:123
	ds_read2_b32 v[62:63], v97 offset0:16 offset1:24
	ds_read2_b32 v[64:65], v97 offset0:148 offset1:156
	ds_read2_b32 v[66:67], v97 offset0:181 offset1:189
	ds_read2_b32 v[68:69], v97 offset0:214 offset1:222
	ds_read2_b32 v[70:71], v97 offset0:247 offset1:255
	s_waitcnt lgkmcnt(4)
	v_bfe_u32 v3, v62, 16, 1
	v_add3_u32 v3, v62, v3, s46
	v_bfe_u32 v4, v56, 16, 1
	v_lshrrev_b32_e32 v3, 16, v3
	v_add3_u32 v4, v56, v4, s46
	v_and_or_b32 v52, v4, s47, v3
	v_bfe_u32 v3, v58, 16, 1
	v_add3_u32 v3, v58, v3, s46
	v_bfe_u32 v4, v60, 16, 1
	v_lshrrev_b32_e32 v3, 16, v3
	v_add3_u32 v4, v60, v4, s46
	v_and_or_b32 v53, v4, s47, v3
	s_waitcnt lgkmcnt(3)
	v_bfe_u32 v3, v64, 16, 1
	v_add3_u32 v3, v64, v3, s46
	s_waitcnt lgkmcnt(2)
	v_bfe_u32 v4, v66, 16, 1
	v_lshrrev_b32_e32 v3, 16, v3
	v_add3_u32 v4, v66, v4, s46
	v_and_or_b32 v54, v4, s47, v3
	s_waitcnt lgkmcnt(1)
	v_bfe_u32 v3, v68, 16, 1
	v_add3_u32 v3, v68, v3, s46
	s_waitcnt lgkmcnt(0)
	v_bfe_u32 v4, v70, 16, 1
	v_lshrrev_b32_e32 v3, 16, v3
	v_add3_u32 v4, v70, v4, s46
	v_and_or_b32 v55, v4, s47, v3
	v_or_b32_e32 v3, v51, v99
	v_lshlrev_b32_e32 v4, 9, v3
	v_bfe_u32 v3, v63, 16, 1
	v_lshl_add_u64 v[72:73], v[48:49], 0, v[4:5]
	v_add3_u32 v3, v63, v3, s46
	v_bfe_u32 v4, v57, 16, 1
	v_lshrrev_b32_e32 v3, 16, v3
	v_add3_u32 v4, v57, v4, s46
	global_store_dwordx4 v[72:73], v[52:55], off
	s_nop 1
	v_and_or_b32 v52, v4, s47, v3
	v_bfe_u32 v3, v59, 16, 1
	v_add3_u32 v3, v59, v3, s46
	v_bfe_u32 v4, v61, 16, 1
	v_lshrrev_b32_e32 v3, 16, v3
	v_add3_u32 v4, v61, v4, s46
	v_and_or_b32 v53, v4, s47, v3
	v_bfe_u32 v3, v65, 16, 1
	v_add3_u32 v3, v65, v3, s46
	v_bfe_u32 v4, v67, 16, 1
	v_lshrrev_b32_e32 v3, 16, v3
	v_add3_u32 v4, v67, v4, s46
	v_and_or_b32 v54, v4, s47, v3
	v_bfe_u32 v3, v69, 16, 1
	v_add3_u32 v3, v69, v3, s46
	v_bfe_u32 v4, v71, 16, 1
	v_lshrrev_b32_e32 v3, 16, v3
	v_add3_u32 v4, v71, v4, s46
	v_and_or_b32 v55, v4, s47, v3
	v_or_b32_e32 v3, v51, v100
	v_lshlrev_b32_e32 v4, 9, v3
	v_lshl_add_u64 v[48:49], v[48:49], 0, v[4:5]
	global_store_dwordx4 v[48:49], v[52:55], off
	s_waitcnt lgkmcnt(0)

.LBB0_930:
	s_lshl_b32 s65, s36, 1
	s_lshl_b32 s68, s37, 1
	v_or_b32_e32 v56, s65, v1
	v_or_b32_e32 v57, s68, v0
	v_add_lshl_u32 v4, v56, v3, 10
	v_add_lshl_u32 v53, v57, v48, 10
	v_or_b32_e32 v52, v49, v4
	v_or_b32_e32 v4, v50, v53
	v_lshl_add_u64 v[54:55], v[4:5], 2, s[4:5]
	v_mov_b32_e32 v53, v5
	v_lshl_add_u64 v[52:53], v[52:53], 2, s[4:5]
	global_load_dword v126, v[54:55], off
	global_load_dword v127, v[52:53], off
	v_mad_u64_u32 v[52:53], s[70:71], v57, s40, v[2:3]
	v_mad_u64_u32 v[54:55], s[70:71], v56, s40, v[2:3]
	s_add_i32 s69, s65, 4
	s_add_i32 s70, s68, 4
	v_or_b32_e32 v56, s69, v1
	v_or_b32_e32 v57, s70, v0
	v_add_lshl_u32 v53, v57, v48, 10
	s_add_i32 s69, s65, 8
	s_add_i32 s37, s37, 16
	s_add_i32 s36, s36, 16
	s_add_i32 s64, s64, -16
	v_mov_b32_e32 v142, v52
	v_mov_b32_e32 v143, v54
	v_add_lshl_u32 v4, v56, v3, 10
	v_or_b32_e32 v52, v49, v4
	v_or_b32_e32 v4, v50, v53
	v_lshl_add_u64 v[54:55], v[4:5], 2, s[4:5]
	v_mov_b32_e32 v53, v5
	v_lshl_add_u64 v[52:53], v[52:53], 2, s[4:5]
	global_load_dword v128, v[54:55], off
	global_load_dword v129, v[52:53], off
	v_mad_u64_u32 v[52:53], s[70:71], v57, s40, v[2:3]
	v_mad_u64_u32 v[54:55], s[70:71], v56, s40, v[2:3]
	s_add_i32 s70, s68, 8
	v_or_b32_e32 v56, s69, v1
	v_or_b32_e32 v57, s70, v0
	v_add_lshl_u32 v53, v57, v48, 10
	s_add_i32 s69, s65, 12
	v_mov_b32_e32 v144, v52
	v_mov_b32_e32 v145, v54
	v_add_lshl_u32 v4, v56, v3, 10
	v_or_b32_e32 v52, v49, v4
	v_or_b32_e32 v4, v50, v53
	v_lshl_add_u64 v[54:55], v[4:5], 2, s[4:5]
	v_mov_b32_e32 v53, v5
	v_lshl_add_u64 v[52:53], v[52:53], 2, s[4:5]
	global_load_dword v130, v[54:55], off
	global_load_dword v131, v[52:53], off
	v_mad_u64_u32 v[52:53], s[70:71], v57, s40, v[2:3]
	v_mad_u64_u32 v[54:55], s[70:71], v56, s40, v[2:3]
	s_add_i32 s70, s68, 12
	v_or_b32_e32 v56, s69, v1
	v_or_b32_e32 v57, s70, v0
	v_add_lshl_u32 v53, v57, v48, 10
	s_add_i32 s69, s65, 16
	v_mov_b32_e32 v146, v52
	v_mov_b32_e32 v147, v54
	v_add_lshl_u32 v4, v56, v3, 10
	v_or_b32_e32 v52, v49, v4
	v_or_b32_e32 v4, v50, v53
	v_lshl_add_u64 v[54:55], v[4:5], 2, s[4:5]
	v_mov_b32_e32 v53, v5
	v_lshl_add_u64 v[52:53], v[52:53], 2, s[4:5]
	global_load_dword v132, v[54:55], off
	global_load_dword v133, v[52:53], off
	v_mad_u64_u32 v[52:53], s[70:71], v57, s40, v[2:3]
	v_mad_u64_u32 v[54:55], s[70:71], v56, s40, v[2:3]
	s_add_i32 s70, s68, 16
	v_or_b32_e32 v56, s69, v1
	v_or_b32_e32 v57, s70, v0
	v_add_lshl_u32 v53, v57, v48, 10
	s_add_i32 s69, s65, 20
	v_mov_b32_e32 v148, v52
	v_mov_b32_e32 v149, v54
	v_add_lshl_u32 v4, v56, v3, 10
	v_or_b32_e32 v52, v49, v4
	v_or_b32_e32 v4, v50, v53
	v_lshl_add_u64 v[54:55], v[4:5], 2, s[4:5]
	v_mov_b32_e32 v53, v5
	v_lshl_add_u64 v[52:53], v[52:53], 2, s[4:5]
	global_load_dword v134, v[54:55], off
	global_load_dword v135, v[52:53], off
	v_mad_u64_u32 v[52:53], s[70:71], v57, s40, v[2:3]
	v_mad_u64_u32 v[54:55], s[70:71], v56, s40, v[2:3]
	s_add_i32 s70, s68, 20
	v_or_b32_e32 v56, s69, v1
	v_or_b32_e32 v57, s70, v0
	v_add_lshl_u32 v53, v57, v48, 10
	s_add_i32 s69, s65, 24
	s_add_i32 s65, s65, 28
	v_mov_b32_e32 v150, v52
	v_mov_b32_e32 v151, v54
	v_add_lshl_u32 v4, v56, v3, 10
	v_or_b32_e32 v52, v49, v4
	v_or_b32_e32 v4, v50, v53
	v_lshl_add_u64 v[54:55], v[4:5], 2, s[4:5]
	v_mov_b32_e32 v53, v5
	v_lshl_add_u64 v[52:53], v[52:53], 2, s[4:5]
	global_load_dword v136, v[54:55], off
	global_load_dword v137, v[52:53], off
	v_mad_u64_u32 v[52:53], s[70:71], v57, s40, v[2:3]
	v_mad_u64_u32 v[54:55], s[70:71], v56, s40, v[2:3]
	s_add_i32 s70, s68, 24
	v_or_b32_e32 v56, s69, v1
	v_or_b32_e32 v57, s70, v0
	v_add_lshl_u32 v53, v57, v48, 10
	s_add_i32 s68, s68, 28
	s_cmp_lg_u32 s64, 0
	v_mov_b32_e32 v152, v52
	v_mov_b32_e32 v153, v54
	v_add_lshl_u32 v4, v56, v3, 10
	v_or_b32_e32 v52, v49, v4
	v_or_b32_e32 v4, v50, v53
	v_lshl_add_u64 v[54:55], v[4:5], 2, s[4:5]
	v_mov_b32_e32 v53, v5
	v_lshl_add_u64 v[52:53], v[52:53], 2, s[4:5]
	global_load_dword v138, v[54:55], off
	global_load_dword v139, v[52:53], off
	v_mad_u64_u32 v[52:53], s[70:71], v57, s40, v[2:3]
	v_mad_u64_u32 v[54:55], s[70:71], v56, s40, v[2:3]
	v_or_b32_e32 v56, s65, v1
	v_or_b32_e32 v57, s68, v0
	v_mov_b32_e32 v55, v5
	v_mov_b32_e32 v154, v52
	v_mov_b32_e32 v155, v54
	v_add_lshl_u32 v4, v56, v3, 10
	v_add_lshl_u32 v52, v57, v48, 10
	v_or_b32_e32 v54, v49, v4
	v_or_b32_e32 v4, v50, v52
	v_lshl_add_u64 v[52:53], v[4:5], 2, s[4:5]
	v_lshl_add_u64 v[54:55], v[54:55], 2, s[4:5]
	global_load_dword v140, v[52:53], off
	global_load_dword v141, v[54:55], off
	v_mad_u64_u32 v[52:53], s[68:69], v57, s40, v[2:3]
	v_mad_u64_u32 v[54:55], s[68:69], v56, s40, v[2:3]
	v_mov_b32_e32 v156, v52
	v_mov_b32_e32 v157, v54
	s_waitcnt vmcnt(15)
	ds_write_b32 v142, v126
	s_waitcnt vmcnt(14)
	ds_write_b32 v143, v127
	s_waitcnt vmcnt(13)
	ds_write_b32 v144, v128
	s_waitcnt vmcnt(12)
	ds_write_b32 v145, v129
	s_waitcnt vmcnt(11)
	ds_write_b32 v146, v130
	s_waitcnt vmcnt(10)
	ds_write_b32 v147, v131
	s_waitcnt vmcnt(9)
	ds_write_b32 v148, v132
	s_waitcnt vmcnt(8)
	ds_write_b32 v149, v133
	s_waitcnt vmcnt(7)
	ds_write_b32 v150, v134
	s_waitcnt vmcnt(6)
	ds_write_b32 v151, v135
	s_waitcnt vmcnt(5)
	ds_write_b32 v152, v136
	s_waitcnt vmcnt(4)
	ds_write_b32 v153, v137
	s_waitcnt vmcnt(3)
	ds_write_b32 v154, v138
	s_waitcnt vmcnt(2)
	ds_write_b32 v155, v139
	s_waitcnt vmcnt(1)
	ds_write_b32 v156, v140
	s_waitcnt vmcnt(0)
	ds_write_b32 v157, v141
	s_cbranch_scc1 .LBB0_930
	s_waitcnt lgkmcnt(0)
	ds_read2_b32 v[56:57], v97 offset0:33 offset1:41
	ds_read2_b32 v[58:59], v97 offset0:66 offset1:74
	ds_read2_b32 v[60:61], v97 offset0:99 offset1:107
	ds_read2_b32 v[62:63], v97 offset1:8
	ds_read2_b32 v[64:65], v97 offset0:132 offset1:140
	ds_read2_b32 v[66:67], v97 offset0:165 offset1:173
	ds_read2_b32 v[68:69], v97 offset0:198 offset1:206
	ds_read2_b32 v[70:71], v97 offset0:231 offset1:239
	v_lshlrev_b32_e32 v4, 1, v48
	s_waitcnt lgkmcnt(4)
	v_bfe_u32 v3, v62, 16, 1
	v_lshl_add_u64 v[48:49], v[12:13], 0, v[4:5]
	v_add3_u32 v3, v62, v3, s46
	v_bfe_u32 v4, v56, 16, 1
	v_lshrrev_b32_e32 v3, 16, v3
	v_add3_u32 v4, v56, v4, s46
	v_and_or_b32 v52, v4, s47, v3
	v_bfe_u32 v3, v58, 16, 1
	v_add3_u32 v3, v58, v3, s46
	v_bfe_u32 v4, v60, 16, 1
	v_lshrrev_b32_e32 v3, 16, v3
	v_add3_u32 v4, v60, v4, s46
	v_and_or_b32 v53, v4, s47, v3
	s_waitcnt lgkmcnt(3)
	v_bfe_u32 v3, v64, 16, 1
	v_add3_u32 v3, v64, v3, s46
	s_waitcnt lgkmcnt(2)
	v_bfe_u32 v4, v66, 16, 1
	v_lshrrev_b32_e32 v3, 16, v3
	v_add3_u32 v4, v66, v4, s46
	v_and_or_b32 v54, v4, s47, v3
	s_waitcnt lgkmcnt(1)
	v_bfe_u32 v3, v68, 16, 1
	v_add3_u32 v3, v68, v3, s46
	s_waitcnt lgkmcnt(0)
	v_bfe_u32 v4, v70, 16, 1
	v_lshrrev_b32_e32 v3, 16, v3
	v_add3_u32 v4, v70, v4, s46
	v_and_or_b32 v55, v4, s47, v3
	v_or_b32_e32 v3, v51, v96
	v_lshlrev_b32_e32 v4, 10, v3
	v_bfe_u32 v3, v63, 16, 1
	v_lshl_add_u64 v[72:73], v[48:49], 0, v[4:5]
	v_add3_u32 v3, v63, v3, s46
	v_bfe_u32 v4, v57, 16, 1
	v_lshrrev_b32_e32 v3, 16, v3
	v_add3_u32 v4, v57, v4, s46
	global_store_dwordx4 v[72:73], v[52:55], off
	s_nop 1
	v_and_or_b32 v52, v4, s47, v3
	v_bfe_u32 v3, v59, 16, 1
	v_add3_u32 v3, v59, v3, s46
	v_bfe_u32 v4, v61, 16, 1
	v_lshrrev_b32_e32 v3, 16, v3
	v_add3_u32 v4, v61, v4, s46
	v_and_or_b32 v53, v4, s47, v3
	v_bfe_u32 v3, v65, 16, 1
	v_add3_u32 v3, v65, v3, s46
	v_bfe_u32 v4, v67, 16, 1
	v_lshrrev_b32_e32 v3, 16, v3
	v_add3_u32 v4, v67, v4, s46
	v_and_or_b32 v54, v4, s47, v3
	v_bfe_u32 v3, v69, 16, 1
	v_add3_u32 v3, v69, v3, s46
	v_bfe_u32 v4, v71, 16, 1
	v_lshrrev_b32_e32 v3, 16, v3
	v_add3_u32 v4, v71, v4, s46
	v_and_or_b32 v55, v4, s47, v3
	v_or_b32_e32 v3, v51, v98
	v_lshlrev_b32_e32 v4, 10, v3
	v_lshl_add_u64 v[56:57], v[48:49], 0, v[4:5]
	global_store_dwordx4 v[56:57], v[52:55], off
	ds_read2_b32 v[56:57], v97 offset0:49 offset1:57
	ds_read2_b32 v[58:59], v97 offset0:82 offset1:90
	ds_read2_b32 v[60:61], v97 offset0:115 offset1:123
	ds_read2_b32 v[62:63], v97 offset0:16 offset1:24
	ds_read2_b32 v[64:65], v97 offset0:148 offset1:156
	ds_read2_b32 v[66:67], v97 offset0:181 offset1:189
	ds_read2_b32 v[68:69], v97 offset0:214 offset1:222
	ds_read2_b32 v[70:71], v97 offset0:247 offset1:255
	s_waitcnt lgkmcnt(4)
	v_bfe_u32 v3, v62, 16, 1
	v_add3_u32 v3, v62, v3, s46
	v_bfe_u32 v4, v56, 16, 1
	v_lshrrev_b32_e32 v3, 16, v3
	v_add3_u32 v4, v56, v4, s46
	v_and_or_b32 v52, v4, s47, v3
	v_bfe_u32 v3, v58, 16, 1
	v_add3_u32 v3, v58, v3, s46
	v_bfe_u32 v4, v60, 16, 1
	v_lshrrev_b32_e32 v3, 16, v3
	v_add3_u32 v4, v60, v4, s46
	v_and_or_b32 v53, v4, s47, v3
	s_waitcnt lgkmcnt(3)
	v_bfe_u32 v3, v64, 16, 1
	v_add3_u32 v3, v64, v3, s46
	s_waitcnt lgkmcnt(2)
	v_bfe_u32 v4, v66, 16, 1
	v_lshrrev_b32_e32 v3, 16, v3
	v_add3_u32 v4, v66, v4, s46
	v_and_or_b32 v54, v4, s47, v3
	s_waitcnt lgkmcnt(1)
	v_bfe_u32 v3, v68, 16, 1
	v_add3_u32 v3, v68, v3, s46
	s_waitcnt lgkmcnt(0)
	v_bfe_u32 v4, v70, 16, 1
	v_lshrrev_b32_e32 v3, 16, v3
	v_add3_u32 v4, v70, v4, s46
	v_and_or_b32 v55, v4, s47, v3
	v_or_b32_e32 v3, v51, v99
	v_lshlrev_b32_e32 v4, 10, v3
	v_bfe_u32 v3, v63, 16, 1
	v_lshl_add_u64 v[72:73], v[48:49], 0, v[4:5]
	v_add3_u32 v3, v63, v3, s46
	v_bfe_u32 v4, v57, 16, 1
	v_lshrrev_b32_e32 v3, 16, v3
	v_add3_u32 v4, v57, v4, s46
	global_store_dwordx4 v[72:73], v[52:55], off
	s_nop 1
	v_and_or_b32 v52, v4, s47, v3
	v_bfe_u32 v3, v59, 16, 1
	v_add3_u32 v3, v59, v3, s46
	v_bfe_u32 v4, v61, 16, 1
	v_lshrrev_b32_e32 v3, 16, v3
	v_add3_u32 v4, v61, v4, s46
	v_and_or_b32 v53, v4, s47, v3
	v_bfe_u32 v3, v65, 16, 1
	v_add3_u32 v3, v65, v3, s46
	v_bfe_u32 v4, v67, 16, 1
	v_lshrrev_b32_e32 v3, 16, v3
	v_add3_u32 v4, v67, v4, s46
	v_and_or_b32 v54, v4, s47, v3
	v_bfe_u32 v3, v69, 16, 1
	v_add3_u32 v3, v69, v3, s46
	v_bfe_u32 v4, v71, 16, 1
	v_lshrrev_b32_e32 v3, 16, v3
	v_add3_u32 v4, v71, v4, s46
	v_and_or_b32 v55, v4, s47, v3
	v_or_b32_e32 v3, v51, v100
	v_lshlrev_b32_e32 v4, 10, v3
	v_lshl_add_u64 v[48:49], v[48:49], 0, v[4:5]
	global_store_dwordx4 v[48:49], v[52:55], off
	s_waitcnt lgkmcnt(0)

.LBB0_935:
	s_lshl_b32 s64, s9, 1
	s_lshl_b32 s37, s8, 1
	v_or_b32_e32 v50, s64, v4
	v_or_b32_e32 v52, s37, v3
	v_mad_u64_u32 v[50:51], s[68:69], v50, s67, v[48:49]
	v_mad_u64_u32 v[52:53], s[68:69], v52, s67, v[48:49]
	global_load_dword v126, v[50:51], off
	global_load_dword v127, v[52:53], off
	v_or_b32_e32 v54, s37, v1
	v_or_b32_e32 v55, s64, v0
	v_mad_u64_u32 v[50:51], s[68:69], v55, s40, v[2:3]
	v_mad_u64_u32 v[52:53], s[68:69], v54, s40, v[2:3]
	s_add_i32 s68, s64, 4
	s_add_i32 s65, s37, 4
	v_or_b32_e32 v55, s68, v0
	v_or_b32_e32 v54, s65, v1
	s_add_i32 s9, s9, 16
	s_add_i32 s8, s8, 16
	s_add_i32 s36, s36, -16
	v_mov_b32_e32 v142, v50
	v_mov_b32_e32 v143, v52
	v_or_b32_e32 v50, s68, v4
	v_or_b32_e32 v52, s65, v3
	v_mad_u64_u32 v[50:51], s[68:69], v50, s67, v[48:49]
	v_mad_u64_u32 v[52:53], s[68:69], v52, s67, v[48:49]
	global_load_dword v128, v[50:51], off
	global_load_dword v129, v[52:53], off
	v_mad_u64_u32 v[50:51], s[68:69], v55, s40, v[2:3]
	v_mad_u64_u32 v[52:53], s[68:69], v54, s40, v[2:3]
	s_add_i32 s68, s64, 8
	s_add_i32 s65, s37, 8
	v_or_b32_e32 v55, s68, v0
	v_or_b32_e32 v54, s65, v1
	v_mov_b32_e32 v144, v50
	v_mov_b32_e32 v145, v52
	v_or_b32_e32 v50, s68, v4
	v_or_b32_e32 v52, s65, v3
	v_mad_u64_u32 v[50:51], s[68:69], v50, s67, v[48:49]
	v_mad_u64_u32 v[52:53], s[68:69], v52, s67, v[48:49]
	global_load_dword v130, v[50:51], off
	global_load_dword v131, v[52:53], off
	v_mad_u64_u32 v[50:51], s[68:69], v55, s40, v[2:3]
	v_mad_u64_u32 v[52:53], s[68:69], v54, s40, v[2:3]
	s_add_i32 s68, s64, 12
	s_add_i32 s65, s37, 12
	v_or_b32_e32 v55, s68, v0
	v_or_b32_e32 v54, s65, v1
	v_mov_b32_e32 v146, v50
	v_mov_b32_e32 v147, v52
	v_or_b32_e32 v50, s68, v4
	v_or_b32_e32 v52, s65, v3
	v_mad_u64_u32 v[50:51], s[68:69], v50, s67, v[48:49]
	v_mad_u64_u32 v[52:53], s[68:69], v52, s67, v[48:49]
	global_load_dword v132, v[50:51], off
	global_load_dword v133, v[52:53], off
	v_mad_u64_u32 v[50:51], s[68:69], v55, s40, v[2:3]
	v_mad_u64_u32 v[52:53], s[68:69], v54, s40, v[2:3]
	s_add_i32 s68, s64, 16
	s_add_i32 s65, s37, 16
	v_or_b32_e32 v55, s68, v0
	v_or_b32_e32 v54, s65, v1
	v_mov_b32_e32 v148, v50
	v_mov_b32_e32 v149, v52
	v_or_b32_e32 v50, s68, v4
	v_or_b32_e32 v52, s65, v3
	v_mad_u64_u32 v[50:51], s[68:69], v50, s67, v[48:49]
	v_mad_u64_u32 v[52:53], s[68:69], v52, s67, v[48:49]
	global_load_dword v134, v[50:51], off
	global_load_dword v135, v[52:53], off
	v_mad_u64_u32 v[50:51], s[68:69], v55, s40, v[2:3]
	v_mad_u64_u32 v[52:53], s[68:69], v54, s40, v[2:3]
	s_add_i32 s68, s64, 20
	s_add_i32 s65, s37, 20
	v_or_b32_e32 v55, s68, v0
	v_or_b32_e32 v54, s65, v1
	v_mov_b32_e32 v150, v50
	v_mov_b32_e32 v151, v52
	v_or_b32_e32 v50, s68, v4
	v_or_b32_e32 v52, s65, v3
	v_mad_u64_u32 v[50:51], s[68:69], v50, s67, v[48:49]
	v_mad_u64_u32 v[52:53], s[68:69], v52, s67, v[48:49]
	global_load_dword v136, v[50:51], off
	global_load_dword v137, v[52:53], off
	v_mad_u64_u32 v[50:51], s[68:69], v55, s40, v[2:3]
	v_mad_u64_u32 v[52:53], s[68:69], v54, s40, v[2:3]
	s_add_i32 s68, s64, 24
	s_add_i32 s65, s37, 24
	v_or_b32_e32 v55, s68, v0
	v_or_b32_e32 v54, s65, v1
	s_add_i32 s64, s64, 28
	s_add_i32 s37, s37, 28
	s_cmp_lg_u32 s36, 0
	v_mov_b32_e32 v152, v50
	v_mov_b32_e32 v153, v52
	v_or_b32_e32 v50, s68, v4
	v_or_b32_e32 v52, s65, v3
	v_mad_u64_u32 v[50:51], s[68:69], v50, s67, v[48:49]
	v_mad_u64_u32 v[52:53], s[68:69], v52, s67, v[48:49]
	global_load_dword v138, v[50:51], off
	global_load_dword v139, v[52:53], off
	v_mad_u64_u32 v[50:51], s[68:69], v55, s40, v[2:3]
	v_mad_u64_u32 v[52:53], s[68:69], v54, s40, v[2:3]
	v_or_b32_e32 v55, s64, v0
	v_or_b32_e32 v54, s37, v1
	v_mov_b32_e32 v154, v50
	v_mov_b32_e32 v155, v52
	v_or_b32_e32 v50, s64, v4
	v_or_b32_e32 v52, s37, v3
	v_mad_u64_u32 v[50:51], s[64:65], v50, s67, v[48:49]
	v_mad_u64_u32 v[52:53], s[64:65], v52, s67, v[48:49]
	global_load_dword v140, v[50:51], off
	global_load_dword v141, v[52:53], off
	v_mad_u64_u32 v[50:51], s[64:65], v55, s40, v[2:3]
	v_mad_u64_u32 v[52:53], s[64:65], v54, s40, v[2:3]
	v_mov_b32_e32 v156, v50
	v_mov_b32_e32 v157, v52
	s_waitcnt vmcnt(15)
	ds_write_b32 v142, v126
	s_waitcnt vmcnt(14)
	ds_write_b32 v143, v127
	s_waitcnt vmcnt(13)
	ds_write_b32 v144, v128
	s_waitcnt vmcnt(12)
	ds_write_b32 v145, v129
	s_waitcnt vmcnt(11)
	ds_write_b32 v146, v130
	s_waitcnt vmcnt(10)
	ds_write_b32 v147, v131
	s_waitcnt vmcnt(9)
	ds_write_b32 v148, v132
	s_waitcnt vmcnt(8)
	ds_write_b32 v149, v133
	s_waitcnt vmcnt(7)
	ds_write_b32 v150, v134
	s_waitcnt vmcnt(6)
	ds_write_b32 v151, v135
	s_waitcnt vmcnt(5)
	ds_write_b32 v152, v136
	s_waitcnt vmcnt(4)
	ds_write_b32 v153, v137
	s_waitcnt vmcnt(3)
	ds_write_b32 v154, v138
	s_waitcnt vmcnt(2)
	ds_write_b32 v155, v139
	s_waitcnt vmcnt(1)
	ds_write_b32 v156, v140
	s_waitcnt vmcnt(0)
	ds_write_b32 v157, v141
	s_cbranch_scc1 .LBB0_935
	v_or_b32_e32 v4, v101, v60
	v_cndmask_b32_e64 v3, 0, 1, s[94:95]
	v_mov_b32_e32 v71, 1.0
	v_cmp_ne_u32_e64 s[8:9], 1, v3
	s_andn2_b64 vcc, exec, s[94:95]
	v_lshlrev_b32_e32 v3, 2, v4
	v_mov_b32_e32 v70, 1.0
	s_cbranch_vccnz .LBB0_938
	global_load_dword v70, v3, s[78:79]

.LBB0_956:
	s_lshl_b32 s36, s9, 1
	s_lshl_b32 s35, s8, 1
	v_or_b32_e32 v50, s36, v4
	v_or_b32_e32 v52, s35, v3
	v_mad_u64_u32 v[50:51], s[64:65], v50, s67, v[48:49]
	v_mad_u64_u32 v[52:53], s[64:65], v52, s67, v[48:49]
	global_load_dword v126, v[50:51], off
	global_load_dword v127, v[52:53], off
	v_or_b32_e32 v54, s35, v1
	v_or_b32_e32 v55, s36, v0
	v_mad_u64_u32 v[50:51], s[64:65], v55, s40, v[2:3]
	v_mad_u64_u32 v[52:53], s[64:65], v54, s40, v[2:3]
	s_add_i32 s64, s36, 4
	s_add_i32 s37, s35, 4
	v_or_b32_e32 v55, s64, v0
	v_or_b32_e32 v54, s37, v1
	s_add_i32 s9, s9, 16
	s_add_i32 s8, s8, 16
	s_add_i32 s34, s34, -16
	v_mov_b32_e32 v142, v50
	v_mov_b32_e32 v143, v52
	v_or_b32_e32 v50, s64, v4
	v_or_b32_e32 v52, s37, v3
	v_mad_u64_u32 v[50:51], s[64:65], v50, s67, v[48:49]
	v_mad_u64_u32 v[52:53], s[64:65], v52, s67, v[48:49]
	global_load_dword v128, v[50:51], off
	global_load_dword v129, v[52:53], off
	v_mad_u64_u32 v[50:51], s[64:65], v55, s40, v[2:3]
	v_mad_u64_u32 v[52:53], s[64:65], v54, s40, v[2:3]
	s_add_i32 s64, s36, 8
	s_add_i32 s37, s35, 8
	v_or_b32_e32 v55, s64, v0
	v_or_b32_e32 v54, s37, v1
	v_mov_b32_e32 v144, v50
	v_mov_b32_e32 v145, v52
	v_or_b32_e32 v50, s64, v4
	v_or_b32_e32 v52, s37, v3
	v_mad_u64_u32 v[50:51], s[64:65], v50, s67, v[48:49]
	v_mad_u64_u32 v[52:53], s[64:65], v52, s67, v[48:49]
	global_load_dword v130, v[50:51], off
	global_load_dword v131, v[52:53], off
	v_mad_u64_u32 v[50:51], s[64:65], v55, s40, v[2:3]
	v_mad_u64_u32 v[52:53], s[64:65], v54, s40, v[2:3]
	s_add_i32 s64, s36, 12
	s_add_i32 s37, s35, 12
	v_or_b32_e32 v55, s64, v0
	v_or_b32_e32 v54, s37, v1
	v_mov_b32_e32 v146, v50
	v_mov_b32_e32 v147, v52
	v_or_b32_e32 v50, s64, v4
	v_or_b32_e32 v52, s37, v3
	v_mad_u64_u32 v[50:51], s[64:65], v50, s67, v[48:49]
	v_mad_u64_u32 v[52:53], s[64:65], v52, s67, v[48:49]
	global_load_dword v132, v[50:51], off
	global_load_dword v133, v[52:53], off
	v_mad_u64_u32 v[50:51], s[64:65], v55, s40, v[2:3]
	v_mad_u64_u32 v[52:53], s[64:65], v54, s40, v[2:3]
	s_add_i32 s64, s36, 16
	s_add_i32 s37, s35, 16
	v_or_b32_e32 v55, s64, v0
	v_or_b32_e32 v54, s37, v1
	v_mov_b32_e32 v148, v50
	v_mov_b32_e32 v149, v52
	v_or_b32_e32 v50, s64, v4
	v_or_b32_e32 v52, s37, v3
	v_mad_u64_u32 v[50:51], s[64:65], v50, s67, v[48:49]
	v_mad_u64_u32 v[52:53], s[64:65], v52, s67, v[48:49]
	global_load_dword v134, v[50:51], off
	global_load_dword v135, v[52:53], off
	v_mad_u64_u32 v[50:51], s[64:65], v55, s40, v[2:3]
	v_mad_u64_u32 v[52:53], s[64:65], v54, s40, v[2:3]
	s_add_i32 s64, s36, 20
	s_add_i32 s37, s35, 20
	v_or_b32_e32 v55, s64, v0
	v_or_b32_e32 v54, s37, v1
	v_mov_b32_e32 v150, v50
	v_mov_b32_e32 v151, v52
	v_or_b32_e32 v50, s64, v4
	v_or_b32_e32 v52, s37, v3
	v_mad_u64_u32 v[50:51], s[64:65], v50, s67, v[48:49]
	v_mad_u64_u32 v[52:53], s[64:65], v52, s67, v[48:49]
	global_load_dword v136, v[50:51], off
	global_load_dword v137, v[52:53], off
	v_mad_u64_u32 v[50:51], s[64:65], v55, s40, v[2:3]
	v_mad_u64_u32 v[52:53], s[64:65], v54, s40, v[2:3]
	s_add_i32 s64, s36, 24
	s_add_i32 s37, s35, 24
	v_or_b32_e32 v55, s64, v0
	v_or_b32_e32 v54, s37, v1
	s_add_i32 s36, s36, 28
	s_add_i32 s35, s35, 28
	s_cmp_lg_u32 s34, 0
	v_mov_b32_e32 v152, v50
	v_mov_b32_e32 v153, v52
	v_or_b32_e32 v50, s64, v4
	v_or_b32_e32 v52, s37, v3
	v_mad_u64_u32 v[50:51], s[64:65], v50, s67, v[48:49]
	v_mad_u64_u32 v[52:53], s[64:65], v52, s67, v[48:49]
	global_load_dword v138, v[50:51], off
	global_load_dword v139, v[52:53], off
	v_mad_u64_u32 v[50:51], s[64:65], v55, s40, v[2:3]
	v_mad_u64_u32 v[52:53], s[64:65], v54, s40, v[2:3]
	v_or_b32_e32 v55, s36, v0
	v_or_b32_e32 v54, s35, v1
	v_mov_b32_e32 v154, v50
	v_mov_b32_e32 v155, v52
	v_or_b32_e32 v50, s36, v4
	v_or_b32_e32 v52, s35, v3
	v_mad_u64_u32 v[50:51], s[36:37], v50, s67, v[48:49]
	v_mad_u64_u32 v[52:53], s[36:37], v52, s67, v[48:49]
	global_load_dword v140, v[50:51], off
	global_load_dword v141, v[52:53], off
	v_mad_u64_u32 v[50:51], s[36:37], v55, s40, v[2:3]
	v_mad_u64_u32 v[52:53], s[36:37], v54, s40, v[2:3]
	v_mov_b32_e32 v156, v50
	v_mov_b32_e32 v157, v52
	s_waitcnt vmcnt(15)
	ds_write_b32 v142, v126
	s_waitcnt vmcnt(14)
	ds_write_b32 v143, v127
	s_waitcnt vmcnt(13)
	ds_write_b32 v144, v128
	s_waitcnt vmcnt(12)
	ds_write_b32 v145, v129
	s_waitcnt vmcnt(11)
	ds_write_b32 v146, v130
	s_waitcnt vmcnt(10)
	ds_write_b32 v147, v131
	s_waitcnt vmcnt(9)
	ds_write_b32 v148, v132
	s_waitcnt vmcnt(8)
	ds_write_b32 v149, v133
	s_waitcnt vmcnt(7)
	ds_write_b32 v150, v134
	s_waitcnt vmcnt(6)
	ds_write_b32 v151, v135
	s_waitcnt vmcnt(5)
	ds_write_b32 v152, v136
	s_waitcnt vmcnt(4)
	ds_write_b32 v153, v137
	s_waitcnt vmcnt(3)
	ds_write_b32 v154, v138
	s_waitcnt vmcnt(2)
	ds_write_b32 v155, v139
	s_waitcnt vmcnt(1)
	ds_write_b32 v156, v140
	s_waitcnt vmcnt(0)
	ds_write_b32 v157, v141
	s_cbranch_scc1 .LBB0_956
	v_or_b32_e32 v4, v101, v60
	v_cndmask_b32_e64 v3, 0, 1, s[94:95]
	v_mov_b32_e32 v69, 1.0
	v_cmp_ne_u32_e64 s[8:9], 1, v3
	s_andn2_b64 vcc, exec, s[94:95]
	v_lshlrev_b32_e32 v3, 2, v4
	v_mov_b32_e32 v68, 1.0
	s_cbranch_vccnz .LBB0_959
	global_load_dword v68, v3, s[78:79]

.LBB0_977:
	s_lshl_b32 s34, s9, 1
	s_lshl_b32 s11, s8, 1
	v_or_b32_e32 v54, s34, v4
	v_or_b32_e32 v56, s11, v3
	v_mad_i64_i32 v[54:55], s[36:37], v54, s41, v[52:53]
	v_mad_i64_i32 v[56:57], s[36:37], v56, s41, v[52:53]
	global_load_dword v126, v[54:55], off
	global_load_dword v127, v[56:57], off
	v_or_b32_e32 v49, s11, v1
	v_or_b32_e32 v51, s34, v0
	v_mad_u64_u32 v[54:55], s[36:37], v51, s40, v[2:3]
	v_mad_u64_u32 v[56:57], s[36:37], v49, s40, v[2:3]
	s_add_i32 s36, s34, 4
	s_add_i32 s35, s11, 4
	v_or_b32_e32 v51, s36, v0
	v_or_b32_e32 v49, s35, v1
	s_add_i32 s9, s9, 16
	s_add_i32 s8, s8, 16
	s_add_i32 s10, s10, -16
	v_mov_b32_e32 v142, v54
	v_mov_b32_e32 v143, v56
	v_or_b32_e32 v54, s36, v4
	v_or_b32_e32 v56, s35, v3
	v_mad_i64_i32 v[54:55], s[36:37], v54, s41, v[52:53]
	v_mad_i64_i32 v[56:57], s[36:37], v56, s41, v[52:53]
	global_load_dword v128, v[54:55], off
	global_load_dword v129, v[56:57], off
	v_mad_u64_u32 v[54:55], s[36:37], v51, s40, v[2:3]
	v_mad_u64_u32 v[56:57], s[36:37], v49, s40, v[2:3]
	s_add_i32 s36, s34, 8
	s_add_i32 s35, s11, 8
	v_or_b32_e32 v51, s36, v0
	v_or_b32_e32 v49, s35, v1
	v_mov_b32_e32 v144, v54
	v_mov_b32_e32 v145, v56
	v_or_b32_e32 v54, s36, v4
	v_or_b32_e32 v56, s35, v3
	v_mad_i64_i32 v[54:55], s[36:37], v54, s41, v[52:53]
	v_mad_i64_i32 v[56:57], s[36:37], v56, s41, v[52:53]
	global_load_dword v130, v[54:55], off
	global_load_dword v131, v[56:57], off
	v_mad_u64_u32 v[54:55], s[36:37], v51, s40, v[2:3]
	v_mad_u64_u32 v[56:57], s[36:37], v49, s40, v[2:3]
	s_add_i32 s36, s34, 12
	s_add_i32 s35, s11, 12
	v_or_b32_e32 v51, s36, v0
	v_or_b32_e32 v49, s35, v1
	v_mov_b32_e32 v146, v54
	v_mov_b32_e32 v147, v56
	v_or_b32_e32 v54, s36, v4
	v_or_b32_e32 v56, s35, v3
	v_mad_i64_i32 v[54:55], s[36:37], v54, s41, v[52:53]
	v_mad_i64_i32 v[56:57], s[36:37], v56, s41, v[52:53]
	global_load_dword v132, v[54:55], off
	global_load_dword v133, v[56:57], off
	v_mad_u64_u32 v[54:55], s[36:37], v51, s40, v[2:3]
	v_mad_u64_u32 v[56:57], s[36:37], v49, s40, v[2:3]
	s_add_i32 s36, s34, 16
	s_add_i32 s35, s11, 16
	v_or_b32_e32 v51, s36, v0
	v_or_b32_e32 v49, s35, v1
	v_mov_b32_e32 v148, v54
	v_mov_b32_e32 v149, v56
	v_or_b32_e32 v54, s36, v4
	v_or_b32_e32 v56, s35, v3
	v_mad_i64_i32 v[54:55], s[36:37], v54, s41, v[52:53]
	v_mad_i64_i32 v[56:57], s[36:37], v56, s41, v[52:53]
	global_load_dword v134, v[54:55], off
	global_load_dword v135, v[56:57], off
	v_mad_u64_u32 v[54:55], s[36:37], v51, s40, v[2:3]
	v_mad_u64_u32 v[56:57], s[36:37], v49, s40, v[2:3]
	s_add_i32 s36, s34, 20
	s_add_i32 s35, s11, 20
	v_or_b32_e32 v51, s36, v0
	v_or_b32_e32 v49, s35, v1
	v_mov_b32_e32 v150, v54
	v_mov_b32_e32 v151, v56
	v_or_b32_e32 v54, s36, v4
	v_or_b32_e32 v56, s35, v3
	v_mad_i64_i32 v[54:55], s[36:37], v54, s41, v[52:53]
	v_mad_i64_i32 v[56:57], s[36:37], v56, s41, v[52:53]
	global_load_dword v136, v[54:55], off
	global_load_dword v137, v[56:57], off
	v_mad_u64_u32 v[54:55], s[36:37], v51, s40, v[2:3]
	v_mad_u64_u32 v[56:57], s[36:37], v49, s40, v[2:3]
	s_add_i32 s36, s34, 24
	s_add_i32 s35, s11, 24
	v_or_b32_e32 v51, s36, v0
	v_or_b32_e32 v49, s35, v1
	s_add_i32 s34, s34, 28
	s_add_i32 s11, s11, 28
	s_cmp_lg_u32 s10, 0
	v_mov_b32_e32 v152, v54
	v_mov_b32_e32 v153, v56
	v_or_b32_e32 v54, s36, v4
	v_or_b32_e32 v56, s35, v3
	v_mad_i64_i32 v[54:55], s[36:37], v54, s41, v[52:53]
	v_mad_i64_i32 v[56:57], s[36:37], v56, s41, v[52:53]
	global_load_dword v138, v[54:55], off
	global_load_dword v139, v[56:57], off
	v_mad_u64_u32 v[54:55], s[36:37], v51, s40, v[2:3]
	v_mad_u64_u32 v[56:57], s[36:37], v49, s40, v[2:3]
	v_or_b32_e32 v51, s34, v0
	v_or_b32_e32 v49, s11, v1
	v_mov_b32_e32 v154, v54
	v_mov_b32_e32 v155, v56
	v_or_b32_e32 v54, s34, v4
	v_or_b32_e32 v56, s11, v3
	v_mad_i64_i32 v[54:55], s[34:35], v54, s41, v[52:53]
	v_mad_i64_i32 v[56:57], s[34:35], v56, s41, v[52:53]
	global_load_dword v140, v[54:55], off
	global_load_dword v141, v[56:57], off
	v_mad_u64_u32 v[54:55], s[34:35], v51, s40, v[2:3]
	v_mad_u64_u32 v[56:57], s[34:35], v49, s40, v[2:3]
	v_mov_b32_e32 v156, v54
	v_mov_b32_e32 v157, v56
	s_waitcnt vmcnt(15)
	ds_write_b32 v142, v126
	s_waitcnt vmcnt(14)
	ds_write_b32 v143, v127
	s_waitcnt vmcnt(13)
	ds_write_b32 v144, v128
	s_waitcnt vmcnt(12)
	ds_write_b32 v145, v129
	s_waitcnt vmcnt(11)
	ds_write_b32 v146, v130
	s_waitcnt vmcnt(10)
	ds_write_b32 v147, v131
	s_waitcnt vmcnt(9)
	ds_write_b32 v148, v132
	s_waitcnt vmcnt(8)
	ds_write_b32 v149, v133
	s_waitcnt vmcnt(7)
	ds_write_b32 v150, v134
	s_waitcnt vmcnt(6)
	ds_write_b32 v151, v135
	s_waitcnt vmcnt(5)
	ds_write_b32 v152, v136
	s_waitcnt vmcnt(4)
	ds_write_b32 v153, v137
	s_waitcnt vmcnt(3)
	ds_write_b32 v154, v138
	s_waitcnt vmcnt(2)
	ds_write_b32 v155, v139
	s_waitcnt vmcnt(1)
	ds_write_b32 v156, v140
	s_waitcnt vmcnt(0)
	ds_write_b32 v157, v141
	s_cbranch_scc1 .LBB0_977
	v_or_b32_e32 v52, v50, v101
	v_cndmask_b32_e64 v3, 0, 1, s[96:97]
	v_mov_b32_e32 v71, 1.0
	v_cmp_ne_u32_e64 s[8:9], 1, v3
	s_andn2_b64 vcc, exec, s[96:97]
	v_ashrrev_i32_e32 v53, 31, v52
	v_mov_b32_e32 v70, 1.0
	s_cbranch_vccnz .LBB0_980
	v_lshl_add_u64 v[54:55], v[52:53], 2, s[28:29]
	global_load_dword v70, v[54:55], off

.LBB0_1776:
	s_lshl_b32 s69, s64, 1
	s_lshl_b32 s70, s65, 1
	v_or_b32_e32 v56, s69, v1
	v_or_b32_e32 v57, s70, v0
	v_add_lshl_u32 v4, v56, v3, 10
	v_add_lshl_u32 v53, v57, v48, 10
	v_or_b32_e32 v52, v49, v4
	v_or_b32_e32 v4, v50, v53
	v_lshl_add_u64 v[54:55], v[4:5], 2, s[88:89]
	v_mov_b32_e32 v53, v5
	v_lshl_add_u64 v[52:53], v[52:53], 2, s[88:89]
	global_load_dword v126, v[54:55], off
	global_load_dword v127, v[52:53], off
	v_mad_u64_u32 v[52:53], s[72:73], v57, s40, v[2:3]
	v_mad_u64_u32 v[54:55], s[72:73], v56, s40, v[2:3]
	s_add_i32 s71, s69, 4
	s_add_i32 s72, s70, 4
	v_or_b32_e32 v56, s71, v1
	v_or_b32_e32 v57, s72, v0
	v_add_lshl_u32 v53, v57, v48, 10
	s_add_i32 s71, s69, 8
	s_add_i32 s65, s65, 16
	s_add_i32 s64, s64, 16
	s_add_i32 s68, s68, -16
	v_mov_b32_e32 v142, v52
	v_mov_b32_e32 v143, v54
	v_add_lshl_u32 v4, v56, v3, 10
	v_or_b32_e32 v52, v49, v4
	v_or_b32_e32 v4, v50, v53
	v_lshl_add_u64 v[54:55], v[4:5], 2, s[88:89]
	v_mov_b32_e32 v53, v5
	v_lshl_add_u64 v[52:53], v[52:53], 2, s[88:89]
	global_load_dword v128, v[54:55], off
	global_load_dword v129, v[52:53], off
	v_mad_u64_u32 v[52:53], s[72:73], v57, s40, v[2:3]
	v_mad_u64_u32 v[54:55], s[72:73], v56, s40, v[2:3]
	s_add_i32 s72, s70, 8
	v_or_b32_e32 v56, s71, v1
	v_or_b32_e32 v57, s72, v0
	v_add_lshl_u32 v53, v57, v48, 10
	s_add_i32 s71, s69, 12
	v_mov_b32_e32 v144, v52
	v_mov_b32_e32 v145, v54
	v_add_lshl_u32 v4, v56, v3, 10
	v_or_b32_e32 v52, v49, v4
	v_or_b32_e32 v4, v50, v53
	v_lshl_add_u64 v[54:55], v[4:5], 2, s[88:89]
	v_mov_b32_e32 v53, v5
	v_lshl_add_u64 v[52:53], v[52:53], 2, s[88:89]
	global_load_dword v130, v[54:55], off
	global_load_dword v131, v[52:53], off
	v_mad_u64_u32 v[52:53], s[72:73], v57, s40, v[2:3]
	v_mad_u64_u32 v[54:55], s[72:73], v56, s40, v[2:3]
	s_add_i32 s72, s70, 12
	v_or_b32_e32 v56, s71, v1
	v_or_b32_e32 v57, s72, v0
	v_add_lshl_u32 v53, v57, v48, 10
	s_add_i32 s71, s69, 16
	v_mov_b32_e32 v146, v52
	v_mov_b32_e32 v147, v54
	v_add_lshl_u32 v4, v56, v3, 10
	v_or_b32_e32 v52, v49, v4
	v_or_b32_e32 v4, v50, v53
	v_lshl_add_u64 v[54:55], v[4:5], 2, s[88:89]
	v_mov_b32_e32 v53, v5
	v_lshl_add_u64 v[52:53], v[52:53], 2, s[88:89]
	global_load_dword v132, v[54:55], off
	global_load_dword v133, v[52:53], off
	v_mad_u64_u32 v[52:53], s[72:73], v57, s40, v[2:3]
	v_mad_u64_u32 v[54:55], s[72:73], v56, s40, v[2:3]
	s_add_i32 s72, s70, 16
	v_or_b32_e32 v56, s71, v1
	v_or_b32_e32 v57, s72, v0
	v_add_lshl_u32 v53, v57, v48, 10
	s_add_i32 s71, s69, 20
	v_mov_b32_e32 v148, v52
	v_mov_b32_e32 v149, v54
	v_add_lshl_u32 v4, v56, v3, 10
	v_or_b32_e32 v52, v49, v4
	v_or_b32_e32 v4, v50, v53
	v_lshl_add_u64 v[54:55], v[4:5], 2, s[88:89]
	v_mov_b32_e32 v53, v5
	v_lshl_add_u64 v[52:53], v[52:53], 2, s[88:89]
	global_load_dword v134, v[54:55], off
	global_load_dword v135, v[52:53], off
	v_mad_u64_u32 v[52:53], s[72:73], v57, s40, v[2:3]
	v_mad_u64_u32 v[54:55], s[72:73], v56, s40, v[2:3]
	s_add_i32 s72, s70, 20
	v_or_b32_e32 v56, s71, v1
	v_or_b32_e32 v57, s72, v0
	v_add_lshl_u32 v53, v57, v48, 10
	s_add_i32 s71, s69, 24
	s_add_i32 s69, s69, 28
	v_mov_b32_e32 v150, v52
	v_mov_b32_e32 v151, v54
	v_add_lshl_u32 v4, v56, v3, 10
	v_or_b32_e32 v52, v49, v4
	v_or_b32_e32 v4, v50, v53
	v_lshl_add_u64 v[54:55], v[4:5], 2, s[88:89]
	v_mov_b32_e32 v53, v5
	v_lshl_add_u64 v[52:53], v[52:53], 2, s[88:89]
	global_load_dword v136, v[54:55], off
	global_load_dword v137, v[52:53], off
	v_mad_u64_u32 v[52:53], s[72:73], v57, s40, v[2:3]
	v_mad_u64_u32 v[54:55], s[72:73], v56, s40, v[2:3]
	s_add_i32 s72, s70, 24
	v_or_b32_e32 v56, s71, v1
	v_or_b32_e32 v57, s72, v0
	v_add_lshl_u32 v53, v57, v48, 10
	s_add_i32 s70, s70, 28
	s_cmp_lg_u32 s68, 0
	v_mov_b32_e32 v152, v52
	v_mov_b32_e32 v153, v54
	v_add_lshl_u32 v4, v56, v3, 10
	v_or_b32_e32 v52, v49, v4
	v_or_b32_e32 v4, v50, v53
	v_lshl_add_u64 v[54:55], v[4:5], 2, s[88:89]
	v_mov_b32_e32 v53, v5
	v_lshl_add_u64 v[52:53], v[52:53], 2, s[88:89]
	global_load_dword v138, v[54:55], off
	global_load_dword v139, v[52:53], off
	v_mad_u64_u32 v[52:53], s[72:73], v57, s40, v[2:3]
	v_mad_u64_u32 v[54:55], s[72:73], v56, s40, v[2:3]
	v_or_b32_e32 v56, s69, v1
	v_or_b32_e32 v57, s70, v0
	v_mov_b32_e32 v55, v5
	v_mov_b32_e32 v154, v52
	v_mov_b32_e32 v155, v54
	v_add_lshl_u32 v4, v56, v3, 10
	v_add_lshl_u32 v52, v57, v48, 10
	v_or_b32_e32 v54, v49, v4
	v_or_b32_e32 v4, v50, v52
	v_lshl_add_u64 v[52:53], v[4:5], 2, s[88:89]
	v_lshl_add_u64 v[54:55], v[54:55], 2, s[88:89]
	global_load_dword v140, v[52:53], off
	global_load_dword v141, v[54:55], off
	v_mad_u64_u32 v[52:53], s[70:71], v57, s40, v[2:3]
	v_mad_u64_u32 v[54:55], s[70:71], v56, s40, v[2:3]
	v_mov_b32_e32 v156, v52
	v_mov_b32_e32 v157, v54
	s_waitcnt vmcnt(15)
	ds_write_b32 v142, v126
	s_waitcnt vmcnt(14)
	ds_write_b32 v143, v127
	s_waitcnt vmcnt(13)
	ds_write_b32 v144, v128
	s_waitcnt vmcnt(12)
	ds_write_b32 v145, v129
	s_waitcnt vmcnt(11)
	ds_write_b32 v146, v130
	s_waitcnt vmcnt(10)
	ds_write_b32 v147, v131
	s_waitcnt vmcnt(9)
	ds_write_b32 v148, v132
	s_waitcnt vmcnt(8)
	ds_write_b32 v149, v133
	s_waitcnt vmcnt(7)
	ds_write_b32 v150, v134
	s_waitcnt vmcnt(6)
	ds_write_b32 v151, v135
	s_waitcnt vmcnt(5)
	ds_write_b32 v152, v136
	s_waitcnt vmcnt(4)
	ds_write_b32 v153, v137
	s_waitcnt vmcnt(3)
	ds_write_b32 v154, v138
	s_waitcnt vmcnt(2)
	ds_write_b32 v155, v139
	s_waitcnt vmcnt(1)
	ds_write_b32 v156, v140
	s_waitcnt vmcnt(0)
	ds_write_b32 v157, v141
	s_cbranch_scc1 .LBB0_1776
	v_or_b32_e32 v3, v51, v96
	v_lshlrev_b32_e32 v4, 2, v3
	v_or_b32_e32 v49, 0x5000, v4
	global_load_dword v90, v49, s[14:15]
	global_load_dword v80, v49, s[94:95]
	v_or_b32_e32 v49, 0x5020, v4
	global_load_dword v62, v49, s[14:15]
	global_load_dword v60, v49, s[94:95]
	v_or_b32_e32 v49, 0x5040, v4
	global_load_dword v58, v49, s[14:15]
	global_load_dword v56, v49, s[94:95]
	v_or_b32_e32 v4, 0x5060, v4
	global_load_dword v52, v4, s[14:15]
	global_load_dword v50, v4, s[94:95]
	s_waitcnt lgkmcnt(0)
	ds_read2_b32 v[74:75], v97 offset0:33 offset1:41
	ds_read2_b32 v[66:67], v97 offset0:66 offset1:74
	ds_read2_b32 v[64:65], v97 offset0:99 offset1:107
	ds_read2_b32 v[76:77], v97 offset0:132 offset1:140
	ds_read2_b32 v[72:73], v97 offset0:165 offset1:173
	ds_read2_b32 v[70:71], v97 offset0:198 offset1:206
	ds_read2_b32 v[68:69], v97 offset0:231 offset1:239
	ds_read2_b32 v[78:79], v97 offset1:8
	s_waitcnt lgkmcnt(4)
	v_mov_b32_e32 v86, v76
	v_mov_b32_e32 v83, v66
	s_waitcnt lgkmcnt(2)
	v_mov_b32_e32 v87, v70
	v_mov_b32_e32 v84, v74
	s_waitcnt lgkmcnt(0)
	v_mov_b32_e32 v82, v78
	v_mov_b32_e32 v85, v64
	v_mov_b32_e32 v88, v72
	v_mov_b32_e32 v89, v68
	v_lshlrev_b32_e32 v4, 1, v48
	v_lshl_add_u64 v[54:55], v[6:7], 0, v[4:5]
	v_lshl_add_u64 v[48:49], v[22:23], 0, v[4:5]
	v_mul_u32_u24_e32 v3, 0xb00, v3
	v_mov_b32_e32 v70, v77
	v_mov_b32_e32 v68, v73
	v_readlane_b32 s72, v255, 50
	v_readlane_b32 s70, v255, 48
	v_readlane_b32 s73, v255, 51
	v_readlane_b32 s71, v255, 49
	s_waitcnt vmcnt(7)
	v_pk_mul_f32 v[112:113], v[90:91], v[86:87] op_sel_hi:[0,1]
	v_pk_mul_f32 v[92:93], v[90:91], v[82:83] op_sel_hi:[0,1]
	v_pk_mul_f32 v[110:111], v[90:91], v[84:85] op_sel_hi:[0,1]
	v_pk_mul_f32 v[90:91], v[90:91], v[88:89] op_sel_hi:[0,1]
	v_bfe_u32 v64, v112, 16, 1
	v_bfe_u32 v66, v113, 16, 1
	v_bfe_u32 v4, v91, 16, 1
	v_bfe_u32 v53, v90, 16, 1
	v_bfe_u32 v63, v93, 16, 1
	v_add3_u32 v66, v113, v66, s46
	v_add3_u32 v64, v112, v64, s46
	v_bfe_u32 v57, v111, 16, 1
	v_add3_u32 v53, v90, v53, s46
	v_add3_u32 v4, v91, v4, s46
	v_bfe_u32 v61, v92, 16, 1
	v_add3_u32 v63, v93, v63, s46
	v_lshrrev_b32_e32 v64, 16, v64
	v_lshrrev_b32_e32 v66, 16, v66
	s_waitcnt vmcnt(6)
	v_pk_mul_f32 v[86:87], v[80:81], v[86:87] op_sel_hi:[0,1]
	v_bfe_u32 v59, v110, 16, 1
	v_add3_u32 v57, v111, v57, s46
	v_add3_u32 v61, v92, v61, s46
	v_lshrrev_b32_e32 v63, 16, v63
	v_and_or_b32 v93, v4, s47, v66
	v_and_or_b32 v92, v53, s47, v64
	v_pk_mul_f32 v[82:83], v[80:81], v[82:83] op_sel_hi:[0,1]
	v_pk_mul_f32 v[84:85], v[80:81], v[84:85] op_sel_hi:[0,1]
	v_pk_mul_f32 v[80:81], v[80:81], v[88:89] op_sel_hi:[0,1]
	v_bfe_u32 v64, v86, 16, 1
	v_bfe_u32 v66, v87, 16, 1
	v_add3_u32 v59, v110, v59, s46
	v_lshrrev_b32_e32 v61, 16, v61
	v_and_or_b32 v91, v57, s47, v63
	v_lshlrev_b32_e32 v4, 1, v3
	v_bfe_u32 v3, v81, 16, 1
	v_bfe_u32 v53, v80, 16, 1
	v_bfe_u32 v63, v83, 16, 1
	v_add3_u32 v66, v87, v66, s46
	v_add3_u32 v64, v86, v64, s46
	v_and_or_b32 v90, v59, s47, v61
	v_bfe_u32 v57, v85, 16, 1
	v_add3_u32 v53, v80, v53, s46
	v_add3_u32 v3, v81, v3, s46
	v_bfe_u32 v61, v82, 16, 1
	v_add3_u32 v63, v83, v63, s46
	v_lshrrev_b32_e32 v64, 16, v64
	v_lshrrev_b32_e32 v66, 16, v66
	v_add3_u32 v57, v85, v57, s46
	v_add3_u32 v61, v82, v61, s46
	v_lshrrev_b32_e32 v63, 16, v63
	v_and_or_b32 v83, v3, s47, v66
	v_and_or_b32 v82, v53, s47, v64
	v_mov_b32_e32 v66, v79
	v_mov_b32_e32 v64, v75
	v_and_or_b32 v81, v57, s47, v63
	s_waitcnt vmcnt(5)
	v_pk_mul_f32 v[78:79], v[62:63], v[66:67] op_sel_hi:[0,1]
	v_pk_mul_f32 v[74:75], v[62:63], v[64:65] op_sel_hi:[0,1]
	v_pk_mul_f32 v[76:77], v[62:63], v[70:71] op_sel_hi:[0,1]
	v_pk_mul_f32 v[62:63], v[62:63], v[68:69] op_sel_hi:[0,1]
	v_bfe_u32 v3, v63, 16, 1
	v_bfe_u32 v59, v84, 16, 1
	v_add3_u32 v3, v63, v3, s46
	v_bfe_u32 v63, v77, 16, 1
	v_lshl_add_u64 v[110:111], v[54:55], 0, v[4:5]
	v_add3_u32 v59, v84, v59, s46
	v_lshl_add_u64 v[84:85], v[48:49], 0, v[4:5]
	v_bfe_u32 v4, v62, 16, 1
	v_add3_u32 v63, v77, v63, s46
	v_lshrrev_b32_e32 v61, 16, v61
	v_bfe_u32 v53, v75, 16, 1
	v_add3_u32 v4, v62, v4, s46
	v_bfe_u32 v62, v76, 16, 1
	v_lshrrev_b32_e32 v63, 16, v63
	v_and_or_b32 v80, v59, s47, v61
	v_add3_u32 v53, v75, v53, s46
	v_bfe_u32 v59, v78, 16, 1
	v_bfe_u32 v61, v79, 16, 1
	v_add3_u32 v62, v76, v62, s46
	v_and_or_b32 v75, v3, s47, v63
	v_or_b32_e32 v3, v51, v98
	v_bfe_u32 v57, v74, 16, 1
	v_add3_u32 v61, v79, v61, s46
	v_add3_u32 v59, v78, v59, s46
	v_lshrrev_b32_e32 v62, 16, v62
	v_mul_u32_u24_e32 v3, 0xb00, v3
	v_add3_u32 v57, v74, v57, s46
	v_lshrrev_b32_e32 v59, 16, v59
	v_lshrrev_b32_e32 v61, 16, v61
	v_and_or_b32 v74, v4, s47, v62
	v_lshlrev_b32_e32 v4, 1, v3
	v_and_or_b32 v73, v53, s47, v61
	v_and_or_b32 v72, v57, s47, v59
	v_lshl_add_u64 v[62:63], v[54:55], 0, v[4:5]
	global_store_dwordx4 v[110:111], v[90:93], off
	global_store_dwordx4 v[84:85], v[80:83], off
	global_store_dwordx4 v[62:63], v[72:75], off
	s_waitcnt vmcnt(7)
	v_pk_mul_f32 v[62:63], v[60:61], v[66:67] op_sel_hi:[0,1]
	v_pk_mul_f32 v[64:65], v[60:61], v[64:65] op_sel_hi:[0,1]
	v_pk_mul_f32 v[66:67], v[60:61], v[70:71] op_sel_hi:[0,1]
	v_pk_mul_f32 v[60:61], v[60:61], v[68:69] op_sel_hi:[0,1]
	v_bfe_u32 v3, v61, 16, 1
	v_bfe_u32 v53, v60, 16, 1
	v_bfe_u32 v57, v65, 16, 1
	v_bfe_u32 v59, v64, 16, 1
	v_add3_u32 v59, v64, v59, s46
	v_add3_u32 v57, v65, v57, s46
	v_add3_u32 v53, v60, v53, s46
	v_add3_u32 v3, v61, v3, s46
	v_bfe_u32 v60, v62, 16, 1
	v_bfe_u32 v61, v63, 16, 1
	v_bfe_u32 v64, v66, 16, 1
	v_bfe_u32 v65, v67, 16, 1
	v_add3_u32 v65, v67, v65, s46
	v_add3_u32 v64, v66, v64, s46
	v_add3_u32 v61, v63, v61, s46
	v_add3_u32 v60, v62, v60, s46
	v_lshrrev_b32_e32 v60, 16, v60
	v_lshrrev_b32_e32 v61, 16, v61
	v_lshrrev_b32_e32 v62, 16, v64
	v_lshrrev_b32_e32 v63, 16, v65
	v_and_or_b32 v63, v3, s47, v63
	v_and_or_b32 v62, v53, s47, v62
	v_and_or_b32 v61, v57, s47, v61
	v_and_or_b32 v60, v59, s47, v60
	v_lshl_add_u64 v[64:65], v[48:49], 0, v[4:5]
	global_store_dwordx4 v[64:65], v[60:63], off
	ds_read2_b32 v[62:63], v97 offset0:16 offset1:24
	ds_read2_b32 v[64:65], v97 offset0:49 offset1:57
	ds_read2_b32 v[66:67], v97 offset0:82 offset1:90
	ds_read2_b32 v[68:69], v97 offset0:115 offset1:123
	ds_read2_b32 v[70:71], v97 offset0:148 offset1:156
	ds_read2_b32 v[72:73], v97 offset0:181 offset1:189
	ds_read2_b32 v[74:75], v97 offset0:214 offset1:222
	ds_read2_b32 v[76:77], v97 offset0:247 offset1:255
	s_waitcnt lgkmcnt(7)
	v_mov_b32_e32 v78, v62
	s_waitcnt lgkmcnt(5)
	v_mov_b32_e32 v79, v66
	v_mov_b32_e32 v80, v64
	s_waitcnt lgkmcnt(4)
	v_mov_b32_e32 v81, v68
	s_waitcnt lgkmcnt(3)
	v_mov_b32_e32 v84, v70
	s_waitcnt lgkmcnt(1)
	v_mov_b32_e32 v85, v74
	v_mov_b32_e32 v88, v72
	s_waitcnt lgkmcnt(0)
	v_mov_b32_e32 v89, v76
	s_waitcnt vmcnt(7)
	v_pk_mul_f32 v[60:61], v[58:59], v[78:79] op_sel_hi:[0,1]
	v_pk_mul_f32 v[82:83], v[58:59], v[80:81] op_sel_hi:[0,1]
	v_pk_mul_f32 v[86:87], v[58:59], v[84:85] op_sel_hi:[0,1]
	v_pk_mul_f32 v[58:59], v[58:59], v[88:89] op_sel_hi:[0,1]
	v_bfe_u32 v3, v59, 16, 1
	v_bfe_u32 v64, v87, 16, 1
	v_add3_u32 v3, v59, v3, s46
	v_bfe_u32 v59, v61, 16, 1
	v_add3_u32 v64, v87, v64, s46
	v_bfe_u32 v4, v58, 16, 1
	v_bfe_u32 v62, v86, 16, 1
	v_add3_u32 v59, v61, v59, s46
	v_lshrrev_b32_e32 v61, 16, v64
	v_add3_u32 v4, v58, v4, s46
	v_bfe_u32 v58, v60, 16, 1
	v_add3_u32 v62, v86, v62, s46
	v_and_or_b32 v61, v3, s47, v61
	v_or_b32_e32 v3, v51, v99
	v_bfe_u32 v53, v83, 16, 1
	v_bfe_u32 v57, v82, 16, 1
	v_add3_u32 v58, v60, v58, s46
	v_lshrrev_b32_e32 v60, 16, v62
	v_mul_u32_u24_e32 v3, 0xb00, v3
	v_add3_u32 v57, v82, v57, s46
	v_add3_u32 v53, v83, v53, s46
	v_lshrrev_b32_e32 v58, 16, v58
	v_lshrrev_b32_e32 v59, 16, v59
	v_and_or_b32 v60, v4, s47, v60
	v_lshlrev_b32_e32 v4, 1, v3
	v_and_or_b32 v59, v53, s47, v59
	v_and_or_b32 v58, v57, s47, v58
	v_lshl_add_u64 v[82:83], v[54:55], 0, v[4:5]
	global_store_dwordx4 v[82:83], v[58:61], off
	v_mov_b32_e32 v68, v65
	v_mov_b32_e32 v66, v63
	s_waitcnt vmcnt(7)
	v_pk_mul_f32 v[58:59], v[56:57], v[78:79] op_sel_hi:[0,1]
	v_pk_mul_f32 v[60:61], v[56:57], v[80:81] op_sel_hi:[0,1]
	v_pk_mul_f32 v[78:79], v[56:57], v[84:85] op_sel_hi:[0,1]
	v_pk_mul_f32 v[56:57], v[56:57], v[88:89] op_sel_hi:[0,1]
	v_bfe_u32 v3, v57, 16, 1
	v_bfe_u32 v53, v56, 16, 1
	v_bfe_u32 v62, v61, 16, 1
	v_bfe_u32 v64, v60, 16, 1
	v_add3_u32 v60, v60, v64, s46
	v_add3_u32 v61, v61, v62, s46
	v_add3_u32 v53, v56, v53, s46
	v_add3_u32 v3, v57, v3, s46
	v_bfe_u32 v56, v58, 16, 1
	v_bfe_u32 v57, v59, 16, 1
	v_bfe_u32 v62, v78, 16, 1
	v_bfe_u32 v64, v79, 16, 1
	v_add3_u32 v64, v79, v64, s46
	v_add3_u32 v62, v78, v62, s46
	v_add3_u32 v57, v59, v57, s46
	v_add3_u32 v56, v58, v56, s46
	v_lshrrev_b32_e32 v56, 16, v56
	v_lshrrev_b32_e32 v57, 16, v57
	v_lshrrev_b32_e32 v58, 16, v62
	v_lshrrev_b32_e32 v59, 16, v64
	v_and_or_b32 v59, v3, s47, v59
	v_and_or_b32 v58, v53, s47, v58
	v_and_or_b32 v57, v61, s47, v57
	v_and_or_b32 v56, v60, s47, v56
	v_lshl_add_u64 v[60:61], v[48:49], 0, v[4:5]
	global_store_dwordx4 v[60:61], v[56:59], off
	v_mov_b32_e32 v74, v71
	v_mov_b32_e32 v76, v73
	s_waitcnt vmcnt(7)
	v_pk_mul_f32 v[58:59], v[52:53], v[68:69] op_sel_hi:[0,1]
	v_pk_mul_f32 v[56:57], v[52:53], v[66:67] op_sel_hi:[0,1]
	v_pk_mul_f32 v[60:61], v[52:53], v[74:75] op_sel_hi:[0,1]
	v_pk_mul_f32 v[52:53], v[52:53], v[76:77] op_sel_hi:[0,1]
	v_bfe_u32 v62, v59, 16, 1
	v_bfe_u32 v3, v53, 16, 1
	v_add3_u32 v62, v59, v62, s46
	v_bfe_u32 v59, v61, 16, 1
	v_bfe_u32 v63, v58, 16, 1
	v_add3_u32 v3, v53, v3, s46
	v_bfe_u32 v53, v57, 16, 1
	v_add3_u32 v59, v61, v59, s46
	v_bfe_u32 v4, v52, 16, 1
	v_add3_u32 v63, v58, v63, s46
	v_bfe_u32 v58, v60, 16, 1
	v_add3_u32 v53, v57, v53, s46
	v_lshrrev_b32_e32 v57, 16, v59
	v_add3_u32 v4, v52, v4, s46
	v_bfe_u32 v52, v56, 16, 1
	v_add3_u32 v58, v60, v58, s46
	v_and_or_b32 v59, v3, s47, v57
	v_or_b32_e32 v3, v51, v100
	v_add3_u32 v52, v56, v52, s46
	v_lshrrev_b32_e32 v56, 16, v58
	v_mul_u32_u24_e32 v3, 0xb00, v3
	v_lshrrev_b32_e32 v52, 16, v52
	v_lshrrev_b32_e32 v53, 16, v53
	v_and_or_b32 v58, v4, s47, v56
	v_lshlrev_b32_e32 v4, 1, v3
	v_and_or_b32 v57, v62, s47, v53
	v_and_or_b32 v56, v63, s47, v52
	v_lshl_add_u64 v[52:53], v[54:55], 0, v[4:5]
	global_store_dwordx4 v[52:53], v[56:59], off
	s_waitcnt vmcnt(7)
	v_pk_mul_f32 v[52:53], v[50:51], v[66:67] op_sel_hi:[0,1]
	v_pk_mul_f32 v[54:55], v[50:51], v[68:69] op_sel_hi:[0,1]
	v_pk_mul_f32 v[56:57], v[50:51], v[74:75] op_sel_hi:[0,1]
	v_pk_mul_f32 v[50:51], v[50:51], v[76:77] op_sel_hi:[0,1]
	v_bfe_u32 v3, v51, 16, 1
	v_bfe_u32 v58, v50, 16, 1
	v_bfe_u32 v59, v55, 16, 1
	v_bfe_u32 v60, v54, 16, 1
	v_add3_u32 v54, v54, v60, s46
	v_add3_u32 v55, v55, v59, s46
	v_add3_u32 v50, v50, v58, s46
	v_add3_u32 v3, v51, v3, s46
	v_bfe_u32 v51, v52, 16, 1
	v_bfe_u32 v58, v53, 16, 1
	v_bfe_u32 v59, v56, 16, 1
	v_bfe_u32 v60, v57, 16, 1
	v_add3_u32 v57, v57, v60, s46
	v_add3_u32 v56, v56, v59, s46
	v_add3_u32 v53, v53, v58, s46
	v_add3_u32 v51, v52, v51, s46
	v_lshrrev_b32_e32 v58, 16, v51
	v_lshrrev_b32_e32 v51, 16, v53
	v_lshrrev_b32_e32 v52, 16, v56
	v_lshrrev_b32_e32 v53, 16, v57
	v_and_or_b32 v53, v3, s47, v53
	v_and_or_b32 v52, v50, s47, v52
	v_and_or_b32 v51, v55, s47, v51
	v_and_or_b32 v50, v54, s47, v58
	v_lshl_add_u64 v[48:49], v[48:49], 0, v[4:5]
	global_store_dwordx4 v[48:49], v[50:53], off
	s_waitcnt lgkmcnt(0)

.LBB0_1780:
	s_lshl_b32 s69, s64, 1
	s_lshl_b32 s70, s65, 1
	v_or_b32_e32 v56, s69, v1
	v_or_b32_e32 v57, s70, v0
	v_add_lshl_u32 v4, v56, v3, 10
	v_add_lshl_u32 v53, v57, v48, 10
	v_or_b32_e32 v52, v49, v4
	v_or_b32_e32 v4, v50, v53
	v_lshl_add_u64 v[54:55], v[4:5], 2, s[60:61]
	v_mov_b32_e32 v53, v5
	v_lshl_add_u64 v[52:53], v[52:53], 2, s[60:61]
	global_load_dword v126, v[54:55], off
	global_load_dword v127, v[52:53], off
	v_mad_u64_u32 v[52:53], s[72:73], v57, s40, v[2:3]
	v_mad_u64_u32 v[54:55], s[72:73], v56, s40, v[2:3]
	s_add_i32 s71, s69, 4
	s_add_i32 s72, s70, 4
	v_or_b32_e32 v56, s71, v1
	v_or_b32_e32 v57, s72, v0
	v_add_lshl_u32 v53, v57, v48, 10
	s_add_i32 s71, s69, 8
	s_add_i32 s65, s65, 16
	s_add_i32 s64, s64, 16
	s_add_i32 s68, s68, -16
	v_mov_b32_e32 v142, v52
	v_mov_b32_e32 v143, v54
	v_add_lshl_u32 v4, v56, v3, 10
	v_or_b32_e32 v52, v49, v4
	v_or_b32_e32 v4, v50, v53
	v_lshl_add_u64 v[54:55], v[4:5], 2, s[60:61]
	v_mov_b32_e32 v53, v5
	v_lshl_add_u64 v[52:53], v[52:53], 2, s[60:61]
	global_load_dword v128, v[54:55], off
	global_load_dword v129, v[52:53], off
	v_mad_u64_u32 v[52:53], s[72:73], v57, s40, v[2:3]
	v_mad_u64_u32 v[54:55], s[72:73], v56, s40, v[2:3]
	s_add_i32 s72, s70, 8
	v_or_b32_e32 v56, s71, v1
	v_or_b32_e32 v57, s72, v0
	v_add_lshl_u32 v53, v57, v48, 10
	s_add_i32 s71, s69, 12
	v_mov_b32_e32 v144, v52
	v_mov_b32_e32 v145, v54
	v_add_lshl_u32 v4, v56, v3, 10
	v_or_b32_e32 v52, v49, v4
	v_or_b32_e32 v4, v50, v53
	v_lshl_add_u64 v[54:55], v[4:5], 2, s[60:61]
	v_mov_b32_e32 v53, v5
	v_lshl_add_u64 v[52:53], v[52:53], 2, s[60:61]
	global_load_dword v130, v[54:55], off
	global_load_dword v131, v[52:53], off
	v_mad_u64_u32 v[52:53], s[72:73], v57, s40, v[2:3]
	v_mad_u64_u32 v[54:55], s[72:73], v56, s40, v[2:3]
	s_add_i32 s72, s70, 12
	v_or_b32_e32 v56, s71, v1
	v_or_b32_e32 v57, s72, v0
	v_add_lshl_u32 v53, v57, v48, 10
	s_add_i32 s71, s69, 16
	v_mov_b32_e32 v146, v52
	v_mov_b32_e32 v147, v54
	v_add_lshl_u32 v4, v56, v3, 10
	v_or_b32_e32 v52, v49, v4
	v_or_b32_e32 v4, v50, v53
	v_lshl_add_u64 v[54:55], v[4:5], 2, s[60:61]
	v_mov_b32_e32 v53, v5
	v_lshl_add_u64 v[52:53], v[52:53], 2, s[60:61]
	global_load_dword v132, v[54:55], off
	global_load_dword v133, v[52:53], off
	v_mad_u64_u32 v[52:53], s[72:73], v57, s40, v[2:3]
	v_mad_u64_u32 v[54:55], s[72:73], v56, s40, v[2:3]
	s_add_i32 s72, s70, 16
	v_or_b32_e32 v56, s71, v1
	v_or_b32_e32 v57, s72, v0
	v_add_lshl_u32 v53, v57, v48, 10
	s_add_i32 s71, s69, 20
	v_mov_b32_e32 v148, v52
	v_mov_b32_e32 v149, v54
	v_add_lshl_u32 v4, v56, v3, 10
	v_or_b32_e32 v52, v49, v4
	v_or_b32_e32 v4, v50, v53
	v_lshl_add_u64 v[54:55], v[4:5], 2, s[60:61]
	v_mov_b32_e32 v53, v5
	v_lshl_add_u64 v[52:53], v[52:53], 2, s[60:61]
	global_load_dword v134, v[54:55], off
	global_load_dword v135, v[52:53], off
	v_mad_u64_u32 v[52:53], s[72:73], v57, s40, v[2:3]
	v_mad_u64_u32 v[54:55], s[72:73], v56, s40, v[2:3]
	s_add_i32 s72, s70, 20
	v_or_b32_e32 v56, s71, v1
	v_or_b32_e32 v57, s72, v0
	v_add_lshl_u32 v53, v57, v48, 10
	s_add_i32 s71, s69, 24
	s_add_i32 s69, s69, 28
	v_mov_b32_e32 v150, v52
	v_mov_b32_e32 v151, v54
	v_add_lshl_u32 v4, v56, v3, 10
	v_or_b32_e32 v52, v49, v4
	v_or_b32_e32 v4, v50, v53
	v_lshl_add_u64 v[54:55], v[4:5], 2, s[60:61]
	v_mov_b32_e32 v53, v5
	v_lshl_add_u64 v[52:53], v[52:53], 2, s[60:61]
	global_load_dword v136, v[54:55], off
	global_load_dword v137, v[52:53], off
	v_mad_u64_u32 v[52:53], s[72:73], v57, s40, v[2:3]
	v_mad_u64_u32 v[54:55], s[72:73], v56, s40, v[2:3]
	s_add_i32 s72, s70, 24
	v_or_b32_e32 v56, s71, v1
	v_or_b32_e32 v57, s72, v0
	v_add_lshl_u32 v53, v57, v48, 10
	s_add_i32 s70, s70, 28
	s_cmp_lg_u32 s68, 0
	v_mov_b32_e32 v152, v52
	v_mov_b32_e32 v153, v54
	v_add_lshl_u32 v4, v56, v3, 10
	v_or_b32_e32 v52, v49, v4
	v_or_b32_e32 v4, v50, v53
	v_lshl_add_u64 v[54:55], v[4:5], 2, s[60:61]
	v_mov_b32_e32 v53, v5
	v_lshl_add_u64 v[52:53], v[52:53], 2, s[60:61]
	global_load_dword v138, v[54:55], off
	global_load_dword v139, v[52:53], off
	v_mad_u64_u32 v[52:53], s[72:73], v57, s40, v[2:3]
	v_mad_u64_u32 v[54:55], s[72:73], v56, s40, v[2:3]
	v_or_b32_e32 v56, s69, v1
	v_or_b32_e32 v57, s70, v0
	v_mov_b32_e32 v55, v5
	v_mov_b32_e32 v154, v52
	v_mov_b32_e32 v155, v54
	v_add_lshl_u32 v4, v56, v3, 10
	v_add_lshl_u32 v52, v57, v48, 10
	v_or_b32_e32 v54, v49, v4
	v_or_b32_e32 v4, v50, v52
	v_lshl_add_u64 v[52:53], v[4:5], 2, s[60:61]
	v_lshl_add_u64 v[54:55], v[54:55], 2, s[60:61]
	global_load_dword v140, v[52:53], off
	global_load_dword v141, v[54:55], off
	v_mad_u64_u32 v[52:53], s[70:71], v57, s40, v[2:3]
	v_mad_u64_u32 v[54:55], s[70:71], v56, s40, v[2:3]
	v_mov_b32_e32 v156, v52
	v_mov_b32_e32 v157, v54
	s_waitcnt vmcnt(15)
	ds_write_b32 v142, v126
	s_waitcnt vmcnt(14)
	ds_write_b32 v143, v127
	s_waitcnt vmcnt(13)
	ds_write_b32 v144, v128
	s_waitcnt vmcnt(12)
	ds_write_b32 v145, v129
	s_waitcnt vmcnt(11)
	ds_write_b32 v146, v130
	s_waitcnt vmcnt(10)
	ds_write_b32 v147, v131
	s_waitcnt vmcnt(9)
	ds_write_b32 v148, v132
	s_waitcnt vmcnt(8)
	ds_write_b32 v149, v133
	s_waitcnt vmcnt(7)
	ds_write_b32 v150, v134
	s_waitcnt vmcnt(6)
	ds_write_b32 v151, v135
	s_waitcnt vmcnt(5)
	ds_write_b32 v152, v136
	s_waitcnt vmcnt(4)
	ds_write_b32 v153, v137
	s_waitcnt vmcnt(3)
	ds_write_b32 v154, v138
	s_waitcnt vmcnt(2)
	ds_write_b32 v155, v139
	s_waitcnt vmcnt(1)
	ds_write_b32 v156, v140
	s_waitcnt vmcnt(0)
	ds_write_b32 v157, v141
	s_cbranch_scc1 .LBB0_1780
	v_or_b32_e32 v3, v51, v96
	v_lshlrev_b32_e32 v4, 2, v3
	v_or_b32_e32 v49, 0x2000, v4
	global_load_dword v90, v49, s[14:15]
	global_load_dword v80, v49, s[94:95]
	v_or_b32_e32 v49, 0x2020, v4
	global_load_dword v62, v49, s[14:15]
	global_load_dword v60, v49, s[94:95]
	v_or_b32_e32 v49, 0x2040, v4
	global_load_dword v58, v49, s[14:15]
	global_load_dword v56, v49, s[94:95]
	v_or_b32_e32 v4, 0x2060, v4
	global_load_dword v52, v4, s[14:15]
	global_load_dword v50, v4, s[94:95]
	s_waitcnt lgkmcnt(0)
	ds_read2_b32 v[74:75], v97 offset0:33 offset1:41
	ds_read2_b32 v[66:67], v97 offset0:66 offset1:74
	ds_read2_b32 v[64:65], v97 offset0:99 offset1:107
	ds_read2_b32 v[76:77], v97 offset0:132 offset1:140
	ds_read2_b32 v[72:73], v97 offset0:165 offset1:173
	ds_read2_b32 v[70:71], v97 offset0:198 offset1:206
	ds_read2_b32 v[68:69], v97 offset0:231 offset1:239
	ds_read2_b32 v[78:79], v97 offset1:8
	s_waitcnt lgkmcnt(4)
	v_mov_b32_e32 v86, v76
	v_mov_b32_e32 v83, v66
	s_waitcnt lgkmcnt(2)
	v_mov_b32_e32 v87, v70
	v_mov_b32_e32 v84, v74
	s_waitcnt lgkmcnt(0)
	v_mov_b32_e32 v82, v78
	v_mov_b32_e32 v85, v64
	v_mov_b32_e32 v88, v72
	v_mov_b32_e32 v89, v68
	v_lshlrev_b32_e32 v4, 1, v48
	v_lshl_add_u64 v[54:55], v[8:9], 0, v[4:5]
	v_lshl_add_u64 v[48:49], v[24:25], 0, v[4:5]
	v_mov_b32_e32 v70, v77
	v_mov_b32_e32 v68, v73
	v_readlane_b32 s72, v255, 50
	v_readlane_b32 s70, v255, 48
	v_readlane_b32 s73, v255, 51
	v_readlane_b32 s71, v255, 49
	s_waitcnt vmcnt(7)
	v_pk_mul_f32 v[112:113], v[90:91], v[86:87] op_sel_hi:[0,1]
	v_pk_mul_f32 v[92:93], v[90:91], v[82:83] op_sel_hi:[0,1]
	v_pk_mul_f32 v[110:111], v[90:91], v[84:85] op_sel_hi:[0,1]
	v_pk_mul_f32 v[90:91], v[90:91], v[88:89] op_sel_hi:[0,1]
	v_bfe_u32 v64, v112, 16, 1
	v_bfe_u32 v66, v113, 16, 1
	v_bfe_u32 v4, v91, 16, 1
	v_bfe_u32 v53, v90, 16, 1
	v_bfe_u32 v63, v93, 16, 1
	v_add3_u32 v66, v113, v66, s46
	v_add3_u32 v64, v112, v64, s46
	v_bfe_u32 v57, v111, 16, 1
	v_add3_u32 v53, v90, v53, s46
	v_add3_u32 v4, v91, v4, s46
	v_bfe_u32 v61, v92, 16, 1
	v_add3_u32 v63, v93, v63, s46
	v_lshrrev_b32_e32 v64, 16, v64
	v_lshrrev_b32_e32 v66, 16, v66
	s_waitcnt vmcnt(6)
	v_pk_mul_f32 v[86:87], v[80:81], v[86:87] op_sel_hi:[0,1]
	v_bfe_u32 v59, v110, 16, 1
	v_add3_u32 v57, v111, v57, s46
	v_add3_u32 v61, v92, v61, s46
	v_lshrrev_b32_e32 v63, 16, v63
	v_and_or_b32 v93, v4, s47, v66
	v_and_or_b32 v92, v53, s47, v64
	v_pk_mul_f32 v[82:83], v[80:81], v[82:83] op_sel_hi:[0,1]
	v_pk_mul_f32 v[84:85], v[80:81], v[84:85] op_sel_hi:[0,1]
	v_pk_mul_f32 v[80:81], v[80:81], v[88:89] op_sel_hi:[0,1]
	v_bfe_u32 v64, v86, 16, 1
	v_bfe_u32 v66, v87, 16, 1
	v_add3_u32 v59, v110, v59, s46
	v_lshrrev_b32_e32 v61, 16, v61
	v_and_or_b32 v91, v57, s47, v63
	v_lshlrev_b32_e32 v4, 11, v3
	v_bfe_u32 v3, v81, 16, 1
	v_bfe_u32 v53, v80, 16, 1
	v_bfe_u32 v63, v83, 16, 1
	v_add3_u32 v66, v87, v66, s46
	v_add3_u32 v64, v86, v64, s46
	v_and_or_b32 v90, v59, s47, v61
	v_bfe_u32 v57, v85, 16, 1
	v_add3_u32 v53, v80, v53, s46
	v_add3_u32 v3, v81, v3, s46
	v_bfe_u32 v61, v82, 16, 1
	v_add3_u32 v63, v83, v63, s46
	v_lshrrev_b32_e32 v64, 16, v64
	v_lshrrev_b32_e32 v66, 16, v66
	v_add3_u32 v57, v85, v57, s46
	v_add3_u32 v61, v82, v61, s46
	v_lshrrev_b32_e32 v63, 16, v63
	v_and_or_b32 v83, v3, s47, v66
	v_and_or_b32 v82, v53, s47, v64
	v_mov_b32_e32 v66, v79
	v_mov_b32_e32 v64, v75
	v_and_or_b32 v81, v57, s47, v63
	s_waitcnt vmcnt(5)
	v_pk_mul_f32 v[78:79], v[62:63], v[66:67] op_sel_hi:[0,1]
	v_pk_mul_f32 v[74:75], v[62:63], v[64:65] op_sel_hi:[0,1]
	v_pk_mul_f32 v[76:77], v[62:63], v[70:71] op_sel_hi:[0,1]
	v_pk_mul_f32 v[62:63], v[62:63], v[68:69] op_sel_hi:[0,1]
	v_bfe_u32 v59, v84, 16, 1
	v_bfe_u32 v3, v63, 16, 1
	v_lshl_add_u64 v[110:111], v[54:55], 0, v[4:5]
	v_add3_u32 v59, v84, v59, s46
	v_lshl_add_u64 v[84:85], v[48:49], 0, v[4:5]
	v_bfe_u32 v4, v62, 16, 1
	v_add3_u32 v3, v63, v3, s46
	v_bfe_u32 v63, v77, 16, 1
	v_lshrrev_b32_e32 v61, 16, v61
	v_add3_u32 v4, v62, v4, s46
	v_bfe_u32 v62, v76, 16, 1
	v_add3_u32 v63, v77, v63, s46
	v_and_or_b32 v80, v59, s47, v61
	v_bfe_u32 v53, v75, 16, 1
	v_bfe_u32 v59, v78, 16, 1
	v_bfe_u32 v61, v79, 16, 1
	v_add3_u32 v62, v76, v62, s46
	v_lshrrev_b32_e32 v63, 16, v63
	v_bfe_u32 v57, v74, 16, 1
	v_add3_u32 v53, v75, v53, s46
	v_add3_u32 v61, v79, v61, s46
	v_add3_u32 v59, v78, v59, s46
	v_lshrrev_b32_e32 v62, 16, v62
	v_and_or_b32 v75, v3, s47, v63
	v_or_b32_e32 v3, v51, v98
	v_add3_u32 v57, v74, v57, s46
	v_lshrrev_b32_e32 v59, 16, v59
	v_lshrrev_b32_e32 v61, 16, v61
	v_and_or_b32 v74, v4, s47, v62
	v_lshlrev_b32_e32 v4, 11, v3
	v_and_or_b32 v73, v53, s47, v61
	v_and_or_b32 v72, v57, s47, v59
	v_lshl_add_u64 v[62:63], v[54:55], 0, v[4:5]
	global_store_dwordx4 v[62:63], v[72:75], off
	s_waitcnt vmcnt(5)
	v_pk_mul_f32 v[62:63], v[60:61], v[66:67] op_sel_hi:[0,1]
	v_pk_mul_f32 v[64:65], v[60:61], v[64:65] op_sel_hi:[0,1]
	v_pk_mul_f32 v[66:67], v[60:61], v[70:71] op_sel_hi:[0,1]
	v_pk_mul_f32 v[60:61], v[60:61], v[68:69] op_sel_hi:[0,1]
	v_bfe_u32 v3, v61, 16, 1
	v_bfe_u32 v53, v60, 16, 1
	v_bfe_u32 v57, v65, 16, 1
	v_bfe_u32 v59, v64, 16, 1
	v_add3_u32 v59, v64, v59, s46
	v_add3_u32 v57, v65, v57, s46
	v_add3_u32 v53, v60, v53, s46
	v_add3_u32 v3, v61, v3, s46
	v_bfe_u32 v60, v62, 16, 1
	v_bfe_u32 v61, v63, 16, 1
	v_bfe_u32 v64, v66, 16, 1
	v_bfe_u32 v65, v67, 16, 1
	v_add3_u32 v65, v67, v65, s46
	v_add3_u32 v64, v66, v64, s46
	v_add3_u32 v61, v63, v61, s46
	v_add3_u32 v60, v62, v60, s46
	v_lshrrev_b32_e32 v60, 16, v60
	v_lshrrev_b32_e32 v61, 16, v61
	v_lshrrev_b32_e32 v62, 16, v64
	v_lshrrev_b32_e32 v63, 16, v65
	v_and_or_b32 v63, v3, s47, v63
	v_and_or_b32 v62, v53, s47, v62
	v_and_or_b32 v61, v57, s47, v61
	v_and_or_b32 v60, v59, s47, v60
	v_lshl_add_u64 v[64:65], v[48:49], 0, v[4:5]
	global_store_dwordx4 v[110:111], v[90:93], off
	global_store_dwordx4 v[84:85], v[80:83], off
	global_store_dwordx4 v[64:65], v[60:63], off
	ds_read2_b32 v[62:63], v97 offset0:49 offset1:57
	ds_read2_b32 v[64:65], v97 offset0:82 offset1:90
	ds_read2_b32 v[66:67], v97 offset0:115 offset1:123
	ds_read2_b32 v[68:69], v97 offset0:148 offset1:156
	ds_read2_b32 v[70:71], v97 offset0:181 offset1:189
	ds_read2_b32 v[72:73], v97 offset0:214 offset1:222
	ds_read2_b32 v[74:75], v97 offset0:247 offset1:255
	ds_read2_b32 v[76:77], v97 offset0:16 offset1:24
	s_waitcnt lgkmcnt(6)
	v_mov_b32_e32 v79, v64
	v_mov_b32_e32 v80, v62
	s_waitcnt lgkmcnt(5)
	v_mov_b32_e32 v81, v66
	s_waitcnt lgkmcnt(4)
	v_mov_b32_e32 v84, v68
	s_waitcnt lgkmcnt(0)
	v_mov_b32_e32 v78, v76
	v_mov_b32_e32 v85, v72
	v_mov_b32_e32 v88, v70
	v_mov_b32_e32 v89, v74
	s_waitcnt vmcnt(7)
	v_pk_mul_f32 v[60:61], v[58:59], v[78:79] op_sel_hi:[0,1]
	v_pk_mul_f32 v[82:83], v[58:59], v[80:81] op_sel_hi:[0,1]
	v_pk_mul_f32 v[86:87], v[58:59], v[84:85] op_sel_hi:[0,1]
	v_pk_mul_f32 v[58:59], v[58:59], v[88:89] op_sel_hi:[0,1]
	v_bfe_u32 v3, v59, 16, 1
	v_bfe_u32 v64, v87, 16, 1
	v_bfe_u32 v4, v58, 16, 1
	v_add3_u32 v3, v59, v3, s46
	v_bfe_u32 v59, v61, 16, 1
	v_bfe_u32 v62, v86, 16, 1
	v_add3_u32 v64, v87, v64, s46
	v_add3_u32 v4, v58, v4, s46
	v_bfe_u32 v58, v60, 16, 1
	v_add3_u32 v62, v86, v62, s46
	v_add3_u32 v59, v61, v59, s46
	v_lshrrev_b32_e32 v61, 16, v64
	v_bfe_u32 v53, v83, 16, 1
	v_bfe_u32 v57, v82, 16, 1
	v_add3_u32 v58, v60, v58, s46
	v_lshrrev_b32_e32 v60, 16, v62
	v_and_or_b32 v61, v3, s47, v61
	v_or_b32_e32 v3, v51, v99
	v_add3_u32 v57, v82, v57, s46
	v_add3_u32 v53, v83, v53, s46
	v_lshrrev_b32_e32 v58, 16, v58
	v_lshrrev_b32_e32 v59, 16, v59
	v_and_or_b32 v60, v4, s47, v60
	v_lshlrev_b32_e32 v4, 11, v3
	v_and_or_b32 v59, v53, s47, v59
	v_and_or_b32 v58, v57, s47, v58
	v_lshl_add_u64 v[82:83], v[54:55], 0, v[4:5]
	global_store_dwordx4 v[82:83], v[58:61], off
	v_mov_b32_e32 v66, v63
	v_mov_b32_e32 v72, v69
	s_waitcnt vmcnt(7)
	v_pk_mul_f32 v[58:59], v[56:57], v[78:79] op_sel_hi:[0,1]
	v_pk_mul_f32 v[60:61], v[56:57], v[80:81] op_sel_hi:[0,1]
	v_pk_mul_f32 v[78:79], v[56:57], v[84:85] op_sel_hi:[0,1]
	v_pk_mul_f32 v[56:57], v[56:57], v[88:89] op_sel_hi:[0,1]
	v_bfe_u32 v3, v57, 16, 1
	v_bfe_u32 v53, v56, 16, 1
	v_bfe_u32 v62, v61, 16, 1
	v_bfe_u32 v64, v60, 16, 1
	v_add3_u32 v60, v60, v64, s46
	v_add3_u32 v61, v61, v62, s46
	v_add3_u32 v53, v56, v53, s46
	v_add3_u32 v3, v57, v3, s46
	v_bfe_u32 v56, v58, 16, 1
	v_bfe_u32 v57, v59, 16, 1
	v_bfe_u32 v62, v78, 16, 1
	v_bfe_u32 v64, v79, 16, 1
	v_add3_u32 v64, v79, v64, s46
	v_add3_u32 v62, v78, v62, s46
	v_add3_u32 v57, v59, v57, s46
	v_add3_u32 v56, v58, v56, s46
	v_lshrrev_b32_e32 v56, 16, v56
	v_lshrrev_b32_e32 v57, 16, v57
	v_lshrrev_b32_e32 v58, 16, v62
	v_lshrrev_b32_e32 v59, 16, v64
	v_and_or_b32 v59, v3, s47, v59
	v_and_or_b32 v58, v53, s47, v58
	v_and_or_b32 v57, v61, s47, v57
	v_and_or_b32 v56, v60, s47, v56
	v_lshl_add_u64 v[60:61], v[48:49], 0, v[4:5]
	global_store_dwordx4 v[60:61], v[56:59], off
	v_mov_b32_e32 v64, v77
	v_mov_b32_e32 v74, v71
	s_waitcnt vmcnt(7)
	v_pk_mul_f32 v[58:59], v[52:53], v[66:67] op_sel_hi:[0,1]
	v_pk_mul_f32 v[56:57], v[52:53], v[64:65] op_sel_hi:[0,1]
	v_pk_mul_f32 v[60:61], v[52:53], v[72:73] op_sel_hi:[0,1]
	v_pk_mul_f32 v[52:53], v[52:53], v[74:75] op_sel_hi:[0,1]
	v_bfe_u32 v62, v59, 16, 1
	v_bfe_u32 v3, v53, 16, 1
	v_bfe_u32 v63, v58, 16, 1
	v_add3_u32 v62, v59, v62, s46
	v_bfe_u32 v59, v61, 16, 1
	v_bfe_u32 v4, v52, 16, 1
	v_add3_u32 v63, v58, v63, s46
	v_add3_u32 v3, v53, v3, s46
	v_bfe_u32 v53, v57, 16, 1
	v_bfe_u32 v58, v60, 16, 1
	v_add3_u32 v59, v61, v59, s46
	v_add3_u32 v4, v52, v4, s46
	v_bfe_u32 v52, v56, 16, 1
	v_add3_u32 v58, v60, v58, s46
	v_add3_u32 v53, v57, v53, s46
	v_lshrrev_b32_e32 v57, 16, v59
	v_add3_u32 v52, v56, v52, s46
	v_lshrrev_b32_e32 v56, 16, v58
	v_and_or_b32 v59, v3, s47, v57
	v_or_b32_e32 v3, v51, v100
	v_lshrrev_b32_e32 v52, 16, v52
	v_lshrrev_b32_e32 v53, 16, v53
	v_and_or_b32 v58, v4, s47, v56
	v_lshlrev_b32_e32 v4, 11, v3
	v_and_or_b32 v57, v62, s47, v53
	v_and_or_b32 v56, v63, s47, v52
	v_lshl_add_u64 v[52:53], v[54:55], 0, v[4:5]
	global_store_dwordx4 v[52:53], v[56:59], off
	s_waitcnt vmcnt(7)
	v_pk_mul_f32 v[52:53], v[50:51], v[64:65] op_sel_hi:[0,1]
	v_pk_mul_f32 v[54:55], v[50:51], v[66:67] op_sel_hi:[0,1]
	v_pk_mul_f32 v[56:57], v[50:51], v[72:73] op_sel_hi:[0,1]
	v_pk_mul_f32 v[50:51], v[50:51], v[74:75] op_sel_hi:[0,1]
	v_bfe_u32 v3, v51, 16, 1
	v_bfe_u32 v58, v50, 16, 1
	v_bfe_u32 v59, v55, 16, 1
	v_bfe_u32 v60, v54, 16, 1
	v_add3_u32 v54, v54, v60, s46
	v_add3_u32 v55, v55, v59, s46
	v_add3_u32 v50, v50, v58, s46
	v_add3_u32 v3, v51, v3, s46
	v_bfe_u32 v51, v52, 16, 1
	v_bfe_u32 v58, v53, 16, 1
	v_bfe_u32 v59, v56, 16, 1
	v_bfe_u32 v60, v57, 16, 1
	v_add3_u32 v57, v57, v60, s46
	v_add3_u32 v56, v56, v59, s46
	v_add3_u32 v53, v53, v58, s46
	v_add3_u32 v51, v52, v51, s46
	v_lshrrev_b32_e32 v58, 16, v51
	v_lshrrev_b32_e32 v51, 16, v53
	v_lshrrev_b32_e32 v52, 16, v56
	v_lshrrev_b32_e32 v53, 16, v57
	v_and_or_b32 v53, v3, s47, v53
	v_and_or_b32 v52, v50, s47, v52
	v_and_or_b32 v51, v55, s47, v51
	v_and_or_b32 v50, v54, s47, v58
	v_lshl_add_u64 v[48:49], v[48:49], 0, v[4:5]
	global_store_dwordx4 v[48:49], v[50:53], off
	s_waitcnt lgkmcnt(0)

.LBB0_1785:
	s_lshl_b32 s69, s64, 1
	s_lshl_b32 s70, s65, 1
	v_or_b32_e32 v56, s69, v1
	v_or_b32_e32 v57, s70, v0
	v_add_lshl_u32 v4, v56, v3, 10
	v_add_lshl_u32 v53, v57, v48, 10
	v_or_b32_e32 v52, v49, v4
	v_or_b32_e32 v4, v50, v53
	v_lshl_add_u64 v[54:55], v[4:5], 2, s[6:7]
	v_mov_b32_e32 v53, v5
	v_lshl_add_u64 v[52:53], v[52:53], 2, s[6:7]
	global_load_dword v126, v[54:55], off
	global_load_dword v127, v[52:53], off
	v_mad_u64_u32 v[52:53], s[72:73], v57, s40, v[2:3]
	v_mad_u64_u32 v[54:55], s[72:73], v56, s40, v[2:3]
	s_add_i32 s71, s69, 4
	s_add_i32 s72, s70, 4
	v_or_b32_e32 v56, s71, v1
	v_or_b32_e32 v57, s72, v0
	v_add_lshl_u32 v53, v57, v48, 10
	s_add_i32 s71, s69, 8
	s_add_i32 s65, s65, 16
	s_add_i32 s64, s64, 16
	s_add_i32 s68, s68, -16
	v_mov_b32_e32 v142, v52
	v_mov_b32_e32 v143, v54
	v_add_lshl_u32 v4, v56, v3, 10
	v_or_b32_e32 v52, v49, v4
	v_or_b32_e32 v4, v50, v53
	v_lshl_add_u64 v[54:55], v[4:5], 2, s[6:7]
	v_mov_b32_e32 v53, v5
	v_lshl_add_u64 v[52:53], v[52:53], 2, s[6:7]
	global_load_dword v128, v[54:55], off
	global_load_dword v129, v[52:53], off
	v_mad_u64_u32 v[52:53], s[72:73], v57, s40, v[2:3]
	v_mad_u64_u32 v[54:55], s[72:73], v56, s40, v[2:3]
	s_add_i32 s72, s70, 8
	v_or_b32_e32 v56, s71, v1
	v_or_b32_e32 v57, s72, v0
	v_add_lshl_u32 v53, v57, v48, 10
	s_add_i32 s71, s69, 12
	v_mov_b32_e32 v144, v52
	v_mov_b32_e32 v145, v54
	v_add_lshl_u32 v4, v56, v3, 10
	v_or_b32_e32 v52, v49, v4
	v_or_b32_e32 v4, v50, v53
	v_lshl_add_u64 v[54:55], v[4:5], 2, s[6:7]
	v_mov_b32_e32 v53, v5
	v_lshl_add_u64 v[52:53], v[52:53], 2, s[6:7]
	global_load_dword v130, v[54:55], off
	global_load_dword v131, v[52:53], off
	v_mad_u64_u32 v[52:53], s[72:73], v57, s40, v[2:3]
	v_mad_u64_u32 v[54:55], s[72:73], v56, s40, v[2:3]
	s_add_i32 s72, s70, 12
	v_or_b32_e32 v56, s71, v1
	v_or_b32_e32 v57, s72, v0
	v_add_lshl_u32 v53, v57, v48, 10
	s_add_i32 s71, s69, 16
	v_mov_b32_e32 v146, v52
	v_mov_b32_e32 v147, v54
	v_add_lshl_u32 v4, v56, v3, 10
	v_or_b32_e32 v52, v49, v4
	v_or_b32_e32 v4, v50, v53
	v_lshl_add_u64 v[54:55], v[4:5], 2, s[6:7]
	v_mov_b32_e32 v53, v5
	v_lshl_add_u64 v[52:53], v[52:53], 2, s[6:7]
	global_load_dword v132, v[54:55], off
	global_load_dword v133, v[52:53], off
	v_mad_u64_u32 v[52:53], s[72:73], v57, s40, v[2:3]
	v_mad_u64_u32 v[54:55], s[72:73], v56, s40, v[2:3]
	s_add_i32 s72, s70, 16
	v_or_b32_e32 v56, s71, v1
	v_or_b32_e32 v57, s72, v0
	v_add_lshl_u32 v53, v57, v48, 10
	s_add_i32 s71, s69, 20
	v_mov_b32_e32 v148, v52
	v_mov_b32_e32 v149, v54
	v_add_lshl_u32 v4, v56, v3, 10
	v_or_b32_e32 v52, v49, v4
	v_or_b32_e32 v4, v50, v53
	v_lshl_add_u64 v[54:55], v[4:5], 2, s[6:7]
	v_mov_b32_e32 v53, v5
	v_lshl_add_u64 v[52:53], v[52:53], 2, s[6:7]
	global_load_dword v134, v[54:55], off
	global_load_dword v135, v[52:53], off
	v_mad_u64_u32 v[52:53], s[72:73], v57, s40, v[2:3]
	v_mad_u64_u32 v[54:55], s[72:73], v56, s40, v[2:3]
	s_add_i32 s72, s70, 20
	v_or_b32_e32 v56, s71, v1
	v_or_b32_e32 v57, s72, v0
	v_add_lshl_u32 v53, v57, v48, 10
	s_add_i32 s71, s69, 24
	s_add_i32 s69, s69, 28
	v_mov_b32_e32 v150, v52
	v_mov_b32_e32 v151, v54
	v_add_lshl_u32 v4, v56, v3, 10
	v_or_b32_e32 v52, v49, v4
	v_or_b32_e32 v4, v50, v53
	v_lshl_add_u64 v[54:55], v[4:5], 2, s[6:7]
	v_mov_b32_e32 v53, v5
	v_lshl_add_u64 v[52:53], v[52:53], 2, s[6:7]
	global_load_dword v136, v[54:55], off
	global_load_dword v137, v[52:53], off
	v_mad_u64_u32 v[52:53], s[72:73], v57, s40, v[2:3]
	v_mad_u64_u32 v[54:55], s[72:73], v56, s40, v[2:3]
	s_add_i32 s72, s70, 24
	v_or_b32_e32 v56, s71, v1
	v_or_b32_e32 v57, s72, v0
	v_add_lshl_u32 v53, v57, v48, 10
	s_add_i32 s70, s70, 28
	s_cmp_lg_u32 s68, 0
	v_mov_b32_e32 v152, v52
	v_mov_b32_e32 v153, v54
	v_add_lshl_u32 v4, v56, v3, 10
	v_or_b32_e32 v52, v49, v4
	v_or_b32_e32 v4, v50, v53
	v_lshl_add_u64 v[54:55], v[4:5], 2, s[6:7]
	v_mov_b32_e32 v53, v5
	v_lshl_add_u64 v[52:53], v[52:53], 2, s[6:7]
	global_load_dword v138, v[54:55], off
	global_load_dword v139, v[52:53], off
	v_mad_u64_u32 v[52:53], s[72:73], v57, s40, v[2:3]
	v_mad_u64_u32 v[54:55], s[72:73], v56, s40, v[2:3]
	v_or_b32_e32 v56, s69, v1
	v_or_b32_e32 v57, s70, v0
	v_mov_b32_e32 v55, v5
	v_mov_b32_e32 v154, v52
	v_mov_b32_e32 v155, v54
	v_add_lshl_u32 v4, v56, v3, 10
	v_add_lshl_u32 v52, v57, v48, 10
	v_or_b32_e32 v54, v49, v4
	v_or_b32_e32 v4, v50, v52
	v_lshl_add_u64 v[52:53], v[4:5], 2, s[6:7]
	v_lshl_add_u64 v[54:55], v[54:55], 2, s[6:7]
	global_load_dword v140, v[52:53], off
	global_load_dword v141, v[54:55], off
	v_mad_u64_u32 v[52:53], s[70:71], v57, s40, v[2:3]
	v_mad_u64_u32 v[54:55], s[70:71], v56, s40, v[2:3]
	v_mov_b32_e32 v156, v52
	v_mov_b32_e32 v157, v54
	s_waitcnt vmcnt(15)
	ds_write_b32 v142, v126
	s_waitcnt vmcnt(14)
	ds_write_b32 v143, v127
	s_waitcnt vmcnt(13)
	ds_write_b32 v144, v128
	s_waitcnt vmcnt(12)
	ds_write_b32 v145, v129
	s_waitcnt vmcnt(11)
	ds_write_b32 v146, v130
	s_waitcnt vmcnt(10)
	ds_write_b32 v147, v131
	s_waitcnt vmcnt(9)
	ds_write_b32 v148, v132
	s_waitcnt vmcnt(8)
	ds_write_b32 v149, v133
	s_waitcnt vmcnt(7)
	ds_write_b32 v150, v134
	s_waitcnt vmcnt(6)
	ds_write_b32 v151, v135
	s_waitcnt vmcnt(5)
	ds_write_b32 v152, v136
	s_waitcnt vmcnt(4)
	ds_write_b32 v153, v137
	s_waitcnt vmcnt(3)
	ds_write_b32 v154, v138
	s_waitcnt vmcnt(2)
	ds_write_b32 v155, v139
	s_waitcnt vmcnt(1)
	ds_write_b32 v156, v140
	s_waitcnt vmcnt(0)
	ds_write_b32 v157, v141
	s_cbranch_scc1 .LBB0_1785
	s_waitcnt lgkmcnt(0)
	ds_read2_b32 v[56:57], v97 offset0:33 offset1:41
	ds_read2_b32 v[58:59], v97 offset0:66 offset1:74
	ds_read2_b32 v[60:61], v97 offset0:99 offset1:107
	ds_read2_b32 v[62:63], v97 offset1:8
	ds_read2_b32 v[64:65], v97 offset0:132 offset1:140
	ds_read2_b32 v[66:67], v97 offset0:165 offset1:173
	ds_read2_b32 v[68:69], v97 offset0:198 offset1:206
	ds_read2_b32 v[70:71], v97 offset0:231 offset1:239
	v_lshlrev_b32_e32 v4, 1, v48
	s_waitcnt lgkmcnt(4)
	v_bfe_u32 v3, v62, 16, 1
	v_lshl_add_u64 v[48:49], v[10:11], 0, v[4:5]
	v_add3_u32 v3, v62, v3, s46
	v_bfe_u32 v4, v56, 16, 1
	v_lshrrev_b32_e32 v3, 16, v3
	v_add3_u32 v4, v56, v4, s46
	v_and_or_b32 v52, v4, s47, v3
	v_bfe_u32 v3, v58, 16, 1
	v_add3_u32 v3, v58, v3, s46
	v_bfe_u32 v4, v60, 16, 1
	v_lshrrev_b32_e32 v3, 16, v3
	v_add3_u32 v4, v60, v4, s46
	v_and_or_b32 v53, v4, s47, v3
	s_waitcnt lgkmcnt(3)
	v_bfe_u32 v3, v64, 16, 1
	v_add3_u32 v3, v64, v3, s46
	s_waitcnt lgkmcnt(2)
	v_bfe_u32 v4, v66, 16, 1
	v_lshrrev_b32_e32 v3, 16, v3
	v_add3_u32 v4, v66, v4, s46
	v_and_or_b32 v54, v4, s47, v3
	s_waitcnt lgkmcnt(1)
	v_bfe_u32 v3, v68, 16, 1
	v_add3_u32 v3, v68, v3, s46
	s_waitcnt lgkmcnt(0)
	v_bfe_u32 v4, v70, 16, 1
	v_lshrrev_b32_e32 v3, 16, v3
	v_add3_u32 v4, v70, v4, s46
	v_and_or_b32 v55, v4, s47, v3
	v_or_b32_e32 v3, v51, v96
	v_lshlrev_b32_e32 v4, 9, v3
	v_bfe_u32 v3, v63, 16, 1
	v_lshl_add_u64 v[72:73], v[48:49], 0, v[4:5]
	v_add3_u32 v3, v63, v3, s46
	v_bfe_u32 v4, v57, 16, 1
	v_lshrrev_b32_e32 v3, 16, v3
	v_add3_u32 v4, v57, v4, s46
	global_store_dwordx4 v[72:73], v[52:55], off
	v_readlane_b32 s72, v255, 50
	v_readlane_b32 s70, v255, 48
	v_and_or_b32 v52, v4, s47, v3
	v_bfe_u32 v3, v59, 16, 1
	v_add3_u32 v3, v59, v3, s46
	v_bfe_u32 v4, v61, 16, 1
	v_lshrrev_b32_e32 v3, 16, v3
	v_add3_u32 v4, v61, v4, s46
	v_and_or_b32 v53, v4, s47, v3
	v_bfe_u32 v3, v65, 16, 1
	v_add3_u32 v3, v65, v3, s46
	v_bfe_u32 v4, v67, 16, 1
	v_lshrrev_b32_e32 v3, 16, v3
	v_add3_u32 v4, v67, v4, s46
	v_and_or_b32 v54, v4, s47, v3
	v_bfe_u32 v3, v69, 16, 1
	v_add3_u32 v3, v69, v3, s46
	v_bfe_u32 v4, v71, 16, 1
	v_lshrrev_b32_e32 v3, 16, v3
	v_add3_u32 v4, v71, v4, s46
	v_and_or_b32 v55, v4, s47, v3
	v_or_b32_e32 v3, v51, v98
	v_lshlrev_b32_e32 v4, 9, v3
	v_lshl_add_u64 v[56:57], v[48:49], 0, v[4:5]
	global_store_dwordx4 v[56:57], v[52:55], off
	ds_read2_b32 v[56:57], v97 offset0:49 offset1:57
	ds_read2_b32 v[58:59], v97 offset0:82 offset1:90
	ds_read2_b32 v[60:61], v97 offset0:115 offset1:123
	ds_read2_b32 v[62:63], v97 offset0:16 offset1:24
	ds_read2_b32 v[64:65], v97 offset0:148 offset1:156
	ds_read2_b32 v[66:67], v97 offset0:181 offset1:189
	ds_read2_b32 v[68:69], v97 offset0:214 offset1:222
	ds_read2_b32 v[70:71], v97 offset0:247 offset1:255
	s_waitcnt lgkmcnt(4)
	v_bfe_u32 v3, v62, 16, 1
	v_add3_u32 v3, v62, v3, s46
	v_bfe_u32 v4, v56, 16, 1
	v_lshrrev_b32_e32 v3, 16, v3
	v_add3_u32 v4, v56, v4, s46
	v_and_or_b32 v52, v4, s47, v3
	v_bfe_u32 v3, v58, 16, 1
	v_add3_u32 v3, v58, v3, s46
	v_bfe_u32 v4, v60, 16, 1
	v_lshrrev_b32_e32 v3, 16, v3
	v_add3_u32 v4, v60, v4, s46
	v_and_or_b32 v53, v4, s47, v3
	s_waitcnt lgkmcnt(3)
	v_bfe_u32 v3, v64, 16, 1
	v_add3_u32 v3, v64, v3, s46
	s_waitcnt lgkmcnt(2)
	v_bfe_u32 v4, v66, 16, 1
	v_lshrrev_b32_e32 v3, 16, v3
	v_add3_u32 v4, v66, v4, s46
	v_and_or_b32 v54, v4, s47, v3
	s_waitcnt lgkmcnt(1)
	v_bfe_u32 v3, v68, 16, 1
	v_add3_u32 v3, v68, v3, s46
	s_waitcnt lgkmcnt(0)
	v_bfe_u32 v4, v70, 16, 1
	v_lshrrev_b32_e32 v3, 16, v3
	v_add3_u32 v4, v70, v4, s46
	v_and_or_b32 v55, v4, s47, v3
	v_or_b32_e32 v3, v51, v99
	v_lshlrev_b32_e32 v4, 9, v3
	v_bfe_u32 v3, v63, 16, 1
	v_lshl_add_u64 v[72:73], v[48:49], 0, v[4:5]
	v_add3_u32 v3, v63, v3, s46
	v_bfe_u32 v4, v57, 16, 1
	v_lshrrev_b32_e32 v3, 16, v3
	v_add3_u32 v4, v57, v4, s46
	global_store_dwordx4 v[72:73], v[52:55], off
	v_readlane_b32 s73, v255, 51
	v_readlane_b32 s71, v255, 49
	v_and_or_b32 v52, v4, s47, v3
	v_bfe_u32 v3, v59, 16, 1
	v_add3_u32 v3, v59, v3, s46
	v_bfe_u32 v4, v61, 16, 1
	v_lshrrev_b32_e32 v3, 16, v3
	v_add3_u32 v4, v61, v4, s46
	v_and_or_b32 v53, v4, s47, v3
	v_bfe_u32 v3, v65, 16, 1
	v_add3_u32 v3, v65, v3, s46
	v_bfe_u32 v4, v67, 16, 1
	v_lshrrev_b32_e32 v3, 16, v3
	v_add3_u32 v4, v67, v4, s46
	v_and_or_b32 v54, v4, s47, v3
	v_bfe_u32 v3, v69, 16, 1
	v_add3_u32 v3, v69, v3, s46
	v_bfe_u32 v4, v71, 16, 1
	v_lshrrev_b32_e32 v3, 16, v3
	v_add3_u32 v4, v71, v4, s46
	v_and_or_b32 v55, v4, s47, v3
	v_or_b32_e32 v3, v51, v100
	v_lshlrev_b32_e32 v4, 9, v3
	v_lshl_add_u64 v[48:49], v[48:49], 0, v[4:5]
	global_store_dwordx4 v[48:49], v[52:55], off
	s_waitcnt lgkmcnt(0)

.LBB0_1790:
	s_lshl_b32 s69, s64, 1
	s_lshl_b32 s70, s65, 1
	v_or_b32_e32 v56, s69, v1
	v_or_b32_e32 v57, s70, v0
	v_add_lshl_u32 v4, v56, v3, 10
	v_add_lshl_u32 v53, v57, v48, 10
	v_or_b32_e32 v52, v49, v4
	v_or_b32_e32 v4, v50, v53
	v_lshl_add_u64 v[54:55], v[4:5], 2, s[4:5]
	v_mov_b32_e32 v53, v5
	v_lshl_add_u64 v[52:53], v[52:53], 2, s[4:5]
	global_load_dword v126, v[54:55], off
	global_load_dword v127, v[52:53], off
	v_mad_u64_u32 v[52:53], s[72:73], v57, s40, v[2:3]
	v_mad_u64_u32 v[54:55], s[72:73], v56, s40, v[2:3]
	s_add_i32 s71, s69, 4
	s_add_i32 s72, s70, 4
	v_or_b32_e32 v56, s71, v1
	v_or_b32_e32 v57, s72, v0
	v_add_lshl_u32 v53, v57, v48, 10
	s_add_i32 s71, s69, 8
	s_add_i32 s65, s65, 16
	s_add_i32 s64, s64, 16
	s_add_i32 s68, s68, -16
	v_mov_b32_e32 v142, v52
	v_mov_b32_e32 v143, v54
	v_add_lshl_u32 v4, v56, v3, 10
	v_or_b32_e32 v52, v49, v4
	v_or_b32_e32 v4, v50, v53
	v_lshl_add_u64 v[54:55], v[4:5], 2, s[4:5]
	v_mov_b32_e32 v53, v5
	v_lshl_add_u64 v[52:53], v[52:53], 2, s[4:5]
	global_load_dword v128, v[54:55], off
	global_load_dword v129, v[52:53], off
	v_mad_u64_u32 v[52:53], s[72:73], v57, s40, v[2:3]
	v_mad_u64_u32 v[54:55], s[72:73], v56, s40, v[2:3]
	s_add_i32 s72, s70, 8
	v_or_b32_e32 v56, s71, v1
	v_or_b32_e32 v57, s72, v0
	v_add_lshl_u32 v53, v57, v48, 10
	s_add_i32 s71, s69, 12
	v_mov_b32_e32 v144, v52
	v_mov_b32_e32 v145, v54
	v_add_lshl_u32 v4, v56, v3, 10
	v_or_b32_e32 v52, v49, v4
	v_or_b32_e32 v4, v50, v53
	v_lshl_add_u64 v[54:55], v[4:5], 2, s[4:5]
	v_mov_b32_e32 v53, v5
	v_lshl_add_u64 v[52:53], v[52:53], 2, s[4:5]
	global_load_dword v130, v[54:55], off
	global_load_dword v131, v[52:53], off
	v_mad_u64_u32 v[52:53], s[72:73], v57, s40, v[2:3]
	v_mad_u64_u32 v[54:55], s[72:73], v56, s40, v[2:3]
	s_add_i32 s72, s70, 12
	v_or_b32_e32 v56, s71, v1
	v_or_b32_e32 v57, s72, v0
	v_add_lshl_u32 v53, v57, v48, 10
	s_add_i32 s71, s69, 16
	v_mov_b32_e32 v146, v52
	v_mov_b32_e32 v147, v54
	v_add_lshl_u32 v4, v56, v3, 10
	v_or_b32_e32 v52, v49, v4
	v_or_b32_e32 v4, v50, v53
	v_lshl_add_u64 v[54:55], v[4:5], 2, s[4:5]
	v_mov_b32_e32 v53, v5
	v_lshl_add_u64 v[52:53], v[52:53], 2, s[4:5]
	global_load_dword v132, v[54:55], off
	global_load_dword v133, v[52:53], off
	v_mad_u64_u32 v[52:53], s[72:73], v57, s40, v[2:3]
	v_mad_u64_u32 v[54:55], s[72:73], v56, s40, v[2:3]
	s_add_i32 s72, s70, 16
	v_or_b32_e32 v56, s71, v1
	v_or_b32_e32 v57, s72, v0
	v_add_lshl_u32 v53, v57, v48, 10
	s_add_i32 s71, s69, 20
	v_mov_b32_e32 v148, v52
	v_mov_b32_e32 v149, v54
	v_add_lshl_u32 v4, v56, v3, 10
	v_or_b32_e32 v52, v49, v4
	v_or_b32_e32 v4, v50, v53
	v_lshl_add_u64 v[54:55], v[4:5], 2, s[4:5]
	v_mov_b32_e32 v53, v5
	v_lshl_add_u64 v[52:53], v[52:53], 2, s[4:5]
	global_load_dword v134, v[54:55], off
	global_load_dword v135, v[52:53], off
	v_mad_u64_u32 v[52:53], s[72:73], v57, s40, v[2:3]
	v_mad_u64_u32 v[54:55], s[72:73], v56, s40, v[2:3]
	s_add_i32 s72, s70, 20
	v_or_b32_e32 v56, s71, v1
	v_or_b32_e32 v57, s72, v0
	v_add_lshl_u32 v53, v57, v48, 10
	s_add_i32 s71, s69, 24
	s_add_i32 s69, s69, 28
	v_mov_b32_e32 v150, v52
	v_mov_b32_e32 v151, v54
	v_add_lshl_u32 v4, v56, v3, 10
	v_or_b32_e32 v52, v49, v4
	v_or_b32_e32 v4, v50, v53
	v_lshl_add_u64 v[54:55], v[4:5], 2, s[4:5]
	v_mov_b32_e32 v53, v5
	v_lshl_add_u64 v[52:53], v[52:53], 2, s[4:5]
	global_load_dword v136, v[54:55], off
	global_load_dword v137, v[52:53], off
	v_mad_u64_u32 v[52:53], s[72:73], v57, s40, v[2:3]
	v_mad_u64_u32 v[54:55], s[72:73], v56, s40, v[2:3]
	s_add_i32 s72, s70, 24
	v_or_b32_e32 v56, s71, v1
	v_or_b32_e32 v57, s72, v0
	v_add_lshl_u32 v53, v57, v48, 10
	s_add_i32 s70, s70, 28
	s_cmp_lg_u32 s68, 0
	v_mov_b32_e32 v152, v52
	v_mov_b32_e32 v153, v54
	v_add_lshl_u32 v4, v56, v3, 10
	v_or_b32_e32 v52, v49, v4
	v_or_b32_e32 v4, v50, v53
	v_lshl_add_u64 v[54:55], v[4:5], 2, s[4:5]
	v_mov_b32_e32 v53, v5
	v_lshl_add_u64 v[52:53], v[52:53], 2, s[4:5]
	global_load_dword v138, v[54:55], off
	global_load_dword v139, v[52:53], off
	v_mad_u64_u32 v[52:53], s[72:73], v57, s40, v[2:3]
	v_mad_u64_u32 v[54:55], s[72:73], v56, s40, v[2:3]
	v_or_b32_e32 v56, s69, v1
	v_or_b32_e32 v57, s70, v0
	v_mov_b32_e32 v55, v5
	v_mov_b32_e32 v154, v52
	v_mov_b32_e32 v155, v54
	v_add_lshl_u32 v4, v56, v3, 10
	v_add_lshl_u32 v52, v57, v48, 10
	v_or_b32_e32 v54, v49, v4
	v_or_b32_e32 v4, v50, v52
	v_lshl_add_u64 v[52:53], v[4:5], 2, s[4:5]
	v_lshl_add_u64 v[54:55], v[54:55], 2, s[4:5]
	global_load_dword v140, v[52:53], off
	global_load_dword v141, v[54:55], off
	v_mad_u64_u32 v[52:53], s[70:71], v57, s40, v[2:3]
	v_mad_u64_u32 v[54:55], s[70:71], v56, s40, v[2:3]
	v_mov_b32_e32 v156, v52
	v_mov_b32_e32 v157, v54
	s_waitcnt vmcnt(15)
	ds_write_b32 v142, v126
	s_waitcnt vmcnt(14)
	ds_write_b32 v143, v127
	s_waitcnt vmcnt(13)
	ds_write_b32 v144, v128
	s_waitcnt vmcnt(12)
	ds_write_b32 v145, v129
	s_waitcnt vmcnt(11)
	ds_write_b32 v146, v130
	s_waitcnt vmcnt(10)
	ds_write_b32 v147, v131
	s_waitcnt vmcnt(9)
	ds_write_b32 v148, v132
	s_waitcnt vmcnt(8)
	ds_write_b32 v149, v133
	s_waitcnt vmcnt(7)
	ds_write_b32 v150, v134
	s_waitcnt vmcnt(6)
	ds_write_b32 v151, v135
	s_waitcnt vmcnt(5)
	ds_write_b32 v152, v136
	s_waitcnt vmcnt(4)
	ds_write_b32 v153, v137
	s_waitcnt vmcnt(3)
	ds_write_b32 v154, v138
	s_waitcnt vmcnt(2)
	ds_write_b32 v155, v139
	s_waitcnt vmcnt(1)
	ds_write_b32 v156, v140
	s_waitcnt vmcnt(0)
	ds_write_b32 v157, v141
	s_cbranch_scc1 .LBB0_1790
	s_waitcnt lgkmcnt(0)
	ds_read2_b32 v[56:57], v97 offset0:33 offset1:41
	ds_read2_b32 v[58:59], v97 offset0:66 offset1:74
	ds_read2_b32 v[60:61], v97 offset0:99 offset1:107
	ds_read2_b32 v[62:63], v97 offset1:8
	ds_read2_b32 v[64:65], v97 offset0:132 offset1:140
	ds_read2_b32 v[66:67], v97 offset0:165 offset1:173
	ds_read2_b32 v[68:69], v97 offset0:198 offset1:206
	ds_read2_b32 v[70:71], v97 offset0:231 offset1:239
	v_lshlrev_b32_e32 v4, 1, v48
	s_waitcnt lgkmcnt(4)
	v_bfe_u32 v3, v62, 16, 1
	v_lshl_add_u64 v[48:49], v[12:13], 0, v[4:5]
	v_add3_u32 v3, v62, v3, s46
	v_bfe_u32 v4, v56, 16, 1
	v_lshrrev_b32_e32 v3, 16, v3
	v_add3_u32 v4, v56, v4, s46
	v_and_or_b32 v52, v4, s47, v3
	v_bfe_u32 v3, v58, 16, 1
	v_add3_u32 v3, v58, v3, s46
	v_bfe_u32 v4, v60, 16, 1
	v_lshrrev_b32_e32 v3, 16, v3
	v_add3_u32 v4, v60, v4, s46
	v_and_or_b32 v53, v4, s47, v3
	s_waitcnt lgkmcnt(3)
	v_bfe_u32 v3, v64, 16, 1
	v_add3_u32 v3, v64, v3, s46
	s_waitcnt lgkmcnt(2)
	v_bfe_u32 v4, v66, 16, 1
	v_lshrrev_b32_e32 v3, 16, v3
	v_add3_u32 v4, v66, v4, s46
	v_and_or_b32 v54, v4, s47, v3
	s_waitcnt lgkmcnt(1)
	v_bfe_u32 v3, v68, 16, 1
	v_add3_u32 v3, v68, v3, s46
	s_waitcnt lgkmcnt(0)
	v_bfe_u32 v4, v70, 16, 1
	v_lshrrev_b32_e32 v3, 16, v3
	v_add3_u32 v4, v70, v4, s46
	v_and_or_b32 v55, v4, s47, v3
	v_or_b32_e32 v3, v51, v96
	v_lshlrev_b32_e32 v4, 10, v3
	v_bfe_u32 v3, v63, 16, 1
	v_lshl_add_u64 v[72:73], v[48:49], 0, v[4:5]
	v_add3_u32 v3, v63, v3, s46
	v_bfe_u32 v4, v57, 16, 1
	v_lshrrev_b32_e32 v3, 16, v3
	v_add3_u32 v4, v57, v4, s46
	global_store_dwordx4 v[72:73], v[52:55], off
	v_readlane_b32 s72, v255, 50
	v_readlane_b32 s70, v255, 48
	v_and_or_b32 v52, v4, s47, v3
	v_bfe_u32 v3, v59, 16, 1
	v_add3_u32 v3, v59, v3, s46
	v_bfe_u32 v4, v61, 16, 1
	v_lshrrev_b32_e32 v3, 16, v3
	v_add3_u32 v4, v61, v4, s46
	v_and_or_b32 v53, v4, s47, v3
	v_bfe_u32 v3, v65, 16, 1
	v_add3_u32 v3, v65, v3, s46
	v_bfe_u32 v4, v67, 16, 1
	v_lshrrev_b32_e32 v3, 16, v3
	v_add3_u32 v4, v67, v4, s46
	v_and_or_b32 v54, v4, s47, v3
	v_bfe_u32 v3, v69, 16, 1
	v_add3_u32 v3, v69, v3, s46
	v_bfe_u32 v4, v71, 16, 1
	v_lshrrev_b32_e32 v3, 16, v3
	v_add3_u32 v4, v71, v4, s46
	v_and_or_b32 v55, v4, s47, v3
	v_or_b32_e32 v3, v51, v98
	v_lshlrev_b32_e32 v4, 10, v3
	v_lshl_add_u64 v[56:57], v[48:49], 0, v[4:5]
	global_store_dwordx4 v[56:57], v[52:55], off
	ds_read2_b32 v[56:57], v97 offset0:49 offset1:57
	ds_read2_b32 v[58:59], v97 offset0:82 offset1:90
	ds_read2_b32 v[60:61], v97 offset0:115 offset1:123
	ds_read2_b32 v[62:63], v97 offset0:16 offset1:24
	ds_read2_b32 v[64:65], v97 offset0:148 offset1:156
	ds_read2_b32 v[66:67], v97 offset0:181 offset1:189
	ds_read2_b32 v[68:69], v97 offset0:214 offset1:222
	ds_read2_b32 v[70:71], v97 offset0:247 offset1:255
	s_waitcnt lgkmcnt(4)
	v_bfe_u32 v3, v62, 16, 1
	v_add3_u32 v3, v62, v3, s46
	v_bfe_u32 v4, v56, 16, 1
	v_lshrrev_b32_e32 v3, 16, v3
	v_add3_u32 v4, v56, v4, s46
	v_and_or_b32 v52, v4, s47, v3
	v_bfe_u32 v3, v58, 16, 1
	v_add3_u32 v3, v58, v3, s46
	v_bfe_u32 v4, v60, 16, 1
	v_lshrrev_b32_e32 v3, 16, v3
	v_add3_u32 v4, v60, v4, s46
	v_and_or_b32 v53, v4, s47, v3
	s_waitcnt lgkmcnt(3)
	v_bfe_u32 v3, v64, 16, 1
	v_add3_u32 v3, v64, v3, s46
	s_waitcnt lgkmcnt(2)
	v_bfe_u32 v4, v66, 16, 1
	v_lshrrev_b32_e32 v3, 16, v3
	v_add3_u32 v4, v66, v4, s46
	v_and_or_b32 v54, v4, s47, v3
	s_waitcnt lgkmcnt(1)
	v_bfe_u32 v3, v68, 16, 1
	v_add3_u32 v3, v68, v3, s46
	s_waitcnt lgkmcnt(0)
	v_bfe_u32 v4, v70, 16, 1
	v_lshrrev_b32_e32 v3, 16, v3
	v_add3_u32 v4, v70, v4, s46
	v_and_or_b32 v55, v4, s47, v3
	v_or_b32_e32 v3, v51, v99
	v_lshlrev_b32_e32 v4, 10, v3
	v_bfe_u32 v3, v63, 16, 1
	v_lshl_add_u64 v[72:73], v[48:49], 0, v[4:5]
	v_add3_u32 v3, v63, v3, s46
	v_bfe_u32 v4, v57, 16, 1
	v_lshrrev_b32_e32 v3, 16, v3
	v_add3_u32 v4, v57, v4, s46
	global_store_dwordx4 v[72:73], v[52:55], off
	v_readlane_b32 s73, v255, 51
	v_readlane_b32 s71, v255, 49
	v_and_or_b32 v52, v4, s47, v3
	v_bfe_u32 v3, v59, 16, 1
	v_add3_u32 v3, v59, v3, s46
	v_bfe_u32 v4, v61, 16, 1
	v_lshrrev_b32_e32 v3, 16, v3
	v_add3_u32 v4, v61, v4, s46
	v_and_or_b32 v53, v4, s47, v3
	v_bfe_u32 v3, v65, 16, 1
	v_add3_u32 v3, v65, v3, s46
	v_bfe_u32 v4, v67, 16, 1
	v_lshrrev_b32_e32 v3, 16, v3
	v_add3_u32 v4, v67, v4, s46
	v_and_or_b32 v54, v4, s47, v3
	v_bfe_u32 v3, v69, 16, 1
	v_add3_u32 v3, v69, v3, s46
	v_bfe_u32 v4, v71, 16, 1
	v_lshrrev_b32_e32 v3, 16, v3
	v_add3_u32 v4, v71, v4, s46
	v_and_or_b32 v55, v4, s47, v3
	v_or_b32_e32 v3, v51, v100
	v_lshlrev_b32_e32 v4, 10, v3
	v_lshl_add_u64 v[48:49], v[48:49], 0, v[4:5]
	global_store_dwordx4 v[48:49], v[52:55], off
	s_waitcnt lgkmcnt(0)

.LBB0_1795:
	s_lshl_b32 s68, s11, 1
	s_lshl_b32 s65, s10, 1
	v_or_b32_e32 v50, s68, v4
	v_or_b32_e32 v52, s65, v3
	v_mad_u64_u32 v[50:51], s[70:71], v50, s67, v[48:49]
	v_mad_u64_u32 v[52:53], s[70:71], v52, s67, v[48:49]
	global_load_dword v126, v[50:51], off
	global_load_dword v127, v[52:53], off
	v_or_b32_e32 v54, s65, v1
	v_or_b32_e32 v55, s68, v0
	v_mad_u64_u32 v[50:51], s[70:71], v55, s40, v[2:3]
	v_mad_u64_u32 v[52:53], s[70:71], v54, s40, v[2:3]
	s_add_i32 s70, s68, 4
	s_add_i32 s69, s65, 4
	v_or_b32_e32 v55, s70, v0
	v_or_b32_e32 v54, s69, v1
	s_add_i32 s11, s11, 16
	s_add_i32 s10, s10, 16
	s_add_i32 s64, s64, -16
	v_mov_b32_e32 v142, v50
	v_mov_b32_e32 v143, v52
	v_or_b32_e32 v50, s70, v4
	v_or_b32_e32 v52, s69, v3
	v_mad_u64_u32 v[50:51], s[70:71], v50, s67, v[48:49]
	v_mad_u64_u32 v[52:53], s[70:71], v52, s67, v[48:49]
	global_load_dword v128, v[50:51], off
	global_load_dword v129, v[52:53], off
	v_mad_u64_u32 v[50:51], s[70:71], v55, s40, v[2:3]
	v_mad_u64_u32 v[52:53], s[70:71], v54, s40, v[2:3]
	s_add_i32 s70, s68, 8
	s_add_i32 s69, s65, 8
	v_or_b32_e32 v55, s70, v0
	v_or_b32_e32 v54, s69, v1
	v_mov_b32_e32 v144, v50
	v_mov_b32_e32 v145, v52
	v_or_b32_e32 v50, s70, v4
	v_or_b32_e32 v52, s69, v3
	v_mad_u64_u32 v[50:51], s[70:71], v50, s67, v[48:49]
	v_mad_u64_u32 v[52:53], s[70:71], v52, s67, v[48:49]
	global_load_dword v130, v[50:51], off
	global_load_dword v131, v[52:53], off
	v_mad_u64_u32 v[50:51], s[70:71], v55, s40, v[2:3]
	v_mad_u64_u32 v[52:53], s[70:71], v54, s40, v[2:3]
	s_add_i32 s70, s68, 12
	s_add_i32 s69, s65, 12
	v_or_b32_e32 v55, s70, v0
	v_or_b32_e32 v54, s69, v1
	v_mov_b32_e32 v146, v50
	v_mov_b32_e32 v147, v52
	v_or_b32_e32 v50, s70, v4
	v_or_b32_e32 v52, s69, v3
	v_mad_u64_u32 v[50:51], s[70:71], v50, s67, v[48:49]
	v_mad_u64_u32 v[52:53], s[70:71], v52, s67, v[48:49]
	global_load_dword v132, v[50:51], off
	global_load_dword v133, v[52:53], off
	v_mad_u64_u32 v[50:51], s[70:71], v55, s40, v[2:3]
	v_mad_u64_u32 v[52:53], s[70:71], v54, s40, v[2:3]
	s_add_i32 s70, s68, 16
	s_add_i32 s69, s65, 16
	v_or_b32_e32 v55, s70, v0
	v_or_b32_e32 v54, s69, v1
	v_mov_b32_e32 v148, v50
	v_mov_b32_e32 v149, v52
	v_or_b32_e32 v50, s70, v4
	v_or_b32_e32 v52, s69, v3
	v_mad_u64_u32 v[50:51], s[70:71], v50, s67, v[48:49]
	v_mad_u64_u32 v[52:53], s[70:71], v52, s67, v[48:49]
	global_load_dword v134, v[50:51], off
	global_load_dword v135, v[52:53], off
	v_mad_u64_u32 v[50:51], s[70:71], v55, s40, v[2:3]
	v_mad_u64_u32 v[52:53], s[70:71], v54, s40, v[2:3]
	s_add_i32 s70, s68, 20
	s_add_i32 s69, s65, 20
	v_or_b32_e32 v55, s70, v0
	v_or_b32_e32 v54, s69, v1
	v_mov_b32_e32 v150, v50
	v_mov_b32_e32 v151, v52
	v_or_b32_e32 v50, s70, v4
	v_or_b32_e32 v52, s69, v3
	v_mad_u64_u32 v[50:51], s[70:71], v50, s67, v[48:49]
	v_mad_u64_u32 v[52:53], s[70:71], v52, s67, v[48:49]
	global_load_dword v136, v[50:51], off
	global_load_dword v137, v[52:53], off
	v_mad_u64_u32 v[50:51], s[70:71], v55, s40, v[2:3]
	v_mad_u64_u32 v[52:53], s[70:71], v54, s40, v[2:3]
	s_add_i32 s70, s68, 24
	s_add_i32 s69, s65, 24
	v_or_b32_e32 v55, s70, v0
	v_or_b32_e32 v54, s69, v1
	s_add_i32 s68, s68, 28
	s_add_i32 s65, s65, 28
	s_cmp_lg_u32 s64, 0
	v_mov_b32_e32 v152, v50
	v_mov_b32_e32 v153, v52
	v_or_b32_e32 v50, s70, v4
	v_or_b32_e32 v52, s69, v3
	v_mad_u64_u32 v[50:51], s[70:71], v50, s67, v[48:49]
	v_mad_u64_u32 v[52:53], s[70:71], v52, s67, v[48:49]
	global_load_dword v138, v[50:51], off
	global_load_dword v139, v[52:53], off
	v_mad_u64_u32 v[50:51], s[70:71], v55, s40, v[2:3]
	v_mad_u64_u32 v[52:53], s[70:71], v54, s40, v[2:3]
	v_or_b32_e32 v55, s68, v0
	v_or_b32_e32 v54, s65, v1
	v_mov_b32_e32 v154, v50
	v_mov_b32_e32 v155, v52
	v_or_b32_e32 v50, s68, v4
	v_or_b32_e32 v52, s65, v3
	v_mad_u64_u32 v[50:51], s[68:69], v50, s67, v[48:49]
	v_mad_u64_u32 v[52:53], s[68:69], v52, s67, v[48:49]
	global_load_dword v140, v[50:51], off
	global_load_dword v141, v[52:53], off
	v_mad_u64_u32 v[50:51], s[68:69], v55, s40, v[2:3]
	v_mad_u64_u32 v[52:53], s[68:69], v54, s40, v[2:3]
	v_mov_b32_e32 v156, v50
	v_mov_b32_e32 v157, v52
	s_waitcnt vmcnt(15)
	ds_write_b32 v142, v126
	s_waitcnt vmcnt(14)
	ds_write_b32 v143, v127
	s_waitcnt vmcnt(13)
	ds_write_b32 v144, v128
	s_waitcnt vmcnt(12)
	ds_write_b32 v145, v129
	s_waitcnt vmcnt(11)
	ds_write_b32 v146, v130
	s_waitcnt vmcnt(10)
	ds_write_b32 v147, v131
	s_waitcnt vmcnt(9)
	ds_write_b32 v148, v132
	s_waitcnt vmcnt(8)
	ds_write_b32 v149, v133
	s_waitcnt vmcnt(7)
	ds_write_b32 v150, v134
	s_waitcnt vmcnt(6)
	ds_write_b32 v151, v135
	s_waitcnt vmcnt(5)
	ds_write_b32 v152, v136
	s_waitcnt vmcnt(4)
	ds_write_b32 v153, v137
	s_waitcnt vmcnt(3)
	ds_write_b32 v154, v138
	s_waitcnt vmcnt(2)
	ds_write_b32 v155, v139
	s_waitcnt vmcnt(1)
	ds_write_b32 v156, v140
	s_waitcnt vmcnt(0)
	ds_write_b32 v157, v141
	s_cbranch_scc1 .LBB0_1795
	v_or_b32_e32 v4, v101, v60
	v_cndmask_b32_e64 v3, 0, 1, s[96:97]
	v_mov_b32_e32 v71, 1.0
	v_cmp_ne_u32_e64 s[10:11], 1, v3
	s_andn2_b64 vcc, exec, s[96:97]
	v_lshlrev_b32_e32 v3, 2, v4
	v_mov_b32_e32 v70, 1.0
	s_cbranch_vccnz .LBB0_1798
	global_load_dword v70, v3, s[72:73]

.LBB0_1816:
	s_lshl_b32 s64, s11, 1
	s_lshl_b32 s37, s10, 1
	v_or_b32_e32 v50, s64, v4
	v_or_b32_e32 v52, s37, v3
	v_mad_u64_u32 v[50:51], s[68:69], v50, s67, v[48:49]
	v_mad_u64_u32 v[52:53], s[68:69], v52, s67, v[48:49]
	global_load_dword v126, v[50:51], off
	global_load_dword v127, v[52:53], off
	v_or_b32_e32 v54, s37, v1
	v_or_b32_e32 v55, s64, v0
	v_mad_u64_u32 v[50:51], s[68:69], v55, s40, v[2:3]
	v_mad_u64_u32 v[52:53], s[68:69], v54, s40, v[2:3]
	s_add_i32 s68, s64, 4
	s_add_i32 s65, s37, 4
	v_or_b32_e32 v55, s68, v0
	v_or_b32_e32 v54, s65, v1
	s_add_i32 s11, s11, 16
	s_add_i32 s10, s10, 16
	s_add_i32 s36, s36, -16
	v_mov_b32_e32 v142, v50
	v_mov_b32_e32 v143, v52
	v_or_b32_e32 v50, s68, v4
	v_or_b32_e32 v52, s65, v3
	v_mad_u64_u32 v[50:51], s[68:69], v50, s67, v[48:49]
	v_mad_u64_u32 v[52:53], s[68:69], v52, s67, v[48:49]
	global_load_dword v128, v[50:51], off
	global_load_dword v129, v[52:53], off
	v_mad_u64_u32 v[50:51], s[68:69], v55, s40, v[2:3]
	v_mad_u64_u32 v[52:53], s[68:69], v54, s40, v[2:3]
	s_add_i32 s68, s64, 8
	s_add_i32 s65, s37, 8
	v_or_b32_e32 v55, s68, v0
	v_or_b32_e32 v54, s65, v1
	v_mov_b32_e32 v144, v50
	v_mov_b32_e32 v145, v52
	v_or_b32_e32 v50, s68, v4
	v_or_b32_e32 v52, s65, v3
	v_mad_u64_u32 v[50:51], s[68:69], v50, s67, v[48:49]
	v_mad_u64_u32 v[52:53], s[68:69], v52, s67, v[48:49]
	global_load_dword v130, v[50:51], off
	global_load_dword v131, v[52:53], off
	v_mad_u64_u32 v[50:51], s[68:69], v55, s40, v[2:3]
	v_mad_u64_u32 v[52:53], s[68:69], v54, s40, v[2:3]
	s_add_i32 s68, s64, 12
	s_add_i32 s65, s37, 12
	v_or_b32_e32 v55, s68, v0
	v_or_b32_e32 v54, s65, v1
	v_mov_b32_e32 v146, v50
	v_mov_b32_e32 v147, v52
	v_or_b32_e32 v50, s68, v4
	v_or_b32_e32 v52, s65, v3
	v_mad_u64_u32 v[50:51], s[68:69], v50, s67, v[48:49]
	v_mad_u64_u32 v[52:53], s[68:69], v52, s67, v[48:49]
	global_load_dword v132, v[50:51], off
	global_load_dword v133, v[52:53], off
	v_mad_u64_u32 v[50:51], s[68:69], v55, s40, v[2:3]
	v_mad_u64_u32 v[52:53], s[68:69], v54, s40, v[2:3]
	s_add_i32 s68, s64, 16
	s_add_i32 s65, s37, 16
	v_or_b32_e32 v55, s68, v0
	v_or_b32_e32 v54, s65, v1
	v_mov_b32_e32 v148, v50
	v_mov_b32_e32 v149, v52
	v_or_b32_e32 v50, s68, v4
	v_or_b32_e32 v52, s65, v3
	v_mad_u64_u32 v[50:51], s[68:69], v50, s67, v[48:49]
	v_mad_u64_u32 v[52:53], s[68:69], v52, s67, v[48:49]
	global_load_dword v134, v[50:51], off
	global_load_dword v135, v[52:53], off
	v_mad_u64_u32 v[50:51], s[68:69], v55, s40, v[2:3]
	v_mad_u64_u32 v[52:53], s[68:69], v54, s40, v[2:3]
	s_add_i32 s68, s64, 20
	s_add_i32 s65, s37, 20
	v_or_b32_e32 v55, s68, v0
	v_or_b32_e32 v54, s65, v1
	v_mov_b32_e32 v150, v50
	v_mov_b32_e32 v151, v52
	v_or_b32_e32 v50, s68, v4
	v_or_b32_e32 v52, s65, v3
	v_mad_u64_u32 v[50:51], s[68:69], v50, s67, v[48:49]
	v_mad_u64_u32 v[52:53], s[68:69], v52, s67, v[48:49]
	global_load_dword v136, v[50:51], off
	global_load_dword v137, v[52:53], off
	v_mad_u64_u32 v[50:51], s[68:69], v55, s40, v[2:3]
	v_mad_u64_u32 v[52:53], s[68:69], v54, s40, v[2:3]
	s_add_i32 s68, s64, 24
	s_add_i32 s65, s37, 24
	v_or_b32_e32 v55, s68, v0
	v_or_b32_e32 v54, s65, v1
	s_add_i32 s64, s64, 28
	s_add_i32 s37, s37, 28
	s_cmp_lg_u32 s36, 0
	v_mov_b32_e32 v152, v50
	v_mov_b32_e32 v153, v52
	v_or_b32_e32 v50, s68, v4
	v_or_b32_e32 v52, s65, v3
	v_mad_u64_u32 v[50:51], s[68:69], v50, s67, v[48:49]
	v_mad_u64_u32 v[52:53], s[68:69], v52, s67, v[48:49]
	global_load_dword v138, v[50:51], off
	global_load_dword v139, v[52:53], off
	v_mad_u64_u32 v[50:51], s[68:69], v55, s40, v[2:3]
	v_mad_u64_u32 v[52:53], s[68:69], v54, s40, v[2:3]
	v_or_b32_e32 v55, s64, v0
	v_or_b32_e32 v54, s37, v1
	v_mov_b32_e32 v154, v50
	v_mov_b32_e32 v155, v52
	v_or_b32_e32 v50, s64, v4
	v_or_b32_e32 v52, s37, v3
	v_mad_u64_u32 v[50:51], s[64:65], v50, s67, v[48:49]
	v_mad_u64_u32 v[52:53], s[64:65], v52, s67, v[48:49]
	global_load_dword v140, v[50:51], off
	global_load_dword v141, v[52:53], off
	v_mad_u64_u32 v[50:51], s[64:65], v55, s40, v[2:3]
	v_mad_u64_u32 v[52:53], s[64:65], v54, s40, v[2:3]
	v_mov_b32_e32 v156, v50
	v_mov_b32_e32 v157, v52
	s_waitcnt vmcnt(15)
	ds_write_b32 v142, v126
	s_waitcnt vmcnt(14)
	ds_write_b32 v143, v127
	s_waitcnt vmcnt(13)
	ds_write_b32 v144, v128
	s_waitcnt vmcnt(12)
	ds_write_b32 v145, v129
	s_waitcnt vmcnt(11)
	ds_write_b32 v146, v130
	s_waitcnt vmcnt(10)
	ds_write_b32 v147, v131
	s_waitcnt vmcnt(9)
	ds_write_b32 v148, v132
	s_waitcnt vmcnt(8)
	ds_write_b32 v149, v133
	s_waitcnt vmcnt(7)
	ds_write_b32 v150, v134
	s_waitcnt vmcnt(6)
	ds_write_b32 v151, v135
	s_waitcnt vmcnt(5)
	ds_write_b32 v152, v136
	s_waitcnt vmcnt(4)
	ds_write_b32 v153, v137
	s_waitcnt vmcnt(3)
	ds_write_b32 v154, v138
	s_waitcnt vmcnt(2)
	ds_write_b32 v155, v139
	s_waitcnt vmcnt(1)
	ds_write_b32 v156, v140
	s_waitcnt vmcnt(0)
	ds_write_b32 v157, v141
	s_cbranch_scc1 .LBB0_1816
	v_or_b32_e32 v4, v101, v60
	v_cndmask_b32_e64 v3, 0, 1, s[96:97]
	v_mov_b32_e32 v69, 1.0
	v_cmp_ne_u32_e64 s[10:11], 1, v3
	s_andn2_b64 vcc, exec, s[96:97]
	v_lshlrev_b32_e32 v3, 2, v4
	v_mov_b32_e32 v68, 1.0
	s_cbranch_vccnz .LBB0_1819
	global_load_dword v68, v3, s[72:73]

.LBB0_1837:
	s_lshl_b32 s36, s11, 1
	s_lshl_b32 s35, s10, 1
	v_or_b32_e32 v54, s36, v4
	v_or_b32_e32 v56, s35, v3
	v_mad_i64_i32 v[54:55], s[64:65], v54, s41, v[52:53]
	v_mad_i64_i32 v[56:57], s[64:65], v56, s41, v[52:53]
	global_load_dword v126, v[54:55], off
	global_load_dword v127, v[56:57], off
	v_or_b32_e32 v49, s35, v1
	v_or_b32_e32 v51, s36, v0
	v_mad_u64_u32 v[54:55], s[64:65], v51, s40, v[2:3]
	v_mad_u64_u32 v[56:57], s[64:65], v49, s40, v[2:3]
	s_add_i32 s64, s36, 4
	s_add_i32 s37, s35, 4
	v_or_b32_e32 v51, s64, v0
	v_or_b32_e32 v49, s37, v1
	s_add_i32 s11, s11, 16
	s_add_i32 s10, s10, 16
	s_add_i32 s34, s34, -16
	v_mov_b32_e32 v142, v54
	v_mov_b32_e32 v143, v56
	v_or_b32_e32 v54, s64, v4
	v_or_b32_e32 v56, s37, v3
	v_mad_i64_i32 v[54:55], s[64:65], v54, s41, v[52:53]
	v_mad_i64_i32 v[56:57], s[64:65], v56, s41, v[52:53]
	global_load_dword v128, v[54:55], off
	global_load_dword v129, v[56:57], off
	v_mad_u64_u32 v[54:55], s[64:65], v51, s40, v[2:3]
	v_mad_u64_u32 v[56:57], s[64:65], v49, s40, v[2:3]
	s_add_i32 s64, s36, 8
	s_add_i32 s37, s35, 8
	v_or_b32_e32 v51, s64, v0
	v_or_b32_e32 v49, s37, v1
	v_mov_b32_e32 v144, v54
	v_mov_b32_e32 v145, v56
	v_or_b32_e32 v54, s64, v4
	v_or_b32_e32 v56, s37, v3
	v_mad_i64_i32 v[54:55], s[64:65], v54, s41, v[52:53]
	v_mad_i64_i32 v[56:57], s[64:65], v56, s41, v[52:53]
	global_load_dword v130, v[54:55], off
	global_load_dword v131, v[56:57], off
	v_mad_u64_u32 v[54:55], s[64:65], v51, s40, v[2:3]
	v_mad_u64_u32 v[56:57], s[64:65], v49, s40, v[2:3]
	s_add_i32 s64, s36, 12
	s_add_i32 s37, s35, 12
	v_or_b32_e32 v51, s64, v0
	v_or_b32_e32 v49, s37, v1
	v_mov_b32_e32 v146, v54
	v_mov_b32_e32 v147, v56
	v_or_b32_e32 v54, s64, v4
	v_or_b32_e32 v56, s37, v3
	v_mad_i64_i32 v[54:55], s[64:65], v54, s41, v[52:53]
	v_mad_i64_i32 v[56:57], s[64:65], v56, s41, v[52:53]
	global_load_dword v132, v[54:55], off
	global_load_dword v133, v[56:57], off
	v_mad_u64_u32 v[54:55], s[64:65], v51, s40, v[2:3]
	v_mad_u64_u32 v[56:57], s[64:65], v49, s40, v[2:3]
	s_add_i32 s64, s36, 16
	s_add_i32 s37, s35, 16
	v_or_b32_e32 v51, s64, v0
	v_or_b32_e32 v49, s37, v1
	v_mov_b32_e32 v148, v54
	v_mov_b32_e32 v149, v56
	v_or_b32_e32 v54, s64, v4
	v_or_b32_e32 v56, s37, v3
	v_mad_i64_i32 v[54:55], s[64:65], v54, s41, v[52:53]
	v_mad_i64_i32 v[56:57], s[64:65], v56, s41, v[52:53]
	global_load_dword v134, v[54:55], off
	global_load_dword v135, v[56:57], off
	v_mad_u64_u32 v[54:55], s[64:65], v51, s40, v[2:3]
	v_mad_u64_u32 v[56:57], s[64:65], v49, s40, v[2:3]
	s_add_i32 s64, s36, 20
	s_add_i32 s37, s35, 20
	v_or_b32_e32 v51, s64, v0
	v_or_b32_e32 v49, s37, v1
	v_mov_b32_e32 v150, v54
	v_mov_b32_e32 v151, v56
	v_or_b32_e32 v54, s64, v4
	v_or_b32_e32 v56, s37, v3
	v_mad_i64_i32 v[54:55], s[64:65], v54, s41, v[52:53]
	v_mad_i64_i32 v[56:57], s[64:65], v56, s41, v[52:53]
	global_load_dword v136, v[54:55], off
	global_load_dword v137, v[56:57], off
	v_mad_u64_u32 v[54:55], s[64:65], v51, s40, v[2:3]
	v_mad_u64_u32 v[56:57], s[64:65], v49, s40, v[2:3]
	s_add_i32 s64, s36, 24
	s_add_i32 s37, s35, 24
	v_or_b32_e32 v51, s64, v0
	v_or_b32_e32 v49, s37, v1
	s_add_i32 s36, s36, 28
	s_add_i32 s35, s35, 28
	s_cmp_lg_u32 s34, 0
	v_mov_b32_e32 v152, v54
	v_mov_b32_e32 v153, v56
	v_or_b32_e32 v54, s64, v4
	v_or_b32_e32 v56, s37, v3
	v_mad_i64_i32 v[54:55], s[64:65], v54, s41, v[52:53]
	v_mad_i64_i32 v[56:57], s[64:65], v56, s41, v[52:53]
	global_load_dword v138, v[54:55], off
	global_load_dword v139, v[56:57], off
	v_mad_u64_u32 v[54:55], s[64:65], v51, s40, v[2:3]
	v_mad_u64_u32 v[56:57], s[64:65], v49, s40, v[2:3]
	v_or_b32_e32 v51, s36, v0
	v_or_b32_e32 v49, s35, v1
	v_mov_b32_e32 v154, v54
	v_mov_b32_e32 v155, v56
	v_or_b32_e32 v54, s36, v4
	v_or_b32_e32 v56, s35, v3
	v_mad_i64_i32 v[54:55], s[36:37], v54, s41, v[52:53]
	v_mad_i64_i32 v[56:57], s[36:37], v56, s41, v[52:53]
	global_load_dword v140, v[54:55], off
	global_load_dword v141, v[56:57], off
	v_mad_u64_u32 v[54:55], s[36:37], v51, s40, v[2:3]
	v_mad_u64_u32 v[56:57], s[36:37], v49, s40, v[2:3]
	v_mov_b32_e32 v156, v54
	v_mov_b32_e32 v157, v56
	s_waitcnt vmcnt(15)
	ds_write_b32 v142, v126
	s_waitcnt vmcnt(14)
	ds_write_b32 v143, v127
	s_waitcnt vmcnt(13)
	ds_write_b32 v144, v128
	s_waitcnt vmcnt(12)
	ds_write_b32 v145, v129
	s_waitcnt vmcnt(11)
	ds_write_b32 v146, v130
	s_waitcnt vmcnt(10)
	ds_write_b32 v147, v131
	s_waitcnt vmcnt(9)
	ds_write_b32 v148, v132
	s_waitcnt vmcnt(8)
	ds_write_b32 v149, v133
	s_waitcnt vmcnt(7)
	ds_write_b32 v150, v134
	s_waitcnt vmcnt(6)
	ds_write_b32 v151, v135
	s_waitcnt vmcnt(5)
	ds_write_b32 v152, v136
	s_waitcnt vmcnt(4)
	ds_write_b32 v153, v137
	s_waitcnt vmcnt(3)
	ds_write_b32 v154, v138
	s_waitcnt vmcnt(2)
	ds_write_b32 v155, v139
	s_waitcnt vmcnt(1)
	ds_write_b32 v156, v140
	s_waitcnt vmcnt(0)
	ds_write_b32 v157, v141
	s_cbranch_scc1 .LBB0_1837
	v_or_b32_e32 v52, v50, v101
	v_cndmask_b32_e64 v3, 0, 1, s[8:9]
	v_mov_b32_e32 v71, 1.0
	v_cmp_ne_u32_e64 s[10:11], 1, v3
	s_andn2_b64 vcc, exec, s[8:9]
	v_ashrrev_i32_e32 v53, 31, v52
	v_mov_b32_e32 v70, 1.0
	s_cbranch_vccnz .LBB0_1840
	v_lshl_add_u64 v[54:55], v[52:53], 2, s[70:71]
	global_load_dword v70, v[54:55], off

.LBB0_2640:
	s_lshl_b32 s61, s54, 1
	s_lshl_b32 s64, s55, 1
	v_or_b32_e32 v56, s61, v1
	v_or_b32_e32 v57, s64, v0
	v_add_lshl_u32 v4, v56, v3, 10
	v_add_lshl_u32 v53, v57, v48, 10
	v_or_b32_e32 v52, v49, v4
	v_or_b32_e32 v4, v50, v53
	v_lshl_add_u64 v[54:55], v[4:5], 2, s[26:27]
	v_mov_b32_e32 v53, v5
	v_lshl_add_u64 v[52:53], v[52:53], 2, s[26:27]
	global_load_dword v126, v[54:55], off
	global_load_dword v127, v[52:53], off
	v_mad_u64_u32 v[52:53], s[66:67], v57, s40, v[2:3]
	v_mad_u64_u32 v[54:55], s[66:67], v56, s40, v[2:3]
	s_add_i32 s65, s61, 4
	s_add_i32 s66, s64, 4
	v_or_b32_e32 v56, s65, v1
	v_or_b32_e32 v57, s66, v0
	v_add_lshl_u32 v53, v57, v48, 10
	s_add_i32 s65, s61, 8
	s_add_i32 s55, s55, 16
	s_add_i32 s54, s54, 16
	s_add_i32 s60, s60, -16
	v_mov_b32_e32 v142, v52
	v_mov_b32_e32 v143, v54
	v_add_lshl_u32 v4, v56, v3, 10
	v_or_b32_e32 v52, v49, v4
	v_or_b32_e32 v4, v50, v53
	v_lshl_add_u64 v[54:55], v[4:5], 2, s[26:27]
	v_mov_b32_e32 v53, v5
	v_lshl_add_u64 v[52:53], v[52:53], 2, s[26:27]
	global_load_dword v128, v[54:55], off
	global_load_dword v129, v[52:53], off
	v_mad_u64_u32 v[52:53], s[66:67], v57, s40, v[2:3]
	v_mad_u64_u32 v[54:55], s[66:67], v56, s40, v[2:3]
	s_add_i32 s66, s64, 8
	v_or_b32_e32 v56, s65, v1
	v_or_b32_e32 v57, s66, v0
	v_add_lshl_u32 v53, v57, v48, 10
	s_add_i32 s65, s61, 12
	v_mov_b32_e32 v144, v52
	v_mov_b32_e32 v145, v54
	v_add_lshl_u32 v4, v56, v3, 10
	v_or_b32_e32 v52, v49, v4
	v_or_b32_e32 v4, v50, v53
	v_lshl_add_u64 v[54:55], v[4:5], 2, s[26:27]
	v_mov_b32_e32 v53, v5
	v_lshl_add_u64 v[52:53], v[52:53], 2, s[26:27]
	global_load_dword v130, v[54:55], off
	global_load_dword v131, v[52:53], off
	v_mad_u64_u32 v[52:53], s[66:67], v57, s40, v[2:3]
	v_mad_u64_u32 v[54:55], s[66:67], v56, s40, v[2:3]
	s_add_i32 s66, s64, 12
	v_or_b32_e32 v56, s65, v1
	v_or_b32_e32 v57, s66, v0
	v_add_lshl_u32 v53, v57, v48, 10
	s_add_i32 s65, s61, 16
	v_mov_b32_e32 v146, v52
	v_mov_b32_e32 v147, v54
	v_add_lshl_u32 v4, v56, v3, 10
	v_or_b32_e32 v52, v49, v4
	v_or_b32_e32 v4, v50, v53
	v_lshl_add_u64 v[54:55], v[4:5], 2, s[26:27]
	v_mov_b32_e32 v53, v5
	v_lshl_add_u64 v[52:53], v[52:53], 2, s[26:27]
	global_load_dword v132, v[54:55], off
	global_load_dword v133, v[52:53], off
	v_mad_u64_u32 v[52:53], s[66:67], v57, s40, v[2:3]
	v_mad_u64_u32 v[54:55], s[66:67], v56, s40, v[2:3]
	s_add_i32 s66, s64, 16
	v_or_b32_e32 v56, s65, v1
	v_or_b32_e32 v57, s66, v0
	v_add_lshl_u32 v53, v57, v48, 10
	s_add_i32 s65, s61, 20
	v_mov_b32_e32 v148, v52
	v_mov_b32_e32 v149, v54
	v_add_lshl_u32 v4, v56, v3, 10
	v_or_b32_e32 v52, v49, v4
	v_or_b32_e32 v4, v50, v53
	v_lshl_add_u64 v[54:55], v[4:5], 2, s[26:27]
	v_mov_b32_e32 v53, v5
	v_lshl_add_u64 v[52:53], v[52:53], 2, s[26:27]
	global_load_dword v134, v[54:55], off
	global_load_dword v135, v[52:53], off
	v_mad_u64_u32 v[52:53], s[66:67], v57, s40, v[2:3]
	v_mad_u64_u32 v[54:55], s[66:67], v56, s40, v[2:3]
	s_add_i32 s66, s64, 20
	v_or_b32_e32 v56, s65, v1
	v_or_b32_e32 v57, s66, v0
	v_add_lshl_u32 v53, v57, v48, 10
	s_add_i32 s65, s61, 24
	s_add_i32 s61, s61, 28
	v_mov_b32_e32 v150, v52
	v_mov_b32_e32 v151, v54
	v_add_lshl_u32 v4, v56, v3, 10
	v_or_b32_e32 v52, v49, v4
	v_or_b32_e32 v4, v50, v53
	v_lshl_add_u64 v[54:55], v[4:5], 2, s[26:27]
	v_mov_b32_e32 v53, v5
	v_lshl_add_u64 v[52:53], v[52:53], 2, s[26:27]
	global_load_dword v136, v[54:55], off
	global_load_dword v137, v[52:53], off
	v_mad_u64_u32 v[52:53], s[66:67], v57, s40, v[2:3]
	v_mad_u64_u32 v[54:55], s[66:67], v56, s40, v[2:3]
	s_add_i32 s66, s64, 24
	v_or_b32_e32 v56, s65, v1
	v_or_b32_e32 v57, s66, v0
	v_add_lshl_u32 v53, v57, v48, 10
	s_add_i32 s64, s64, 28
	s_cmp_lg_u32 s60, 0
	v_mov_b32_e32 v152, v52
	v_mov_b32_e32 v153, v54
	v_add_lshl_u32 v4, v56, v3, 10
	v_or_b32_e32 v52, v49, v4
	v_or_b32_e32 v4, v50, v53
	v_lshl_add_u64 v[54:55], v[4:5], 2, s[26:27]
	v_mov_b32_e32 v53, v5
	v_lshl_add_u64 v[52:53], v[52:53], 2, s[26:27]
	global_load_dword v138, v[54:55], off
	global_load_dword v139, v[52:53], off
	v_mad_u64_u32 v[52:53], s[66:67], v57, s40, v[2:3]
	v_mad_u64_u32 v[54:55], s[66:67], v56, s40, v[2:3]
	v_or_b32_e32 v56, s61, v1
	v_or_b32_e32 v57, s64, v0
	v_mov_b32_e32 v55, v5
	v_mov_b32_e32 v154, v52
	v_mov_b32_e32 v155, v54
	v_add_lshl_u32 v4, v56, v3, 10
	v_add_lshl_u32 v52, v57, v48, 10
	v_or_b32_e32 v54, v49, v4
	v_or_b32_e32 v4, v50, v52
	v_lshl_add_u64 v[52:53], v[4:5], 2, s[26:27]
	v_lshl_add_u64 v[54:55], v[54:55], 2, s[26:27]
	global_load_dword v140, v[52:53], off
	global_load_dword v141, v[54:55], off
	v_mad_u64_u32 v[52:53], s[64:65], v57, s40, v[2:3]
	v_mad_u64_u32 v[54:55], s[64:65], v56, s40, v[2:3]
	v_mov_b32_e32 v156, v52
	v_mov_b32_e32 v157, v54
	s_waitcnt vmcnt(15)
	ds_write_b32 v142, v126
	s_waitcnt vmcnt(14)
	ds_write_b32 v143, v127
	s_waitcnt vmcnt(13)
	ds_write_b32 v144, v128
	s_waitcnt vmcnt(12)
	ds_write_b32 v145, v129
	s_waitcnt vmcnt(11)
	ds_write_b32 v146, v130
	s_waitcnt vmcnt(10)
	ds_write_b32 v147, v131
	s_waitcnt vmcnt(9)
	ds_write_b32 v148, v132
	s_waitcnt vmcnt(8)
	ds_write_b32 v149, v133
	s_waitcnt vmcnt(7)
	ds_write_b32 v150, v134
	s_waitcnt vmcnt(6)
	ds_write_b32 v151, v135
	s_waitcnt vmcnt(5)
	ds_write_b32 v152, v136
	s_waitcnt vmcnt(4)
	ds_write_b32 v153, v137
	s_waitcnt vmcnt(3)
	ds_write_b32 v154, v138
	s_waitcnt vmcnt(2)
	ds_write_b32 v155, v139
	s_waitcnt vmcnt(1)
	ds_write_b32 v156, v140
	s_waitcnt vmcnt(0)
	ds_write_b32 v157, v141
	s_cbranch_scc1 .LBB0_2640
	v_or_b32_e32 v3, v51, v96
	v_lshlrev_b32_e32 v4, 2, v3
	v_or_b32_e32 v49, 0x5000, v4
	global_load_dword v90, v49, s[92:93]
	global_load_dword v80, v49, s[94:95]
	v_or_b32_e32 v49, 0x5020, v4
	global_load_dword v62, v49, s[92:93]
	global_load_dword v60, v49, s[94:95]
	v_or_b32_e32 v49, 0x5040, v4
	global_load_dword v58, v49, s[92:93]
	global_load_dword v56, v49, s[94:95]
	v_or_b32_e32 v4, 0x5060, v4
	global_load_dword v52, v4, s[92:93]
	global_load_dword v50, v4, s[94:95]
	s_waitcnt lgkmcnt(0)
	ds_read2_b32 v[74:75], v97 offset0:33 offset1:41
	ds_read2_b32 v[66:67], v97 offset0:66 offset1:74
	ds_read2_b32 v[64:65], v97 offset0:99 offset1:107
	ds_read2_b32 v[76:77], v97 offset0:132 offset1:140
	ds_read2_b32 v[72:73], v97 offset0:165 offset1:173
	ds_read2_b32 v[70:71], v97 offset0:198 offset1:206
	ds_read2_b32 v[68:69], v97 offset0:231 offset1:239
	ds_read2_b32 v[78:79], v97 offset1:8
	s_waitcnt lgkmcnt(4)
	v_mov_b32_e32 v86, v76
	v_mov_b32_e32 v83, v66
	s_waitcnt lgkmcnt(2)
	v_mov_b32_e32 v87, v70
	v_mov_b32_e32 v84, v74
	s_waitcnt lgkmcnt(0)
	v_mov_b32_e32 v82, v78
	v_mov_b32_e32 v85, v64
	v_mov_b32_e32 v88, v72
	v_mov_b32_e32 v89, v68
	v_lshlrev_b32_e32 v4, 1, v48
	v_lshl_add_u64 v[54:55], v[6:7], 0, v[4:5]
	v_lshl_add_u64 v[48:49], v[22:23], 0, v[4:5]
	v_mul_u32_u24_e32 v3, 0xb00, v3
	v_mov_b32_e32 v70, v77
	v_mov_b32_e32 v68, v73
	s_waitcnt vmcnt(7)
	v_pk_mul_f32 v[112:113], v[90:91], v[86:87] op_sel_hi:[0,1]
	v_pk_mul_f32 v[92:93], v[90:91], v[82:83] op_sel_hi:[0,1]
	v_pk_mul_f32 v[110:111], v[90:91], v[84:85] op_sel_hi:[0,1]
	v_pk_mul_f32 v[90:91], v[90:91], v[88:89] op_sel_hi:[0,1]
	v_bfe_u32 v64, v112, 16, 1
	v_bfe_u32 v66, v113, 16, 1
	v_bfe_u32 v4, v91, 16, 1
	v_bfe_u32 v53, v90, 16, 1
	v_bfe_u32 v63, v93, 16, 1
	v_add3_u32 v66, v113, v66, s46
	v_add3_u32 v64, v112, v64, s46
	v_bfe_u32 v57, v111, 16, 1
	v_add3_u32 v53, v90, v53, s46
	v_add3_u32 v4, v91, v4, s46
	v_bfe_u32 v61, v92, 16, 1
	v_add3_u32 v63, v93, v63, s46
	v_lshrrev_b32_e32 v64, 16, v64
	v_lshrrev_b32_e32 v66, 16, v66
	s_waitcnt vmcnt(6)
	v_pk_mul_f32 v[86:87], v[80:81], v[86:87] op_sel_hi:[0,1]
	v_bfe_u32 v59, v110, 16, 1
	v_add3_u32 v57, v111, v57, s46
	v_add3_u32 v61, v92, v61, s46
	v_lshrrev_b32_e32 v63, 16, v63
	v_and_or_b32 v93, v4, s47, v66
	v_and_or_b32 v92, v53, s47, v64
	v_pk_mul_f32 v[82:83], v[80:81], v[82:83] op_sel_hi:[0,1]
	v_pk_mul_f32 v[84:85], v[80:81], v[84:85] op_sel_hi:[0,1]
	v_pk_mul_f32 v[80:81], v[80:81], v[88:89] op_sel_hi:[0,1]
	v_bfe_u32 v64, v86, 16, 1
	v_bfe_u32 v66, v87, 16, 1
	v_add3_u32 v59, v110, v59, s46
	v_lshrrev_b32_e32 v61, 16, v61
	v_and_or_b32 v91, v57, s47, v63
	v_lshlrev_b32_e32 v4, 1, v3
	v_bfe_u32 v3, v81, 16, 1
	v_bfe_u32 v53, v80, 16, 1
	v_bfe_u32 v63, v83, 16, 1
	v_add3_u32 v66, v87, v66, s46
	v_add3_u32 v64, v86, v64, s46
	v_and_or_b32 v90, v59, s47, v61
	v_bfe_u32 v57, v85, 16, 1
	v_add3_u32 v53, v80, v53, s46
	v_add3_u32 v3, v81, v3, s46
	v_bfe_u32 v61, v82, 16, 1
	v_add3_u32 v63, v83, v63, s46
	v_lshrrev_b32_e32 v64, 16, v64
	v_lshrrev_b32_e32 v66, 16, v66
	v_add3_u32 v57, v85, v57, s46
	v_add3_u32 v61, v82, v61, s46
	v_lshrrev_b32_e32 v63, 16, v63
	v_and_or_b32 v83, v3, s47, v66
	v_and_or_b32 v82, v53, s47, v64
	v_mov_b32_e32 v66, v79
	v_mov_b32_e32 v64, v75
	v_and_or_b32 v81, v57, s47, v63
	s_waitcnt vmcnt(5)
	v_pk_mul_f32 v[78:79], v[62:63], v[66:67] op_sel_hi:[0,1]
	v_pk_mul_f32 v[74:75], v[62:63], v[64:65] op_sel_hi:[0,1]
	v_pk_mul_f32 v[76:77], v[62:63], v[70:71] op_sel_hi:[0,1]
	v_pk_mul_f32 v[62:63], v[62:63], v[68:69] op_sel_hi:[0,1]
	v_bfe_u32 v3, v63, 16, 1
	v_bfe_u32 v59, v84, 16, 1
	v_add3_u32 v3, v63, v3, s46
	v_bfe_u32 v63, v77, 16, 1
	v_lshl_add_u64 v[110:111], v[54:55], 0, v[4:5]
	v_add3_u32 v59, v84, v59, s46
	v_lshl_add_u64 v[84:85], v[48:49], 0, v[4:5]
	v_bfe_u32 v4, v62, 16, 1
	v_add3_u32 v63, v77, v63, s46
	v_lshrrev_b32_e32 v61, 16, v61
	v_bfe_u32 v53, v75, 16, 1
	v_add3_u32 v4, v62, v4, s46
	v_bfe_u32 v62, v76, 16, 1
	v_lshrrev_b32_e32 v63, 16, v63
	v_and_or_b32 v80, v59, s47, v61
	v_add3_u32 v53, v75, v53, s46
	v_bfe_u32 v59, v78, 16, 1
	v_bfe_u32 v61, v79, 16, 1
	v_add3_u32 v62, v76, v62, s46
	v_and_or_b32 v75, v3, s47, v63
	v_or_b32_e32 v3, v51, v98
	v_bfe_u32 v57, v74, 16, 1
	v_add3_u32 v61, v79, v61, s46
	v_add3_u32 v59, v78, v59, s46
	v_lshrrev_b32_e32 v62, 16, v62
	v_mul_u32_u24_e32 v3, 0xb00, v3
	v_add3_u32 v57, v74, v57, s46
	v_lshrrev_b32_e32 v59, 16, v59
	v_lshrrev_b32_e32 v61, 16, v61
	v_and_or_b32 v74, v4, s47, v62
	v_lshlrev_b32_e32 v4, 1, v3
	v_and_or_b32 v73, v53, s47, v61
	v_and_or_b32 v72, v57, s47, v59
	v_lshl_add_u64 v[62:63], v[54:55], 0, v[4:5]
	global_store_dwordx4 v[110:111], v[90:93], off
	global_store_dwordx4 v[84:85], v[80:83], off
	global_store_dwordx4 v[62:63], v[72:75], off
	s_waitcnt vmcnt(7)
	v_pk_mul_f32 v[62:63], v[60:61], v[66:67] op_sel_hi:[0,1]
	v_pk_mul_f32 v[64:65], v[60:61], v[64:65] op_sel_hi:[0,1]
	v_pk_mul_f32 v[66:67], v[60:61], v[70:71] op_sel_hi:[0,1]
	v_pk_mul_f32 v[60:61], v[60:61], v[68:69] op_sel_hi:[0,1]
	v_bfe_u32 v3, v61, 16, 1
	v_bfe_u32 v53, v60, 16, 1
	v_bfe_u32 v57, v65, 16, 1
	v_bfe_u32 v59, v64, 16, 1
	v_add3_u32 v59, v64, v59, s46
	v_add3_u32 v57, v65, v57, s46
	v_add3_u32 v53, v60, v53, s46
	v_add3_u32 v3, v61, v3, s46
	v_bfe_u32 v60, v62, 16, 1
	v_bfe_u32 v61, v63, 16, 1
	v_bfe_u32 v64, v66, 16, 1
	v_bfe_u32 v65, v67, 16, 1
	v_add3_u32 v65, v67, v65, s46
	v_add3_u32 v64, v66, v64, s46
	v_add3_u32 v61, v63, v61, s46
	v_add3_u32 v60, v62, v60, s46
	v_lshrrev_b32_e32 v60, 16, v60
	v_lshrrev_b32_e32 v61, 16, v61
	v_lshrrev_b32_e32 v62, 16, v64
	v_lshrrev_b32_e32 v63, 16, v65
	v_and_or_b32 v63, v3, s47, v63
	v_and_or_b32 v62, v53, s47, v62
	v_and_or_b32 v61, v57, s47, v61
	v_and_or_b32 v60, v59, s47, v60
	v_lshl_add_u64 v[64:65], v[48:49], 0, v[4:5]
	global_store_dwordx4 v[64:65], v[60:63], off
	ds_read2_b32 v[62:63], v97 offset0:16 offset1:24
	ds_read2_b32 v[64:65], v97 offset0:49 offset1:57
	ds_read2_b32 v[66:67], v97 offset0:82 offset1:90
	ds_read2_b32 v[68:69], v97 offset0:115 offset1:123
	ds_read2_b32 v[70:71], v97 offset0:148 offset1:156
	ds_read2_b32 v[72:73], v97 offset0:181 offset1:189
	ds_read2_b32 v[74:75], v97 offset0:214 offset1:222
	ds_read2_b32 v[76:77], v97 offset0:247 offset1:255
	s_waitcnt lgkmcnt(7)
	v_mov_b32_e32 v78, v62
	s_waitcnt lgkmcnt(5)
	v_mov_b32_e32 v79, v66
	v_mov_b32_e32 v80, v64
	s_waitcnt lgkmcnt(4)
	v_mov_b32_e32 v81, v68
	s_waitcnt lgkmcnt(3)
	v_mov_b32_e32 v84, v70
	s_waitcnt lgkmcnt(1)
	v_mov_b32_e32 v85, v74
	v_mov_b32_e32 v88, v72
	s_waitcnt lgkmcnt(0)
	v_mov_b32_e32 v89, v76
	s_waitcnt vmcnt(7)
	v_pk_mul_f32 v[60:61], v[58:59], v[78:79] op_sel_hi:[0,1]
	v_pk_mul_f32 v[82:83], v[58:59], v[80:81] op_sel_hi:[0,1]
	v_pk_mul_f32 v[86:87], v[58:59], v[84:85] op_sel_hi:[0,1]
	v_pk_mul_f32 v[58:59], v[58:59], v[88:89] op_sel_hi:[0,1]
	v_bfe_u32 v3, v59, 16, 1
	v_bfe_u32 v64, v87, 16, 1
	v_add3_u32 v3, v59, v3, s46
	v_bfe_u32 v59, v61, 16, 1
	v_add3_u32 v64, v87, v64, s46
	v_bfe_u32 v4, v58, 16, 1
	v_bfe_u32 v62, v86, 16, 1
	v_add3_u32 v59, v61, v59, s46
	v_lshrrev_b32_e32 v61, 16, v64
	v_add3_u32 v4, v58, v4, s46
	v_bfe_u32 v58, v60, 16, 1
	v_add3_u32 v62, v86, v62, s46
	v_and_or_b32 v61, v3, s47, v61
	v_or_b32_e32 v3, v51, v99
	v_bfe_u32 v53, v83, 16, 1
	v_bfe_u32 v57, v82, 16, 1
	v_add3_u32 v58, v60, v58, s46
	v_lshrrev_b32_e32 v60, 16, v62
	v_mul_u32_u24_e32 v3, 0xb00, v3
	v_add3_u32 v57, v82, v57, s46
	v_add3_u32 v53, v83, v53, s46
	v_lshrrev_b32_e32 v58, 16, v58
	v_lshrrev_b32_e32 v59, 16, v59
	v_and_or_b32 v60, v4, s47, v60
	v_lshlrev_b32_e32 v4, 1, v3
	v_and_or_b32 v59, v53, s47, v59
	v_and_or_b32 v58, v57, s47, v58
	v_lshl_add_u64 v[82:83], v[54:55], 0, v[4:5]
	global_store_dwordx4 v[82:83], v[58:61], off
	v_mov_b32_e32 v68, v65
	v_mov_b32_e32 v66, v63
	s_waitcnt vmcnt(7)
	v_pk_mul_f32 v[58:59], v[56:57], v[78:79] op_sel_hi:[0,1]
	v_pk_mul_f32 v[60:61], v[56:57], v[80:81] op_sel_hi:[0,1]
	v_pk_mul_f32 v[78:79], v[56:57], v[84:85] op_sel_hi:[0,1]
	v_pk_mul_f32 v[56:57], v[56:57], v[88:89] op_sel_hi:[0,1]
	v_bfe_u32 v3, v57, 16, 1
	v_bfe_u32 v53, v56, 16, 1
	v_bfe_u32 v62, v61, 16, 1
	v_bfe_u32 v64, v60, 16, 1
	v_add3_u32 v60, v60, v64, s46
	v_add3_u32 v61, v61, v62, s46
	v_add3_u32 v53, v56, v53, s46
	v_add3_u32 v3, v57, v3, s46
	v_bfe_u32 v56, v58, 16, 1
	v_bfe_u32 v57, v59, 16, 1
	v_bfe_u32 v62, v78, 16, 1
	v_bfe_u32 v64, v79, 16, 1
	v_add3_u32 v64, v79, v64, s46
	v_add3_u32 v62, v78, v62, s46
	v_add3_u32 v57, v59, v57, s46
	v_add3_u32 v56, v58, v56, s46
	v_lshrrev_b32_e32 v56, 16, v56
	v_lshrrev_b32_e32 v57, 16, v57
	v_lshrrev_b32_e32 v58, 16, v62
	v_lshrrev_b32_e32 v59, 16, v64
	v_and_or_b32 v59, v3, s47, v59
	v_and_or_b32 v58, v53, s47, v58
	v_and_or_b32 v57, v61, s47, v57
	v_and_or_b32 v56, v60, s47, v56
	v_lshl_add_u64 v[60:61], v[48:49], 0, v[4:5]
	global_store_dwordx4 v[60:61], v[56:59], off
	v_mov_b32_e32 v74, v71
	v_mov_b32_e32 v76, v73
	s_waitcnt vmcnt(7)
	v_pk_mul_f32 v[58:59], v[52:53], v[68:69] op_sel_hi:[0,1]
	v_pk_mul_f32 v[56:57], v[52:53], v[66:67] op_sel_hi:[0,1]
	v_pk_mul_f32 v[60:61], v[52:53], v[74:75] op_sel_hi:[0,1]
	v_pk_mul_f32 v[52:53], v[52:53], v[76:77] op_sel_hi:[0,1]
	v_bfe_u32 v62, v59, 16, 1
	v_bfe_u32 v3, v53, 16, 1
	v_add3_u32 v62, v59, v62, s46
	v_bfe_u32 v59, v61, 16, 1
	v_bfe_u32 v63, v58, 16, 1
	v_add3_u32 v3, v53, v3, s46
	v_bfe_u32 v53, v57, 16, 1
	v_add3_u32 v59, v61, v59, s46
	v_bfe_u32 v4, v52, 16, 1
	v_add3_u32 v63, v58, v63, s46
	v_bfe_u32 v58, v60, 16, 1
	v_add3_u32 v53, v57, v53, s46
	v_lshrrev_b32_e32 v57, 16, v59
	v_add3_u32 v4, v52, v4, s46
	v_bfe_u32 v52, v56, 16, 1
	v_add3_u32 v58, v60, v58, s46
	v_and_or_b32 v59, v3, s47, v57
	v_or_b32_e32 v3, v51, v100
	v_add3_u32 v52, v56, v52, s46
	v_lshrrev_b32_e32 v56, 16, v58
	v_mul_u32_u24_e32 v3, 0xb00, v3
	v_lshrrev_b32_e32 v52, 16, v52
	v_lshrrev_b32_e32 v53, 16, v53
	v_and_or_b32 v58, v4, s47, v56
	v_lshlrev_b32_e32 v4, 1, v3
	v_and_or_b32 v57, v62, s47, v53
	v_and_or_b32 v56, v63, s47, v52
	v_lshl_add_u64 v[52:53], v[54:55], 0, v[4:5]
	global_store_dwordx4 v[52:53], v[56:59], off
	s_waitcnt vmcnt(7)
	v_pk_mul_f32 v[52:53], v[50:51], v[66:67] op_sel_hi:[0,1]
	v_pk_mul_f32 v[54:55], v[50:51], v[68:69] op_sel_hi:[0,1]
	v_pk_mul_f32 v[56:57], v[50:51], v[74:75] op_sel_hi:[0,1]
	v_pk_mul_f32 v[50:51], v[50:51], v[76:77] op_sel_hi:[0,1]
	v_bfe_u32 v3, v51, 16, 1
	v_bfe_u32 v58, v50, 16, 1
	v_bfe_u32 v59, v55, 16, 1
	v_bfe_u32 v60, v54, 16, 1
	v_add3_u32 v54, v54, v60, s46
	v_add3_u32 v55, v55, v59, s46
	v_add3_u32 v50, v50, v58, s46
	v_add3_u32 v3, v51, v3, s46
	v_bfe_u32 v51, v52, 16, 1
	v_bfe_u32 v58, v53, 16, 1
	v_bfe_u32 v59, v56, 16, 1
	v_bfe_u32 v60, v57, 16, 1
	v_add3_u32 v57, v57, v60, s46
	v_add3_u32 v56, v56, v59, s46
	v_add3_u32 v53, v53, v58, s46
	v_add3_u32 v51, v52, v51, s46
	v_lshrrev_b32_e32 v58, 16, v51
	v_lshrrev_b32_e32 v51, 16, v53
	v_lshrrev_b32_e32 v52, 16, v56
	v_lshrrev_b32_e32 v53, 16, v57
	v_and_or_b32 v53, v3, s47, v53
	v_and_or_b32 v52, v50, s47, v52
	v_and_or_b32 v51, v55, s47, v51
	v_and_or_b32 v50, v54, s47, v58
	v_lshl_add_u64 v[48:49], v[48:49], 0, v[4:5]
	global_store_dwordx4 v[48:49], v[50:53], off
	s_waitcnt lgkmcnt(0)

.LBB0_2644:
	s_lshl_b32 s61, s54, 1
	s_lshl_b32 s64, s55, 1
	v_or_b32_e32 v56, s61, v1
	v_or_b32_e32 v57, s64, v0
	v_add_lshl_u32 v4, v56, v3, 10
	v_add_lshl_u32 v53, v57, v48, 10
	v_or_b32_e32 v52, v49, v4
	v_or_b32_e32 v4, v50, v53
	v_lshl_add_u64 v[54:55], v[4:5], 2, s[16:17]
	v_mov_b32_e32 v53, v5
	v_lshl_add_u64 v[52:53], v[52:53], 2, s[16:17]
	global_load_dword v126, v[54:55], off
	global_load_dword v127, v[52:53], off
	v_mad_u64_u32 v[52:53], s[66:67], v57, s40, v[2:3]
	v_mad_u64_u32 v[54:55], s[66:67], v56, s40, v[2:3]
	s_add_i32 s65, s61, 4
	s_add_i32 s66, s64, 4
	v_or_b32_e32 v56, s65, v1
	v_or_b32_e32 v57, s66, v0
	v_add_lshl_u32 v53, v57, v48, 10
	s_add_i32 s65, s61, 8
	s_add_i32 s55, s55, 16
	s_add_i32 s54, s54, 16
	s_add_i32 s60, s60, -16
	v_mov_b32_e32 v142, v52
	v_mov_b32_e32 v143, v54
	v_add_lshl_u32 v4, v56, v3, 10
	v_or_b32_e32 v52, v49, v4
	v_or_b32_e32 v4, v50, v53
	v_lshl_add_u64 v[54:55], v[4:5], 2, s[16:17]
	v_mov_b32_e32 v53, v5
	v_lshl_add_u64 v[52:53], v[52:53], 2, s[16:17]
	global_load_dword v128, v[54:55], off
	global_load_dword v129, v[52:53], off
	v_mad_u64_u32 v[52:53], s[66:67], v57, s40, v[2:3]
	v_mad_u64_u32 v[54:55], s[66:67], v56, s40, v[2:3]
	s_add_i32 s66, s64, 8
	v_or_b32_e32 v56, s65, v1
	v_or_b32_e32 v57, s66, v0
	v_add_lshl_u32 v53, v57, v48, 10
	s_add_i32 s65, s61, 12
	v_mov_b32_e32 v144, v52
	v_mov_b32_e32 v145, v54
	v_add_lshl_u32 v4, v56, v3, 10
	v_or_b32_e32 v52, v49, v4
	v_or_b32_e32 v4, v50, v53
	v_lshl_add_u64 v[54:55], v[4:5], 2, s[16:17]
	v_mov_b32_e32 v53, v5
	v_lshl_add_u64 v[52:53], v[52:53], 2, s[16:17]
	global_load_dword v130, v[54:55], off
	global_load_dword v131, v[52:53], off
	v_mad_u64_u32 v[52:53], s[66:67], v57, s40, v[2:3]
	v_mad_u64_u32 v[54:55], s[66:67], v56, s40, v[2:3]
	s_add_i32 s66, s64, 12
	v_or_b32_e32 v56, s65, v1
	v_or_b32_e32 v57, s66, v0
	v_add_lshl_u32 v53, v57, v48, 10
	s_add_i32 s65, s61, 16
	v_mov_b32_e32 v146, v52
	v_mov_b32_e32 v147, v54
	v_add_lshl_u32 v4, v56, v3, 10
	v_or_b32_e32 v52, v49, v4
	v_or_b32_e32 v4, v50, v53
	v_lshl_add_u64 v[54:55], v[4:5], 2, s[16:17]
	v_mov_b32_e32 v53, v5
	v_lshl_add_u64 v[52:53], v[52:53], 2, s[16:17]
	global_load_dword v132, v[54:55], off
	global_load_dword v133, v[52:53], off
	v_mad_u64_u32 v[52:53], s[66:67], v57, s40, v[2:3]
	v_mad_u64_u32 v[54:55], s[66:67], v56, s40, v[2:3]
	s_add_i32 s66, s64, 16
	v_or_b32_e32 v56, s65, v1
	v_or_b32_e32 v57, s66, v0
	v_add_lshl_u32 v53, v57, v48, 10
	s_add_i32 s65, s61, 20
	v_mov_b32_e32 v148, v52
	v_mov_b32_e32 v149, v54
	v_add_lshl_u32 v4, v56, v3, 10
	v_or_b32_e32 v52, v49, v4
	v_or_b32_e32 v4, v50, v53
	v_lshl_add_u64 v[54:55], v[4:5], 2, s[16:17]
	v_mov_b32_e32 v53, v5
	v_lshl_add_u64 v[52:53], v[52:53], 2, s[16:17]
	global_load_dword v134, v[54:55], off
	global_load_dword v135, v[52:53], off
	v_mad_u64_u32 v[52:53], s[66:67], v57, s40, v[2:3]
	v_mad_u64_u32 v[54:55], s[66:67], v56, s40, v[2:3]
	s_add_i32 s66, s64, 20
	v_or_b32_e32 v56, s65, v1
	v_or_b32_e32 v57, s66, v0
	v_add_lshl_u32 v53, v57, v48, 10
	s_add_i32 s65, s61, 24
	s_add_i32 s61, s61, 28
	v_mov_b32_e32 v150, v52
	v_mov_b32_e32 v151, v54
	v_add_lshl_u32 v4, v56, v3, 10
	v_or_b32_e32 v52, v49, v4
	v_or_b32_e32 v4, v50, v53
	v_lshl_add_u64 v[54:55], v[4:5], 2, s[16:17]
	v_mov_b32_e32 v53, v5
	v_lshl_add_u64 v[52:53], v[52:53], 2, s[16:17]
	global_load_dword v136, v[54:55], off
	global_load_dword v137, v[52:53], off
	v_mad_u64_u32 v[52:53], s[66:67], v57, s40, v[2:3]
	v_mad_u64_u32 v[54:55], s[66:67], v56, s40, v[2:3]
	s_add_i32 s66, s64, 24
	v_or_b32_e32 v56, s65, v1
	v_or_b32_e32 v57, s66, v0
	v_add_lshl_u32 v53, v57, v48, 10
	s_add_i32 s64, s64, 28
	s_cmp_lg_u32 s60, 0
	v_mov_b32_e32 v152, v52
	v_mov_b32_e32 v153, v54
	v_add_lshl_u32 v4, v56, v3, 10
	v_or_b32_e32 v52, v49, v4
	v_or_b32_e32 v4, v50, v53
	v_lshl_add_u64 v[54:55], v[4:5], 2, s[16:17]
	v_mov_b32_e32 v53, v5
	v_lshl_add_u64 v[52:53], v[52:53], 2, s[16:17]
	global_load_dword v138, v[54:55], off
	global_load_dword v139, v[52:53], off
	v_mad_u64_u32 v[52:53], s[66:67], v57, s40, v[2:3]
	v_mad_u64_u32 v[54:55], s[66:67], v56, s40, v[2:3]
	v_or_b32_e32 v56, s61, v1
	v_or_b32_e32 v57, s64, v0
	v_mov_b32_e32 v55, v5
	v_mov_b32_e32 v154, v52
	v_mov_b32_e32 v155, v54
	v_add_lshl_u32 v4, v56, v3, 10
	v_add_lshl_u32 v52, v57, v48, 10
	v_or_b32_e32 v54, v49, v4
	v_or_b32_e32 v4, v50, v52
	v_lshl_add_u64 v[52:53], v[4:5], 2, s[16:17]
	v_lshl_add_u64 v[54:55], v[54:55], 2, s[16:17]
	global_load_dword v140, v[52:53], off
	global_load_dword v141, v[54:55], off
	v_mad_u64_u32 v[52:53], s[64:65], v57, s40, v[2:3]
	v_mad_u64_u32 v[54:55], s[64:65], v56, s40, v[2:3]
	v_mov_b32_e32 v156, v52
	v_mov_b32_e32 v157, v54
	s_waitcnt vmcnt(15)
	ds_write_b32 v142, v126
	s_waitcnt vmcnt(14)
	ds_write_b32 v143, v127
	s_waitcnt vmcnt(13)
	ds_write_b32 v144, v128
	s_waitcnt vmcnt(12)
	ds_write_b32 v145, v129
	s_waitcnt vmcnt(11)
	ds_write_b32 v146, v130
	s_waitcnt vmcnt(10)
	ds_write_b32 v147, v131
	s_waitcnt vmcnt(9)
	ds_write_b32 v148, v132
	s_waitcnt vmcnt(8)
	ds_write_b32 v149, v133
	s_waitcnt vmcnt(7)
	ds_write_b32 v150, v134
	s_waitcnt vmcnt(6)
	ds_write_b32 v151, v135
	s_waitcnt vmcnt(5)
	ds_write_b32 v152, v136
	s_waitcnt vmcnt(4)
	ds_write_b32 v153, v137
	s_waitcnt vmcnt(3)
	ds_write_b32 v154, v138
	s_waitcnt vmcnt(2)
	ds_write_b32 v155, v139
	s_waitcnt vmcnt(1)
	ds_write_b32 v156, v140
	s_waitcnt vmcnt(0)
	ds_write_b32 v157, v141
	s_cbranch_scc1 .LBB0_2644
	v_or_b32_e32 v3, v51, v96
	v_lshlrev_b32_e32 v4, 2, v3
	v_or_b32_e32 v49, 0x2000, v4
	global_load_dword v90, v49, s[92:93]
	global_load_dword v80, v49, s[94:95]
	v_or_b32_e32 v49, 0x2020, v4
	global_load_dword v62, v49, s[92:93]
	global_load_dword v60, v49, s[94:95]
	v_or_b32_e32 v49, 0x2040, v4
	global_load_dword v58, v49, s[92:93]
	global_load_dword v56, v49, s[94:95]
	v_or_b32_e32 v4, 0x2060, v4
	global_load_dword v52, v4, s[92:93]
	global_load_dword v50, v4, s[94:95]
	s_waitcnt lgkmcnt(0)
	ds_read2_b32 v[74:75], v97 offset0:33 offset1:41
	ds_read2_b32 v[66:67], v97 offset0:66 offset1:74
	ds_read2_b32 v[64:65], v97 offset0:99 offset1:107
	ds_read2_b32 v[76:77], v97 offset0:132 offset1:140
	ds_read2_b32 v[72:73], v97 offset0:165 offset1:173
	ds_read2_b32 v[70:71], v97 offset0:198 offset1:206
	ds_read2_b32 v[68:69], v97 offset0:231 offset1:239
	ds_read2_b32 v[78:79], v97 offset1:8
	s_waitcnt lgkmcnt(4)
	v_mov_b32_e32 v86, v76
	v_mov_b32_e32 v83, v66
	s_waitcnt lgkmcnt(2)
	v_mov_b32_e32 v87, v70
	v_mov_b32_e32 v84, v74
	s_waitcnt lgkmcnt(0)
	v_mov_b32_e32 v82, v78
	v_mov_b32_e32 v85, v64
	v_mov_b32_e32 v88, v72
	v_mov_b32_e32 v89, v68
	v_lshlrev_b32_e32 v4, 1, v48
	v_lshl_add_u64 v[54:55], v[8:9], 0, v[4:5]
	v_lshl_add_u64 v[48:49], v[24:25], 0, v[4:5]
	v_mov_b32_e32 v70, v77
	v_mov_b32_e32 v68, v73
	s_waitcnt vmcnt(7)
	v_pk_mul_f32 v[112:113], v[90:91], v[86:87] op_sel_hi:[0,1]
	v_pk_mul_f32 v[92:93], v[90:91], v[82:83] op_sel_hi:[0,1]
	v_pk_mul_f32 v[110:111], v[90:91], v[84:85] op_sel_hi:[0,1]
	v_pk_mul_f32 v[90:91], v[90:91], v[88:89] op_sel_hi:[0,1]
	v_bfe_u32 v64, v112, 16, 1
	v_bfe_u32 v66, v113, 16, 1
	v_bfe_u32 v4, v91, 16, 1
	v_bfe_u32 v53, v90, 16, 1
	v_bfe_u32 v63, v93, 16, 1
	v_add3_u32 v66, v113, v66, s46
	v_add3_u32 v64, v112, v64, s46
	v_bfe_u32 v57, v111, 16, 1
	v_add3_u32 v53, v90, v53, s46
	v_add3_u32 v4, v91, v4, s46
	v_bfe_u32 v61, v92, 16, 1
	v_add3_u32 v63, v93, v63, s46
	v_lshrrev_b32_e32 v64, 16, v64
	v_lshrrev_b32_e32 v66, 16, v66
	s_waitcnt vmcnt(6)
	v_pk_mul_f32 v[86:87], v[80:81], v[86:87] op_sel_hi:[0,1]
	v_bfe_u32 v59, v110, 16, 1
	v_add3_u32 v57, v111, v57, s46
	v_add3_u32 v61, v92, v61, s46
	v_lshrrev_b32_e32 v63, 16, v63
	v_and_or_b32 v93, v4, s47, v66
	v_and_or_b32 v92, v53, s47, v64
	v_pk_mul_f32 v[82:83], v[80:81], v[82:83] op_sel_hi:[0,1]
	v_pk_mul_f32 v[84:85], v[80:81], v[84:85] op_sel_hi:[0,1]
	v_pk_mul_f32 v[80:81], v[80:81], v[88:89] op_sel_hi:[0,1]
	v_bfe_u32 v64, v86, 16, 1
	v_bfe_u32 v66, v87, 16, 1
	v_add3_u32 v59, v110, v59, s46
	v_lshrrev_b32_e32 v61, 16, v61
	v_and_or_b32 v91, v57, s47, v63
	v_lshlrev_b32_e32 v4, 11, v3
	v_bfe_u32 v3, v81, 16, 1
	v_bfe_u32 v53, v80, 16, 1
	v_bfe_u32 v63, v83, 16, 1
	v_add3_u32 v66, v87, v66, s46
	v_add3_u32 v64, v86, v64, s46
	v_and_or_b32 v90, v59, s47, v61
	v_bfe_u32 v57, v85, 16, 1
	v_add3_u32 v53, v80, v53, s46
	v_add3_u32 v3, v81, v3, s46
	v_bfe_u32 v61, v82, 16, 1
	v_add3_u32 v63, v83, v63, s46
	v_lshrrev_b32_e32 v64, 16, v64
	v_lshrrev_b32_e32 v66, 16, v66
	v_add3_u32 v57, v85, v57, s46
	v_add3_u32 v61, v82, v61, s46
	v_lshrrev_b32_e32 v63, 16, v63
	v_and_or_b32 v83, v3, s47, v66
	v_and_or_b32 v82, v53, s47, v64
	v_mov_b32_e32 v66, v79
	v_mov_b32_e32 v64, v75
	v_and_or_b32 v81, v57, s47, v63
	s_waitcnt vmcnt(5)
	v_pk_mul_f32 v[78:79], v[62:63], v[66:67] op_sel_hi:[0,1]
	v_pk_mul_f32 v[74:75], v[62:63], v[64:65] op_sel_hi:[0,1]
	v_pk_mul_f32 v[76:77], v[62:63], v[70:71] op_sel_hi:[0,1]
	v_pk_mul_f32 v[62:63], v[62:63], v[68:69] op_sel_hi:[0,1]
	v_bfe_u32 v59, v84, 16, 1
	v_bfe_u32 v3, v63, 16, 1
	v_lshl_add_u64 v[110:111], v[54:55], 0, v[4:5]
	v_add3_u32 v59, v84, v59, s46
	v_lshl_add_u64 v[84:85], v[48:49], 0, v[4:5]
	v_bfe_u32 v4, v62, 16, 1
	v_add3_u32 v3, v63, v3, s46
	v_bfe_u32 v63, v77, 16, 1
	v_lshrrev_b32_e32 v61, 16, v61
	v_add3_u32 v4, v62, v4, s46
	v_bfe_u32 v62, v76, 16, 1
	v_add3_u32 v63, v77, v63, s46
	v_and_or_b32 v80, v59, s47, v61
	v_bfe_u32 v53, v75, 16, 1
	v_bfe_u32 v59, v78, 16, 1
	v_bfe_u32 v61, v79, 16, 1
	v_add3_u32 v62, v76, v62, s46
	v_lshrrev_b32_e32 v63, 16, v63
	v_bfe_u32 v57, v74, 16, 1
	v_add3_u32 v53, v75, v53, s46
	v_add3_u32 v61, v79, v61, s46
	v_add3_u32 v59, v78, v59, s46
	v_lshrrev_b32_e32 v62, 16, v62
	v_and_or_b32 v75, v3, s47, v63
	v_or_b32_e32 v3, v51, v98
	v_add3_u32 v57, v74, v57, s46
	v_lshrrev_b32_e32 v59, 16, v59
	v_lshrrev_b32_e32 v61, 16, v61
	v_and_or_b32 v74, v4, s47, v62
	v_lshlrev_b32_e32 v4, 11, v3
	v_and_or_b32 v73, v53, s47, v61
	v_and_or_b32 v72, v57, s47, v59
	v_lshl_add_u64 v[62:63], v[54:55], 0, v[4:5]
	global_store_dwordx4 v[62:63], v[72:75], off
	s_waitcnt vmcnt(5)
	v_pk_mul_f32 v[62:63], v[60:61], v[66:67] op_sel_hi:[0,1]
	v_pk_mul_f32 v[64:65], v[60:61], v[64:65] op_sel_hi:[0,1]
	v_pk_mul_f32 v[66:67], v[60:61], v[70:71] op_sel_hi:[0,1]
	v_pk_mul_f32 v[60:61], v[60:61], v[68:69] op_sel_hi:[0,1]
	v_bfe_u32 v3, v61, 16, 1
	v_bfe_u32 v53, v60, 16, 1
	v_bfe_u32 v57, v65, 16, 1
	v_bfe_u32 v59, v64, 16, 1
	v_add3_u32 v59, v64, v59, s46
	v_add3_u32 v57, v65, v57, s46
	v_add3_u32 v53, v60, v53, s46
	v_add3_u32 v3, v61, v3, s46
	v_bfe_u32 v60, v62, 16, 1
	v_bfe_u32 v61, v63, 16, 1
	v_bfe_u32 v64, v66, 16, 1
	v_bfe_u32 v65, v67, 16, 1
	v_add3_u32 v65, v67, v65, s46
	v_add3_u32 v64, v66, v64, s46
	v_add3_u32 v61, v63, v61, s46
	v_add3_u32 v60, v62, v60, s46
	v_lshrrev_b32_e32 v60, 16, v60
	v_lshrrev_b32_e32 v61, 16, v61
	v_lshrrev_b32_e32 v62, 16, v64
	v_lshrrev_b32_e32 v63, 16, v65
	v_and_or_b32 v63, v3, s47, v63
	v_and_or_b32 v62, v53, s47, v62
	v_and_or_b32 v61, v57, s47, v61
	v_and_or_b32 v60, v59, s47, v60
	v_lshl_add_u64 v[64:65], v[48:49], 0, v[4:5]
	global_store_dwordx4 v[110:111], v[90:93], off
	global_store_dwordx4 v[84:85], v[80:83], off
	global_store_dwordx4 v[64:65], v[60:63], off
	ds_read2_b32 v[62:63], v97 offset0:49 offset1:57
	ds_read2_b32 v[64:65], v97 offset0:82 offset1:90
	ds_read2_b32 v[66:67], v97 offset0:115 offset1:123
	ds_read2_b32 v[68:69], v97 offset0:148 offset1:156
	ds_read2_b32 v[70:71], v97 offset0:181 offset1:189
	ds_read2_b32 v[72:73], v97 offset0:214 offset1:222
	ds_read2_b32 v[74:75], v97 offset0:247 offset1:255
	ds_read2_b32 v[76:77], v97 offset0:16 offset1:24
	s_waitcnt lgkmcnt(6)
	v_mov_b32_e32 v79, v64
	v_mov_b32_e32 v80, v62
	s_waitcnt lgkmcnt(5)
	v_mov_b32_e32 v81, v66
	s_waitcnt lgkmcnt(4)
	v_mov_b32_e32 v84, v68
	s_waitcnt lgkmcnt(0)
	v_mov_b32_e32 v78, v76
	v_mov_b32_e32 v85, v72
	v_mov_b32_e32 v88, v70
	v_mov_b32_e32 v89, v74
	s_waitcnt vmcnt(7)
	v_pk_mul_f32 v[60:61], v[58:59], v[78:79] op_sel_hi:[0,1]
	v_pk_mul_f32 v[82:83], v[58:59], v[80:81] op_sel_hi:[0,1]
	v_pk_mul_f32 v[86:87], v[58:59], v[84:85] op_sel_hi:[0,1]
	v_pk_mul_f32 v[58:59], v[58:59], v[88:89] op_sel_hi:[0,1]
	v_bfe_u32 v3, v59, 16, 1
	v_bfe_u32 v64, v87, 16, 1
	v_bfe_u32 v4, v58, 16, 1
	v_add3_u32 v3, v59, v3, s46
	v_bfe_u32 v59, v61, 16, 1
	v_bfe_u32 v62, v86, 16, 1
	v_add3_u32 v64, v87, v64, s46
	v_add3_u32 v4, v58, v4, s46
	v_bfe_u32 v58, v60, 16, 1
	v_add3_u32 v62, v86, v62, s46
	v_add3_u32 v59, v61, v59, s46
	v_lshrrev_b32_e32 v61, 16, v64
	v_bfe_u32 v53, v83, 16, 1
	v_bfe_u32 v57, v82, 16, 1
	v_add3_u32 v58, v60, v58, s46
	v_lshrrev_b32_e32 v60, 16, v62
	v_and_or_b32 v61, v3, s47, v61
	v_or_b32_e32 v3, v51, v99
	v_add3_u32 v57, v82, v57, s46
	v_add3_u32 v53, v83, v53, s46
	v_lshrrev_b32_e32 v58, 16, v58
	v_lshrrev_b32_e32 v59, 16, v59
	v_and_or_b32 v60, v4, s47, v60
	v_lshlrev_b32_e32 v4, 11, v3
	v_and_or_b32 v59, v53, s47, v59
	v_and_or_b32 v58, v57, s47, v58
	v_lshl_add_u64 v[82:83], v[54:55], 0, v[4:5]
	global_store_dwordx4 v[82:83], v[58:61], off
	v_mov_b32_e32 v66, v63
	v_mov_b32_e32 v72, v69
	s_waitcnt vmcnt(7)
	v_pk_mul_f32 v[58:59], v[56:57], v[78:79] op_sel_hi:[0,1]
	v_pk_mul_f32 v[60:61], v[56:57], v[80:81] op_sel_hi:[0,1]
	v_pk_mul_f32 v[78:79], v[56:57], v[84:85] op_sel_hi:[0,1]
	v_pk_mul_f32 v[56:57], v[56:57], v[88:89] op_sel_hi:[0,1]
	v_bfe_u32 v3, v57, 16, 1
	v_bfe_u32 v53, v56, 16, 1
	v_bfe_u32 v62, v61, 16, 1
	v_bfe_u32 v64, v60, 16, 1
	v_add3_u32 v60, v60, v64, s46
	v_add3_u32 v61, v61, v62, s46
	v_add3_u32 v53, v56, v53, s46
	v_add3_u32 v3, v57, v3, s46
	v_bfe_u32 v56, v58, 16, 1
	v_bfe_u32 v57, v59, 16, 1
	v_bfe_u32 v62, v78, 16, 1
	v_bfe_u32 v64, v79, 16, 1
	v_add3_u32 v64, v79, v64, s46
	v_add3_u32 v62, v78, v62, s46
	v_add3_u32 v57, v59, v57, s46
	v_add3_u32 v56, v58, v56, s46
	v_lshrrev_b32_e32 v56, 16, v56
	v_lshrrev_b32_e32 v57, 16, v57
	v_lshrrev_b32_e32 v58, 16, v62
	v_lshrrev_b32_e32 v59, 16, v64
	v_and_or_b32 v59, v3, s47, v59
	v_and_or_b32 v58, v53, s47, v58
	v_and_or_b32 v57, v61, s47, v57
	v_and_or_b32 v56, v60, s47, v56
	v_lshl_add_u64 v[60:61], v[48:49], 0, v[4:5]
	global_store_dwordx4 v[60:61], v[56:59], off
	v_mov_b32_e32 v64, v77
	v_mov_b32_e32 v74, v71
	s_waitcnt vmcnt(7)
	v_pk_mul_f32 v[58:59], v[52:53], v[66:67] op_sel_hi:[0,1]
	v_pk_mul_f32 v[56:57], v[52:53], v[64:65] op_sel_hi:[0,1]
	v_pk_mul_f32 v[60:61], v[52:53], v[72:73] op_sel_hi:[0,1]
	v_pk_mul_f32 v[52:53], v[52:53], v[74:75] op_sel_hi:[0,1]
	v_bfe_u32 v62, v59, 16, 1
	v_bfe_u32 v3, v53, 16, 1
	v_bfe_u32 v63, v58, 16, 1
	v_add3_u32 v62, v59, v62, s46
	v_bfe_u32 v59, v61, 16, 1
	v_bfe_u32 v4, v52, 16, 1
	v_add3_u32 v63, v58, v63, s46
	v_add3_u32 v3, v53, v3, s46
	v_bfe_u32 v53, v57, 16, 1
	v_bfe_u32 v58, v60, 16, 1
	v_add3_u32 v59, v61, v59, s46
	v_add3_u32 v4, v52, v4, s46
	v_bfe_u32 v52, v56, 16, 1
	v_add3_u32 v58, v60, v58, s46
	v_add3_u32 v53, v57, v53, s46
	v_lshrrev_b32_e32 v57, 16, v59
	v_add3_u32 v52, v56, v52, s46
	v_lshrrev_b32_e32 v56, 16, v58
	v_and_or_b32 v59, v3, s47, v57
	v_or_b32_e32 v3, v51, v100
	v_lshrrev_b32_e32 v52, 16, v52
	v_lshrrev_b32_e32 v53, 16, v53
	v_and_or_b32 v58, v4, s47, v56
	v_lshlrev_b32_e32 v4, 11, v3
	v_and_or_b32 v57, v62, s47, v53
	v_and_or_b32 v56, v63, s47, v52
	v_lshl_add_u64 v[52:53], v[54:55], 0, v[4:5]
	global_store_dwordx4 v[52:53], v[56:59], off
	s_waitcnt vmcnt(7)
	v_pk_mul_f32 v[52:53], v[50:51], v[64:65] op_sel_hi:[0,1]
	v_pk_mul_f32 v[54:55], v[50:51], v[66:67] op_sel_hi:[0,1]
	v_pk_mul_f32 v[56:57], v[50:51], v[72:73] op_sel_hi:[0,1]
	v_pk_mul_f32 v[50:51], v[50:51], v[74:75] op_sel_hi:[0,1]
	v_bfe_u32 v3, v51, 16, 1
	v_bfe_u32 v58, v50, 16, 1
	v_bfe_u32 v59, v55, 16, 1
	v_bfe_u32 v60, v54, 16, 1
	v_add3_u32 v54, v54, v60, s46
	v_add3_u32 v55, v55, v59, s46
	v_add3_u32 v50, v50, v58, s46
	v_add3_u32 v3, v51, v3, s46
	v_bfe_u32 v51, v52, 16, 1
	v_bfe_u32 v58, v53, 16, 1
	v_bfe_u32 v59, v56, 16, 1
	v_bfe_u32 v60, v57, 16, 1
	v_add3_u32 v57, v57, v60, s46
	v_add3_u32 v56, v56, v59, s46
	v_add3_u32 v53, v53, v58, s46
	v_add3_u32 v51, v52, v51, s46
	v_lshrrev_b32_e32 v58, 16, v51
	v_lshrrev_b32_e32 v51, 16, v53
	v_lshrrev_b32_e32 v52, 16, v56
	v_lshrrev_b32_e32 v53, 16, v57
	v_and_or_b32 v53, v3, s47, v53
	v_and_or_b32 v52, v50, s47, v52
	v_and_or_b32 v51, v55, s47, v51
	v_and_or_b32 v50, v54, s47, v58
	v_lshl_add_u64 v[48:49], v[48:49], 0, v[4:5]
	global_store_dwordx4 v[48:49], v[50:53], off
	s_waitcnt lgkmcnt(0)

.LBB0_2649:
	s_lshl_b32 s55, s48, 1
	s_lshl_b32 s60, s49, 1
	v_or_b32_e32 v56, s55, v1
	v_or_b32_e32 v57, s60, v0
	v_add_lshl_u32 v4, v56, v3, 10
	v_add_lshl_u32 v53, v57, v48, 10
	v_or_b32_e32 v52, v49, v4
	v_or_b32_e32 v4, v50, v53
	v_lshl_add_u64 v[54:55], v[4:5], 2, s[6:7]
	v_mov_b32_e32 v53, v5
	v_lshl_add_u64 v[52:53], v[52:53], 2, s[6:7]
	global_load_dword v126, v[54:55], off
	global_load_dword v127, v[52:53], off
	v_mad_u64_u32 v[52:53], s[64:65], v57, s40, v[2:3]
	v_mad_u64_u32 v[54:55], s[64:65], v56, s40, v[2:3]
	s_add_i32 s61, s55, 4
	s_add_i32 s64, s60, 4
	v_or_b32_e32 v56, s61, v1
	v_or_b32_e32 v57, s64, v0
	v_add_lshl_u32 v53, v57, v48, 10
	s_add_i32 s61, s55, 8
	s_add_i32 s49, s49, 16
	s_add_i32 s48, s48, 16
	s_add_i32 s54, s54, -16
	v_mov_b32_e32 v142, v52
	v_mov_b32_e32 v143, v54
	v_add_lshl_u32 v4, v56, v3, 10
	v_or_b32_e32 v52, v49, v4
	v_or_b32_e32 v4, v50, v53
	v_lshl_add_u64 v[54:55], v[4:5], 2, s[6:7]
	v_mov_b32_e32 v53, v5
	v_lshl_add_u64 v[52:53], v[52:53], 2, s[6:7]
	global_load_dword v128, v[54:55], off
	global_load_dword v129, v[52:53], off
	v_mad_u64_u32 v[52:53], s[64:65], v57, s40, v[2:3]
	v_mad_u64_u32 v[54:55], s[64:65], v56, s40, v[2:3]
	s_add_i32 s64, s60, 8
	v_or_b32_e32 v56, s61, v1
	v_or_b32_e32 v57, s64, v0
	v_add_lshl_u32 v53, v57, v48, 10
	s_add_i32 s61, s55, 12
	v_mov_b32_e32 v144, v52
	v_mov_b32_e32 v145, v54
	v_add_lshl_u32 v4, v56, v3, 10
	v_or_b32_e32 v52, v49, v4
	v_or_b32_e32 v4, v50, v53
	v_lshl_add_u64 v[54:55], v[4:5], 2, s[6:7]
	v_mov_b32_e32 v53, v5
	v_lshl_add_u64 v[52:53], v[52:53], 2, s[6:7]
	global_load_dword v130, v[54:55], off
	global_load_dword v131, v[52:53], off
	v_mad_u64_u32 v[52:53], s[64:65], v57, s40, v[2:3]
	v_mad_u64_u32 v[54:55], s[64:65], v56, s40, v[2:3]
	s_add_i32 s64, s60, 12
	v_or_b32_e32 v56, s61, v1
	v_or_b32_e32 v57, s64, v0
	v_add_lshl_u32 v53, v57, v48, 10
	s_add_i32 s61, s55, 16
	v_mov_b32_e32 v146, v52
	v_mov_b32_e32 v147, v54
	v_add_lshl_u32 v4, v56, v3, 10
	v_or_b32_e32 v52, v49, v4
	v_or_b32_e32 v4, v50, v53
	v_lshl_add_u64 v[54:55], v[4:5], 2, s[6:7]
	v_mov_b32_e32 v53, v5
	v_lshl_add_u64 v[52:53], v[52:53], 2, s[6:7]
	global_load_dword v132, v[54:55], off
	global_load_dword v133, v[52:53], off
	v_mad_u64_u32 v[52:53], s[64:65], v57, s40, v[2:3]
	v_mad_u64_u32 v[54:55], s[64:65], v56, s40, v[2:3]
	s_add_i32 s64, s60, 16
	v_or_b32_e32 v56, s61, v1
	v_or_b32_e32 v57, s64, v0
	v_add_lshl_u32 v53, v57, v48, 10
	s_add_i32 s61, s55, 20
	v_mov_b32_e32 v148, v52
	v_mov_b32_e32 v149, v54
	v_add_lshl_u32 v4, v56, v3, 10
	v_or_b32_e32 v52, v49, v4
	v_or_b32_e32 v4, v50, v53
	v_lshl_add_u64 v[54:55], v[4:5], 2, s[6:7]
	v_mov_b32_e32 v53, v5
	v_lshl_add_u64 v[52:53], v[52:53], 2, s[6:7]
	global_load_dword v134, v[54:55], off
	global_load_dword v135, v[52:53], off
	v_mad_u64_u32 v[52:53], s[64:65], v57, s40, v[2:3]
	v_mad_u64_u32 v[54:55], s[64:65], v56, s40, v[2:3]
	s_add_i32 s64, s60, 20
	v_or_b32_e32 v56, s61, v1
	v_or_b32_e32 v57, s64, v0
	v_add_lshl_u32 v53, v57, v48, 10
	s_add_i32 s61, s55, 24
	s_add_i32 s55, s55, 28
	v_mov_b32_e32 v150, v52
	v_mov_b32_e32 v151, v54
	v_add_lshl_u32 v4, v56, v3, 10
	v_or_b32_e32 v52, v49, v4
	v_or_b32_e32 v4, v50, v53
	v_lshl_add_u64 v[54:55], v[4:5], 2, s[6:7]
	v_mov_b32_e32 v53, v5
	v_lshl_add_u64 v[52:53], v[52:53], 2, s[6:7]
	global_load_dword v136, v[54:55], off
	global_load_dword v137, v[52:53], off
	v_mad_u64_u32 v[52:53], s[64:65], v57, s40, v[2:3]
	v_mad_u64_u32 v[54:55], s[64:65], v56, s40, v[2:3]
	s_add_i32 s64, s60, 24
	v_or_b32_e32 v56, s61, v1
	v_or_b32_e32 v57, s64, v0
	v_add_lshl_u32 v53, v57, v48, 10
	s_add_i32 s60, s60, 28
	s_cmp_lg_u32 s54, 0
	v_mov_b32_e32 v152, v52
	v_mov_b32_e32 v153, v54
	v_add_lshl_u32 v4, v56, v3, 10
	v_or_b32_e32 v52, v49, v4
	v_or_b32_e32 v4, v50, v53
	v_lshl_add_u64 v[54:55], v[4:5], 2, s[6:7]
	v_mov_b32_e32 v53, v5
	v_lshl_add_u64 v[52:53], v[52:53], 2, s[6:7]
	global_load_dword v138, v[54:55], off
	global_load_dword v139, v[52:53], off
	v_mad_u64_u32 v[52:53], s[64:65], v57, s40, v[2:3]
	v_mad_u64_u32 v[54:55], s[64:65], v56, s40, v[2:3]
	v_or_b32_e32 v56, s55, v1
	v_or_b32_e32 v57, s60, v0
	v_mov_b32_e32 v55, v5
	v_mov_b32_e32 v154, v52
	v_mov_b32_e32 v155, v54
	v_add_lshl_u32 v4, v56, v3, 10
	v_add_lshl_u32 v52, v57, v48, 10
	v_or_b32_e32 v54, v49, v4
	v_or_b32_e32 v4, v50, v52
	v_lshl_add_u64 v[52:53], v[4:5], 2, s[6:7]
	v_lshl_add_u64 v[54:55], v[54:55], 2, s[6:7]
	global_load_dword v140, v[52:53], off
	global_load_dword v141, v[54:55], off
	v_mad_u64_u32 v[52:53], s[60:61], v57, s40, v[2:3]
	v_mad_u64_u32 v[54:55], s[60:61], v56, s40, v[2:3]
	v_mov_b32_e32 v156, v52
	v_mov_b32_e32 v157, v54
	s_waitcnt vmcnt(15)
	ds_write_b32 v142, v126
	s_waitcnt vmcnt(14)
	ds_write_b32 v143, v127
	s_waitcnt vmcnt(13)
	ds_write_b32 v144, v128
	s_waitcnt vmcnt(12)
	ds_write_b32 v145, v129
	s_waitcnt vmcnt(11)
	ds_write_b32 v146, v130
	s_waitcnt vmcnt(10)
	ds_write_b32 v147, v131
	s_waitcnt vmcnt(9)
	ds_write_b32 v148, v132
	s_waitcnt vmcnt(8)
	ds_write_b32 v149, v133
	s_waitcnt vmcnt(7)
	ds_write_b32 v150, v134
	s_waitcnt vmcnt(6)
	ds_write_b32 v151, v135
	s_waitcnt vmcnt(5)
	ds_write_b32 v152, v136
	s_waitcnt vmcnt(4)
	ds_write_b32 v153, v137
	s_waitcnt vmcnt(3)
	ds_write_b32 v154, v138
	s_waitcnt vmcnt(2)
	ds_write_b32 v155, v139
	s_waitcnt vmcnt(1)
	ds_write_b32 v156, v140
	s_waitcnt vmcnt(0)
	ds_write_b32 v157, v141
	s_cbranch_scc1 .LBB0_2649
	s_waitcnt lgkmcnt(0)
	ds_read2_b32 v[56:57], v97 offset0:33 offset1:41
	ds_read2_b32 v[58:59], v97 offset0:66 offset1:74
	ds_read2_b32 v[60:61], v97 offset0:99 offset1:107
	ds_read2_b32 v[62:63], v97 offset1:8
	ds_read2_b32 v[64:65], v97 offset0:132 offset1:140
	ds_read2_b32 v[66:67], v97 offset0:165 offset1:173
	ds_read2_b32 v[68:69], v97 offset0:198 offset1:206
	ds_read2_b32 v[70:71], v97 offset0:231 offset1:239
	v_lshlrev_b32_e32 v4, 1, v48
	s_waitcnt lgkmcnt(4)
	v_bfe_u32 v3, v62, 16, 1
	v_lshl_add_u64 v[48:49], v[10:11], 0, v[4:5]
	v_add3_u32 v3, v62, v3, s46
	v_bfe_u32 v4, v56, 16, 1
	v_lshrrev_b32_e32 v3, 16, v3
	v_add3_u32 v4, v56, v4, s46
	v_and_or_b32 v52, v4, s47, v3
	v_bfe_u32 v3, v58, 16, 1
	v_add3_u32 v3, v58, v3, s46
	v_bfe_u32 v4, v60, 16, 1
	v_lshrrev_b32_e32 v3, 16, v3
	v_add3_u32 v4, v60, v4, s46
	v_and_or_b32 v53, v4, s47, v3
	s_waitcnt lgkmcnt(3)
	v_bfe_u32 v3, v64, 16, 1
	v_add3_u32 v3, v64, v3, s46
	s_waitcnt lgkmcnt(2)
	v_bfe_u32 v4, v66, 16, 1
	v_lshrrev_b32_e32 v3, 16, v3
	v_add3_u32 v4, v66, v4, s46
	v_and_or_b32 v54, v4, s47, v3
	s_waitcnt lgkmcnt(1)
	v_bfe_u32 v3, v68, 16, 1
	v_add3_u32 v3, v68, v3, s46
	s_waitcnt lgkmcnt(0)
	v_bfe_u32 v4, v70, 16, 1
	v_lshrrev_b32_e32 v3, 16, v3
	v_add3_u32 v4, v70, v4, s46
	v_and_or_b32 v55, v4, s47, v3
	v_or_b32_e32 v3, v51, v96
	v_lshlrev_b32_e32 v4, 9, v3
	v_bfe_u32 v3, v63, 16, 1
	v_lshl_add_u64 v[72:73], v[48:49], 0, v[4:5]
	v_add3_u32 v3, v63, v3, s46
	v_bfe_u32 v4, v57, 16, 1
	v_lshrrev_b32_e32 v3, 16, v3
	v_add3_u32 v4, v57, v4, s46
	global_store_dwordx4 v[72:73], v[52:55], off
	s_nop 1
	v_and_or_b32 v52, v4, s47, v3
	v_bfe_u32 v3, v59, 16, 1
	v_add3_u32 v3, v59, v3, s46
	v_bfe_u32 v4, v61, 16, 1
	v_lshrrev_b32_e32 v3, 16, v3
	v_add3_u32 v4, v61, v4, s46
	v_and_or_b32 v53, v4, s47, v3
	v_bfe_u32 v3, v65, 16, 1
	v_add3_u32 v3, v65, v3, s46
	v_bfe_u32 v4, v67, 16, 1
	v_lshrrev_b32_e32 v3, 16, v3
	v_add3_u32 v4, v67, v4, s46
	v_and_or_b32 v54, v4, s47, v3
	v_bfe_u32 v3, v69, 16, 1
	v_add3_u32 v3, v69, v3, s46
	v_bfe_u32 v4, v71, 16, 1
	v_lshrrev_b32_e32 v3, 16, v3
	v_add3_u32 v4, v71, v4, s46
	v_and_or_b32 v55, v4, s47, v3
	v_or_b32_e32 v3, v51, v98
	v_lshlrev_b32_e32 v4, 9, v3
	v_lshl_add_u64 v[56:57], v[48:49], 0, v[4:5]
	global_store_dwordx4 v[56:57], v[52:55], off
	ds_read2_b32 v[56:57], v97 offset0:49 offset1:57
	ds_read2_b32 v[58:59], v97 offset0:82 offset1:90
	ds_read2_b32 v[60:61], v97 offset0:115 offset1:123
	ds_read2_b32 v[62:63], v97 offset0:16 offset1:24
	ds_read2_b32 v[64:65], v97 offset0:148 offset1:156
	ds_read2_b32 v[66:67], v97 offset0:181 offset1:189
	ds_read2_b32 v[68:69], v97 offset0:214 offset1:222
	ds_read2_b32 v[70:71], v97 offset0:247 offset1:255
	s_waitcnt lgkmcnt(4)
	v_bfe_u32 v3, v62, 16, 1
	v_add3_u32 v3, v62, v3, s46
	v_bfe_u32 v4, v56, 16, 1
	v_lshrrev_b32_e32 v3, 16, v3
	v_add3_u32 v4, v56, v4, s46
	v_and_or_b32 v52, v4, s47, v3
	v_bfe_u32 v3, v58, 16, 1
	v_add3_u32 v3, v58, v3, s46
	v_bfe_u32 v4, v60, 16, 1
	v_lshrrev_b32_e32 v3, 16, v3
	v_add3_u32 v4, v60, v4, s46
	v_and_or_b32 v53, v4, s47, v3
	s_waitcnt lgkmcnt(3)
	v_bfe_u32 v3, v64, 16, 1
	v_add3_u32 v3, v64, v3, s46
	s_waitcnt lgkmcnt(2)
	v_bfe_u32 v4, v66, 16, 1
	v_lshrrev_b32_e32 v3, 16, v3
	v_add3_u32 v4, v66, v4, s46
	v_and_or_b32 v54, v4, s47, v3
	s_waitcnt lgkmcnt(1)
	v_bfe_u32 v3, v68, 16, 1
	v_add3_u32 v3, v68, v3, s46
	s_waitcnt lgkmcnt(0)
	v_bfe_u32 v4, v70, 16, 1
	v_lshrrev_b32_e32 v3, 16, v3
	v_add3_u32 v4, v70, v4, s46
	v_and_or_b32 v55, v4, s47, v3
	v_or_b32_e32 v3, v51, v99
	v_lshlrev_b32_e32 v4, 9, v3
	v_bfe_u32 v3, v63, 16, 1
	v_lshl_add_u64 v[72:73], v[48:49], 0, v[4:5]
	v_add3_u32 v3, v63, v3, s46
	v_bfe_u32 v4, v57, 16, 1
	v_lshrrev_b32_e32 v3, 16, v3
	v_add3_u32 v4, v57, v4, s46
	global_store_dwordx4 v[72:73], v[52:55], off
	s_nop 1
	v_and_or_b32 v52, v4, s47, v3
	v_bfe_u32 v3, v59, 16, 1
	v_add3_u32 v3, v59, v3, s46
	v_bfe_u32 v4, v61, 16, 1
	v_lshrrev_b32_e32 v3, 16, v3
	v_add3_u32 v4, v61, v4, s46
	v_and_or_b32 v53, v4, s47, v3
	v_bfe_u32 v3, v65, 16, 1
	v_add3_u32 v3, v65, v3, s46
	v_bfe_u32 v4, v67, 16, 1
	v_lshrrev_b32_e32 v3, 16, v3
	v_add3_u32 v4, v67, v4, s46
	v_and_or_b32 v54, v4, s47, v3
	v_bfe_u32 v3, v69, 16, 1
	v_add3_u32 v3, v69, v3, s46
	v_bfe_u32 v4, v71, 16, 1
	v_lshrrev_b32_e32 v3, 16, v3
	v_add3_u32 v4, v71, v4, s46
	v_and_or_b32 v55, v4, s47, v3
	v_or_b32_e32 v3, v51, v100
	v_lshlrev_b32_e32 v4, 9, v3
	v_lshl_add_u64 v[48:49], v[48:49], 0, v[4:5]
	global_store_dwordx4 v[48:49], v[52:55], off
	s_waitcnt lgkmcnt(0)

.LBB0_2654:
	s_lshl_b32 s49, s36, 1
	s_lshl_b32 s54, s37, 1
	v_or_b32_e32 v56, s49, v1
	v_or_b32_e32 v57, s54, v0
	v_add_lshl_u32 v4, v56, v3, 10
	v_add_lshl_u32 v53, v57, v48, 10
	v_or_b32_e32 v52, v49, v4
	v_or_b32_e32 v4, v50, v53
	v_lshl_add_u64 v[54:55], v[4:5], 2, s[4:5]
	v_mov_b32_e32 v53, v5
	v_lshl_add_u64 v[52:53], v[52:53], 2, s[4:5]
	global_load_dword v126, v[54:55], off
	global_load_dword v127, v[52:53], off
	v_mad_u64_u32 v[52:53], s[60:61], v57, s40, v[2:3]
	v_mad_u64_u32 v[54:55], s[60:61], v56, s40, v[2:3]
	s_add_i32 s55, s49, 4
	s_add_i32 s60, s54, 4
	v_or_b32_e32 v56, s55, v1
	v_or_b32_e32 v57, s60, v0
	v_add_lshl_u32 v53, v57, v48, 10
	s_add_i32 s55, s49, 8
	s_add_i32 s37, s37, 16
	s_add_i32 s36, s36, 16
	s_add_i32 s48, s48, -16
	v_mov_b32_e32 v142, v52
	v_mov_b32_e32 v143, v54
	v_add_lshl_u32 v4, v56, v3, 10
	v_or_b32_e32 v52, v49, v4
	v_or_b32_e32 v4, v50, v53
	v_lshl_add_u64 v[54:55], v[4:5], 2, s[4:5]
	v_mov_b32_e32 v53, v5
	v_lshl_add_u64 v[52:53], v[52:53], 2, s[4:5]
	global_load_dword v128, v[54:55], off
	global_load_dword v129, v[52:53], off
	v_mad_u64_u32 v[52:53], s[60:61], v57, s40, v[2:3]
	v_mad_u64_u32 v[54:55], s[60:61], v56, s40, v[2:3]
	s_add_i32 s60, s54, 8
	v_or_b32_e32 v56, s55, v1
	v_or_b32_e32 v57, s60, v0
	v_add_lshl_u32 v53, v57, v48, 10
	s_add_i32 s55, s49, 12
	v_mov_b32_e32 v144, v52
	v_mov_b32_e32 v145, v54
	v_add_lshl_u32 v4, v56, v3, 10
	v_or_b32_e32 v52, v49, v4
	v_or_b32_e32 v4, v50, v53
	v_lshl_add_u64 v[54:55], v[4:5], 2, s[4:5]
	v_mov_b32_e32 v53, v5
	v_lshl_add_u64 v[52:53], v[52:53], 2, s[4:5]
	global_load_dword v130, v[54:55], off
	global_load_dword v131, v[52:53], off
	v_mad_u64_u32 v[52:53], s[60:61], v57, s40, v[2:3]
	v_mad_u64_u32 v[54:55], s[60:61], v56, s40, v[2:3]
	s_add_i32 s60, s54, 12
	v_or_b32_e32 v56, s55, v1
	v_or_b32_e32 v57, s60, v0
	v_add_lshl_u32 v53, v57, v48, 10
	s_add_i32 s55, s49, 16
	v_mov_b32_e32 v146, v52
	v_mov_b32_e32 v147, v54
	v_add_lshl_u32 v4, v56, v3, 10
	v_or_b32_e32 v52, v49, v4
	v_or_b32_e32 v4, v50, v53
	v_lshl_add_u64 v[54:55], v[4:5], 2, s[4:5]
	v_mov_b32_e32 v53, v5
	v_lshl_add_u64 v[52:53], v[52:53], 2, s[4:5]
	global_load_dword v132, v[54:55], off
	global_load_dword v133, v[52:53], off
	v_mad_u64_u32 v[52:53], s[60:61], v57, s40, v[2:3]
	v_mad_u64_u32 v[54:55], s[60:61], v56, s40, v[2:3]
	s_add_i32 s60, s54, 16
	v_or_b32_e32 v56, s55, v1
	v_or_b32_e32 v57, s60, v0
	v_add_lshl_u32 v53, v57, v48, 10
	s_add_i32 s55, s49, 20
	v_mov_b32_e32 v148, v52
	v_mov_b32_e32 v149, v54
	v_add_lshl_u32 v4, v56, v3, 10
	v_or_b32_e32 v52, v49, v4
	v_or_b32_e32 v4, v50, v53
	v_lshl_add_u64 v[54:55], v[4:5], 2, s[4:5]
	v_mov_b32_e32 v53, v5
	v_lshl_add_u64 v[52:53], v[52:53], 2, s[4:5]
	global_load_dword v134, v[54:55], off
	global_load_dword v135, v[52:53], off
	v_mad_u64_u32 v[52:53], s[60:61], v57, s40, v[2:3]
	v_mad_u64_u32 v[54:55], s[60:61], v56, s40, v[2:3]
	s_add_i32 s60, s54, 20
	v_or_b32_e32 v56, s55, v1
	v_or_b32_e32 v57, s60, v0
	v_add_lshl_u32 v53, v57, v48, 10
	s_add_i32 s55, s49, 24
	s_add_i32 s49, s49, 28
	v_mov_b32_e32 v150, v52
	v_mov_b32_e32 v151, v54
	v_add_lshl_u32 v4, v56, v3, 10
	v_or_b32_e32 v52, v49, v4
	v_or_b32_e32 v4, v50, v53
	v_lshl_add_u64 v[54:55], v[4:5], 2, s[4:5]
	v_mov_b32_e32 v53, v5
	v_lshl_add_u64 v[52:53], v[52:53], 2, s[4:5]
	global_load_dword v136, v[54:55], off
	global_load_dword v137, v[52:53], off
	v_mad_u64_u32 v[52:53], s[60:61], v57, s40, v[2:3]
	v_mad_u64_u32 v[54:55], s[60:61], v56, s40, v[2:3]
	s_add_i32 s60, s54, 24
	v_or_b32_e32 v56, s55, v1
	v_or_b32_e32 v57, s60, v0
	v_add_lshl_u32 v53, v57, v48, 10
	s_add_i32 s54, s54, 28
	s_cmp_lg_u32 s48, 0
	v_mov_b32_e32 v152, v52
	v_mov_b32_e32 v153, v54
	v_add_lshl_u32 v4, v56, v3, 10
	v_or_b32_e32 v52, v49, v4
	v_or_b32_e32 v4, v50, v53
	v_lshl_add_u64 v[54:55], v[4:5], 2, s[4:5]
	v_mov_b32_e32 v53, v5
	v_lshl_add_u64 v[52:53], v[52:53], 2, s[4:5]
	global_load_dword v138, v[54:55], off
	global_load_dword v139, v[52:53], off
	v_mad_u64_u32 v[52:53], s[60:61], v57, s40, v[2:3]
	v_mad_u64_u32 v[54:55], s[60:61], v56, s40, v[2:3]
	v_or_b32_e32 v56, s49, v1
	v_or_b32_e32 v57, s54, v0
	v_mov_b32_e32 v55, v5
	v_mov_b32_e32 v154, v52
	v_mov_b32_e32 v155, v54
	v_add_lshl_u32 v4, v56, v3, 10
	v_add_lshl_u32 v52, v57, v48, 10
	v_or_b32_e32 v54, v49, v4
	v_or_b32_e32 v4, v50, v52
	v_lshl_add_u64 v[52:53], v[4:5], 2, s[4:5]
	v_lshl_add_u64 v[54:55], v[54:55], 2, s[4:5]
	global_load_dword v140, v[52:53], off
	global_load_dword v141, v[54:55], off
	v_mad_u64_u32 v[52:53], s[54:55], v57, s40, v[2:3]
	v_mad_u64_u32 v[54:55], s[54:55], v56, s40, v[2:3]
	v_mov_b32_e32 v156, v52
	v_mov_b32_e32 v157, v54
	s_waitcnt vmcnt(15)
	ds_write_b32 v142, v126
	s_waitcnt vmcnt(14)
	ds_write_b32 v143, v127
	s_waitcnt vmcnt(13)
	ds_write_b32 v144, v128
	s_waitcnt vmcnt(12)
	ds_write_b32 v145, v129
	s_waitcnt vmcnt(11)
	ds_write_b32 v146, v130
	s_waitcnt vmcnt(10)
	ds_write_b32 v147, v131
	s_waitcnt vmcnt(9)
	ds_write_b32 v148, v132
	s_waitcnt vmcnt(8)
	ds_write_b32 v149, v133
	s_waitcnt vmcnt(7)
	ds_write_b32 v150, v134
	s_waitcnt vmcnt(6)
	ds_write_b32 v151, v135
	s_waitcnt vmcnt(5)
	ds_write_b32 v152, v136
	s_waitcnt vmcnt(4)
	ds_write_b32 v153, v137
	s_waitcnt vmcnt(3)
	ds_write_b32 v154, v138
	s_waitcnt vmcnt(2)
	ds_write_b32 v155, v139
	s_waitcnt vmcnt(1)
	ds_write_b32 v156, v140
	s_waitcnt vmcnt(0)
	ds_write_b32 v157, v141
	s_cbranch_scc1 .LBB0_2654
	s_waitcnt lgkmcnt(0)
	ds_read2_b32 v[56:57], v97 offset0:33 offset1:41
	ds_read2_b32 v[58:59], v97 offset0:66 offset1:74
	ds_read2_b32 v[60:61], v97 offset0:99 offset1:107
	ds_read2_b32 v[62:63], v97 offset1:8
	ds_read2_b32 v[64:65], v97 offset0:132 offset1:140
	ds_read2_b32 v[66:67], v97 offset0:165 offset1:173
	ds_read2_b32 v[68:69], v97 offset0:198 offset1:206
	ds_read2_b32 v[70:71], v97 offset0:231 offset1:239
	v_lshlrev_b32_e32 v4, 1, v48
	s_waitcnt lgkmcnt(4)
	v_bfe_u32 v3, v62, 16, 1
	v_lshl_add_u64 v[48:49], v[12:13], 0, v[4:5]
	v_add3_u32 v3, v62, v3, s46
	v_bfe_u32 v4, v56, 16, 1
	v_lshrrev_b32_e32 v3, 16, v3
	v_add3_u32 v4, v56, v4, s46
	v_and_or_b32 v52, v4, s47, v3
	v_bfe_u32 v3, v58, 16, 1
	v_add3_u32 v3, v58, v3, s46
	v_bfe_u32 v4, v60, 16, 1
	v_lshrrev_b32_e32 v3, 16, v3
	v_add3_u32 v4, v60, v4, s46
	v_and_or_b32 v53, v4, s47, v3
	s_waitcnt lgkmcnt(3)
	v_bfe_u32 v3, v64, 16, 1
	v_add3_u32 v3, v64, v3, s46
	s_waitcnt lgkmcnt(2)
	v_bfe_u32 v4, v66, 16, 1
	v_lshrrev_b32_e32 v3, 16, v3
	v_add3_u32 v4, v66, v4, s46
	v_and_or_b32 v54, v4, s47, v3
	s_waitcnt lgkmcnt(1)
	v_bfe_u32 v3, v68, 16, 1
	v_add3_u32 v3, v68, v3, s46
	s_waitcnt lgkmcnt(0)
	v_bfe_u32 v4, v70, 16, 1
	v_lshrrev_b32_e32 v3, 16, v3
	v_add3_u32 v4, v70, v4, s46
	v_and_or_b32 v55, v4, s47, v3
	v_or_b32_e32 v3, v51, v96
	v_lshlrev_b32_e32 v4, 10, v3
	v_bfe_u32 v3, v63, 16, 1
	v_lshl_add_u64 v[72:73], v[48:49], 0, v[4:5]
	v_add3_u32 v3, v63, v3, s46
	v_bfe_u32 v4, v57, 16, 1
	v_lshrrev_b32_e32 v3, 16, v3
	v_add3_u32 v4, v57, v4, s46
	global_store_dwordx4 v[72:73], v[52:55], off
	s_nop 1
	v_and_or_b32 v52, v4, s47, v3
	v_bfe_u32 v3, v59, 16, 1
	v_add3_u32 v3, v59, v3, s46
	v_bfe_u32 v4, v61, 16, 1
	v_lshrrev_b32_e32 v3, 16, v3
	v_add3_u32 v4, v61, v4, s46
	v_and_or_b32 v53, v4, s47, v3
	v_bfe_u32 v3, v65, 16, 1
	v_add3_u32 v3, v65, v3, s46
	v_bfe_u32 v4, v67, 16, 1
	v_lshrrev_b32_e32 v3, 16, v3
	v_add3_u32 v4, v67, v4, s46
	v_and_or_b32 v54, v4, s47, v3
	v_bfe_u32 v3, v69, 16, 1
	v_add3_u32 v3, v69, v3, s46
	v_bfe_u32 v4, v71, 16, 1
	v_lshrrev_b32_e32 v3, 16, v3
	v_add3_u32 v4, v71, v4, s46
	v_and_or_b32 v55, v4, s47, v3
	v_or_b32_e32 v3, v51, v98
	v_lshlrev_b32_e32 v4, 10, v3
	v_lshl_add_u64 v[56:57], v[48:49], 0, v[4:5]
	global_store_dwordx4 v[56:57], v[52:55], off
	ds_read2_b32 v[56:57], v97 offset0:49 offset1:57
	ds_read2_b32 v[58:59], v97 offset0:82 offset1:90
	ds_read2_b32 v[60:61], v97 offset0:115 offset1:123
	ds_read2_b32 v[62:63], v97 offset0:16 offset1:24
	ds_read2_b32 v[64:65], v97 offset0:148 offset1:156
	ds_read2_b32 v[66:67], v97 offset0:181 offset1:189
	ds_read2_b32 v[68:69], v97 offset0:214 offset1:222
	ds_read2_b32 v[70:71], v97 offset0:247 offset1:255
	s_waitcnt lgkmcnt(4)
	v_bfe_u32 v3, v62, 16, 1
	v_add3_u32 v3, v62, v3, s46
	v_bfe_u32 v4, v56, 16, 1
	v_lshrrev_b32_e32 v3, 16, v3
	v_add3_u32 v4, v56, v4, s46
	v_and_or_b32 v52, v4, s47, v3
	v_bfe_u32 v3, v58, 16, 1
	v_add3_u32 v3, v58, v3, s46
	v_bfe_u32 v4, v60, 16, 1
	v_lshrrev_b32_e32 v3, 16, v3
	v_add3_u32 v4, v60, v4, s46
	v_and_or_b32 v53, v4, s47, v3
	s_waitcnt lgkmcnt(3)
	v_bfe_u32 v3, v64, 16, 1
	v_add3_u32 v3, v64, v3, s46
	s_waitcnt lgkmcnt(2)
	v_bfe_u32 v4, v66, 16, 1
	v_lshrrev_b32_e32 v3, 16, v3
	v_add3_u32 v4, v66, v4, s46
	v_and_or_b32 v54, v4, s47, v3
	s_waitcnt lgkmcnt(1)
	v_bfe_u32 v3, v68, 16, 1
	v_add3_u32 v3, v68, v3, s46
	s_waitcnt lgkmcnt(0)
	v_bfe_u32 v4, v70, 16, 1
	v_lshrrev_b32_e32 v3, 16, v3
	v_add3_u32 v4, v70, v4, s46
	v_and_or_b32 v55, v4, s47, v3
	v_or_b32_e32 v3, v51, v99
	v_lshlrev_b32_e32 v4, 10, v3
	v_bfe_u32 v3, v63, 16, 1
	v_lshl_add_u64 v[72:73], v[48:49], 0, v[4:5]
	v_add3_u32 v3, v63, v3, s46
	v_bfe_u32 v4, v57, 16, 1
	v_lshrrev_b32_e32 v3, 16, v3
	v_add3_u32 v4, v57, v4, s46
	global_store_dwordx4 v[72:73], v[52:55], off
	s_nop 1
	v_and_or_b32 v52, v4, s47, v3
	v_bfe_u32 v3, v59, 16, 1
	v_add3_u32 v3, v59, v3, s46
	v_bfe_u32 v4, v61, 16, 1
	v_lshrrev_b32_e32 v3, 16, v3
	v_add3_u32 v4, v61, v4, s46
	v_and_or_b32 v53, v4, s47, v3
	v_bfe_u32 v3, v65, 16, 1
	v_add3_u32 v3, v65, v3, s46
	v_bfe_u32 v4, v67, 16, 1
	v_lshrrev_b32_e32 v3, 16, v3
	v_add3_u32 v4, v67, v4, s46
	v_and_or_b32 v54, v4, s47, v3
	v_bfe_u32 v3, v69, 16, 1
	v_add3_u32 v3, v69, v3, s46
	v_bfe_u32 v4, v71, 16, 1
	v_lshrrev_b32_e32 v3, 16, v3
	v_add3_u32 v4, v71, v4, s46
	v_and_or_b32 v55, v4, s47, v3
	v_or_b32_e32 v3, v51, v100
	v_lshlrev_b32_e32 v4, 10, v3
	v_lshl_add_u64 v[48:49], v[48:49], 0, v[4:5]
	global_store_dwordx4 v[48:49], v[52:55], off
	s_waitcnt lgkmcnt(0)

.LBB0_2659:
	s_lshl_b32 s48, s11, 1
	s_lshl_b32 s37, s10, 1
	v_or_b32_e32 v50, s48, v4
	v_or_b32_e32 v52, s37, v3
	v_mad_u64_u32 v[50:51], s[54:55], v50, s53, v[48:49]
	v_mad_u64_u32 v[52:53], s[54:55], v52, s53, v[48:49]
	global_load_dword v126, v[50:51], off
	global_load_dword v127, v[52:53], off
	v_or_b32_e32 v54, s37, v1
	v_or_b32_e32 v55, s48, v0
	v_mad_u64_u32 v[50:51], s[54:55], v55, s40, v[2:3]
	v_mad_u64_u32 v[52:53], s[54:55], v54, s40, v[2:3]
	s_add_i32 s54, s48, 4
	s_add_i32 s49, s37, 4
	v_or_b32_e32 v55, s54, v0
	v_or_b32_e32 v54, s49, v1
	s_add_i32 s11, s11, 16
	s_add_i32 s10, s10, 16
	s_add_i32 s36, s36, -16
	v_mov_b32_e32 v142, v50
	v_mov_b32_e32 v143, v52
	v_or_b32_e32 v50, s54, v4
	v_or_b32_e32 v52, s49, v3
	v_mad_u64_u32 v[50:51], s[54:55], v50, s53, v[48:49]
	v_mad_u64_u32 v[52:53], s[54:55], v52, s53, v[48:49]
	global_load_dword v128, v[50:51], off
	global_load_dword v129, v[52:53], off
	v_mad_u64_u32 v[50:51], s[54:55], v55, s40, v[2:3]
	v_mad_u64_u32 v[52:53], s[54:55], v54, s40, v[2:3]
	s_add_i32 s54, s48, 8
	s_add_i32 s49, s37, 8
	v_or_b32_e32 v55, s54, v0
	v_or_b32_e32 v54, s49, v1
	v_mov_b32_e32 v144, v50
	v_mov_b32_e32 v145, v52
	v_or_b32_e32 v50, s54, v4
	v_or_b32_e32 v52, s49, v3
	v_mad_u64_u32 v[50:51], s[54:55], v50, s53, v[48:49]
	v_mad_u64_u32 v[52:53], s[54:55], v52, s53, v[48:49]
	global_load_dword v130, v[50:51], off
	global_load_dword v131, v[52:53], off
	v_mad_u64_u32 v[50:51], s[54:55], v55, s40, v[2:3]
	v_mad_u64_u32 v[52:53], s[54:55], v54, s40, v[2:3]
	s_add_i32 s54, s48, 12
	s_add_i32 s49, s37, 12
	v_or_b32_e32 v55, s54, v0
	v_or_b32_e32 v54, s49, v1
	v_mov_b32_e32 v146, v50
	v_mov_b32_e32 v147, v52
	v_or_b32_e32 v50, s54, v4
	v_or_b32_e32 v52, s49, v3
	v_mad_u64_u32 v[50:51], s[54:55], v50, s53, v[48:49]
	v_mad_u64_u32 v[52:53], s[54:55], v52, s53, v[48:49]
	global_load_dword v132, v[50:51], off
	global_load_dword v133, v[52:53], off
	v_mad_u64_u32 v[50:51], s[54:55], v55, s40, v[2:3]
	v_mad_u64_u32 v[52:53], s[54:55], v54, s40, v[2:3]
	s_add_i32 s54, s48, 16
	s_add_i32 s49, s37, 16
	v_or_b32_e32 v55, s54, v0
	v_or_b32_e32 v54, s49, v1
	v_mov_b32_e32 v148, v50
	v_mov_b32_e32 v149, v52
	v_or_b32_e32 v50, s54, v4
	v_or_b32_e32 v52, s49, v3
	v_mad_u64_u32 v[50:51], s[54:55], v50, s53, v[48:49]
	v_mad_u64_u32 v[52:53], s[54:55], v52, s53, v[48:49]
	global_load_dword v134, v[50:51], off
	global_load_dword v135, v[52:53], off
	v_mad_u64_u32 v[50:51], s[54:55], v55, s40, v[2:3]
	v_mad_u64_u32 v[52:53], s[54:55], v54, s40, v[2:3]
	s_add_i32 s54, s48, 20
	s_add_i32 s49, s37, 20
	v_or_b32_e32 v55, s54, v0
	v_or_b32_e32 v54, s49, v1
	v_mov_b32_e32 v150, v50
	v_mov_b32_e32 v151, v52
	v_or_b32_e32 v50, s54, v4
	v_or_b32_e32 v52, s49, v3
	v_mad_u64_u32 v[50:51], s[54:55], v50, s53, v[48:49]
	v_mad_u64_u32 v[52:53], s[54:55], v52, s53, v[48:49]
	global_load_dword v136, v[50:51], off
	global_load_dword v137, v[52:53], off
	v_mad_u64_u32 v[50:51], s[54:55], v55, s40, v[2:3]
	v_mad_u64_u32 v[52:53], s[54:55], v54, s40, v[2:3]
	s_add_i32 s54, s48, 24
	s_add_i32 s49, s37, 24
	v_or_b32_e32 v55, s54, v0
	v_or_b32_e32 v54, s49, v1
	s_add_i32 s48, s48, 28
	s_add_i32 s37, s37, 28
	s_cmp_lg_u32 s36, 0
	v_mov_b32_e32 v152, v50
	v_mov_b32_e32 v153, v52
	v_or_b32_e32 v50, s54, v4
	v_or_b32_e32 v52, s49, v3
	v_mad_u64_u32 v[50:51], s[54:55], v50, s53, v[48:49]
	v_mad_u64_u32 v[52:53], s[54:55], v52, s53, v[48:49]
	global_load_dword v138, v[50:51], off
	global_load_dword v139, v[52:53], off
	v_mad_u64_u32 v[50:51], s[54:55], v55, s40, v[2:3]
	v_mad_u64_u32 v[52:53], s[54:55], v54, s40, v[2:3]
	v_or_b32_e32 v55, s48, v0
	v_or_b32_e32 v54, s37, v1
	v_mov_b32_e32 v154, v50
	v_mov_b32_e32 v155, v52
	v_or_b32_e32 v50, s48, v4
	v_or_b32_e32 v52, s37, v3
	v_mad_u64_u32 v[50:51], s[48:49], v50, s53, v[48:49]
	v_mad_u64_u32 v[52:53], s[48:49], v52, s53, v[48:49]
	global_load_dword v140, v[50:51], off
	global_load_dword v141, v[52:53], off
	v_mad_u64_u32 v[50:51], s[48:49], v55, s40, v[2:3]
	v_mad_u64_u32 v[52:53], s[48:49], v54, s40, v[2:3]
	v_mov_b32_e32 v156, v50
	v_mov_b32_e32 v157, v52
	s_waitcnt vmcnt(15)
	ds_write_b32 v142, v126
	s_waitcnt vmcnt(14)
	ds_write_b32 v143, v127
	s_waitcnt vmcnt(13)
	ds_write_b32 v144, v128
	s_waitcnt vmcnt(12)
	ds_write_b32 v145, v129
	s_waitcnt vmcnt(11)
	ds_write_b32 v146, v130
	s_waitcnt vmcnt(10)
	ds_write_b32 v147, v131
	s_waitcnt vmcnt(9)
	ds_write_b32 v148, v132
	s_waitcnt vmcnt(8)
	ds_write_b32 v149, v133
	s_waitcnt vmcnt(7)
	ds_write_b32 v150, v134
	s_waitcnt vmcnt(6)
	ds_write_b32 v151, v135
	s_waitcnt vmcnt(5)
	ds_write_b32 v152, v136
	s_waitcnt vmcnt(4)
	ds_write_b32 v153, v137
	s_waitcnt vmcnt(3)
	ds_write_b32 v154, v138
	s_waitcnt vmcnt(2)
	ds_write_b32 v155, v139
	s_waitcnt vmcnt(1)
	ds_write_b32 v156, v140
	s_waitcnt vmcnt(0)
	ds_write_b32 v157, v141
	s_cbranch_scc1 .LBB0_2659
	v_or_b32_e32 v4, v101, v60
	v_cndmask_b32_e64 v3, 0, 1, s[18:19]
	v_mov_b32_e32 v71, 1.0
	v_cmp_ne_u32_e64 s[10:11], 1, v3
	s_andn2_b64 vcc, exec, s[18:19]
	v_lshlrev_b32_e32 v3, 2, v4
	v_mov_b32_e32 v70, 1.0
	s_cbranch_vccnz .LBB0_2662
	global_load_dword v70, v3, s[14:15]

.LBB0_2680:
	s_lshl_b32 s36, s11, 1
	s_lshl_b32 s35, s10, 1
	v_or_b32_e32 v50, s36, v4
	v_or_b32_e32 v52, s35, v3
	v_mad_u64_u32 v[50:51], s[48:49], v50, s53, v[48:49]
	v_mad_u64_u32 v[52:53], s[48:49], v52, s53, v[48:49]
	global_load_dword v126, v[50:51], off
	global_load_dword v127, v[52:53], off
	v_or_b32_e32 v54, s35, v1
	v_or_b32_e32 v55, s36, v0
	v_mad_u64_u32 v[50:51], s[48:49], v55, s40, v[2:3]
	v_mad_u64_u32 v[52:53], s[48:49], v54, s40, v[2:3]
	s_add_i32 s48, s36, 4
	s_add_i32 s37, s35, 4
	v_or_b32_e32 v55, s48, v0
	v_or_b32_e32 v54, s37, v1
	s_add_i32 s11, s11, 16
	s_add_i32 s10, s10, 16
	s_add_i32 s34, s34, -16
	v_mov_b32_e32 v142, v50
	v_mov_b32_e32 v143, v52
	v_or_b32_e32 v50, s48, v4
	v_or_b32_e32 v52, s37, v3
	v_mad_u64_u32 v[50:51], s[48:49], v50, s53, v[48:49]
	v_mad_u64_u32 v[52:53], s[48:49], v52, s53, v[48:49]
	global_load_dword v128, v[50:51], off
	global_load_dword v129, v[52:53], off
	v_mad_u64_u32 v[50:51], s[48:49], v55, s40, v[2:3]
	v_mad_u64_u32 v[52:53], s[48:49], v54, s40, v[2:3]
	s_add_i32 s48, s36, 8
	s_add_i32 s37, s35, 8
	v_or_b32_e32 v55, s48, v0
	v_or_b32_e32 v54, s37, v1
	v_mov_b32_e32 v144, v50
	v_mov_b32_e32 v145, v52
	v_or_b32_e32 v50, s48, v4
	v_or_b32_e32 v52, s37, v3
	v_mad_u64_u32 v[50:51], s[48:49], v50, s53, v[48:49]
	v_mad_u64_u32 v[52:53], s[48:49], v52, s53, v[48:49]
	global_load_dword v130, v[50:51], off
	global_load_dword v131, v[52:53], off
	v_mad_u64_u32 v[50:51], s[48:49], v55, s40, v[2:3]
	v_mad_u64_u32 v[52:53], s[48:49], v54, s40, v[2:3]
	s_add_i32 s48, s36, 12
	s_add_i32 s37, s35, 12
	v_or_b32_e32 v55, s48, v0
	v_or_b32_e32 v54, s37, v1
	v_mov_b32_e32 v146, v50
	v_mov_b32_e32 v147, v52
	v_or_b32_e32 v50, s48, v4
	v_or_b32_e32 v52, s37, v3
	v_mad_u64_u32 v[50:51], s[48:49], v50, s53, v[48:49]
	v_mad_u64_u32 v[52:53], s[48:49], v52, s53, v[48:49]
	global_load_dword v132, v[50:51], off
	global_load_dword v133, v[52:53], off
	v_mad_u64_u32 v[50:51], s[48:49], v55, s40, v[2:3]
	v_mad_u64_u32 v[52:53], s[48:49], v54, s40, v[2:3]
	s_add_i32 s48, s36, 16
	s_add_i32 s37, s35, 16
	v_or_b32_e32 v55, s48, v0
	v_or_b32_e32 v54, s37, v1
	v_mov_b32_e32 v148, v50
	v_mov_b32_e32 v149, v52
	v_or_b32_e32 v50, s48, v4
	v_or_b32_e32 v52, s37, v3
	v_mad_u64_u32 v[50:51], s[48:49], v50, s53, v[48:49]
	v_mad_u64_u32 v[52:53], s[48:49], v52, s53, v[48:49]
	global_load_dword v134, v[50:51], off
	global_load_dword v135, v[52:53], off
	v_mad_u64_u32 v[50:51], s[48:49], v55, s40, v[2:3]
	v_mad_u64_u32 v[52:53], s[48:49], v54, s40, v[2:3]
	s_add_i32 s48, s36, 20
	s_add_i32 s37, s35, 20
	v_or_b32_e32 v55, s48, v0
	v_or_b32_e32 v54, s37, v1
	v_mov_b32_e32 v150, v50
	v_mov_b32_e32 v151, v52
	v_or_b32_e32 v50, s48, v4
	v_or_b32_e32 v52, s37, v3
	v_mad_u64_u32 v[50:51], s[48:49], v50, s53, v[48:49]
	v_mad_u64_u32 v[52:53], s[48:49], v52, s53, v[48:49]
	global_load_dword v136, v[50:51], off
	global_load_dword v137, v[52:53], off
	v_mad_u64_u32 v[50:51], s[48:49], v55, s40, v[2:3]
	v_mad_u64_u32 v[52:53], s[48:49], v54, s40, v[2:3]
	s_add_i32 s48, s36, 24
	s_add_i32 s37, s35, 24
	v_or_b32_e32 v55, s48, v0
	v_or_b32_e32 v54, s37, v1
	s_add_i32 s36, s36, 28
	s_add_i32 s35, s35, 28
	s_cmp_lg_u32 s34, 0
	v_mov_b32_e32 v152, v50
	v_mov_b32_e32 v153, v52
	v_or_b32_e32 v50, s48, v4
	v_or_b32_e32 v52, s37, v3
	v_mad_u64_u32 v[50:51], s[48:49], v50, s53, v[48:49]
	v_mad_u64_u32 v[52:53], s[48:49], v52, s53, v[48:49]
	global_load_dword v138, v[50:51], off
	global_load_dword v139, v[52:53], off
	v_mad_u64_u32 v[50:51], s[48:49], v55, s40, v[2:3]
	v_mad_u64_u32 v[52:53], s[48:49], v54, s40, v[2:3]
	v_or_b32_e32 v55, s36, v0
	v_or_b32_e32 v54, s35, v1
	v_mov_b32_e32 v154, v50
	v_mov_b32_e32 v155, v52
	v_or_b32_e32 v50, s36, v4
	v_or_b32_e32 v52, s35, v3
	v_mad_u64_u32 v[50:51], s[36:37], v50, s53, v[48:49]
	v_mad_u64_u32 v[52:53], s[36:37], v52, s53, v[48:49]
	global_load_dword v140, v[50:51], off
	global_load_dword v141, v[52:53], off
	v_mad_u64_u32 v[50:51], s[36:37], v55, s40, v[2:3]
	v_mad_u64_u32 v[52:53], s[36:37], v54, s40, v[2:3]
	v_mov_b32_e32 v156, v50
	v_mov_b32_e32 v157, v52
	s_waitcnt vmcnt(15)
	ds_write_b32 v142, v126
	s_waitcnt vmcnt(14)
	ds_write_b32 v143, v127
	s_waitcnt vmcnt(13)
	ds_write_b32 v144, v128
	s_waitcnt vmcnt(12)
	ds_write_b32 v145, v129
	s_waitcnt vmcnt(11)
	ds_write_b32 v146, v130
	s_waitcnt vmcnt(10)
	ds_write_b32 v147, v131
	s_waitcnt vmcnt(9)
	ds_write_b32 v148, v132
	s_waitcnt vmcnt(8)
	ds_write_b32 v149, v133
	s_waitcnt vmcnt(7)
	ds_write_b32 v150, v134
	s_waitcnt vmcnt(6)
	ds_write_b32 v151, v135
	s_waitcnt vmcnt(5)
	ds_write_b32 v152, v136
	s_waitcnt vmcnt(4)
	ds_write_b32 v153, v137
	s_waitcnt vmcnt(3)
	ds_write_b32 v154, v138
	s_waitcnt vmcnt(2)
	ds_write_b32 v155, v139
	s_waitcnt vmcnt(1)
	ds_write_b32 v156, v140
	s_waitcnt vmcnt(0)
	ds_write_b32 v157, v141
	s_cbranch_scc1 .LBB0_2680
	v_or_b32_e32 v4, v101, v60
	v_cndmask_b32_e64 v3, 0, 1, s[18:19]
	v_mov_b32_e32 v69, 1.0
	v_cmp_ne_u32_e64 s[10:11], 1, v3
	s_andn2_b64 vcc, exec, s[18:19]
	v_lshlrev_b32_e32 v3, 2, v4
	v_mov_b32_e32 v68, 1.0
	s_cbranch_vccnz .LBB0_2683
	global_load_dword v68, v3, s[14:15]

.LBB0_2701:
	s_lshl_b32 s34, s11, 1
	s_lshl_b32 s25, s10, 1
	v_or_b32_e32 v54, s34, v4
	v_or_b32_e32 v56, s25, v3
	v_mad_i64_i32 v[54:55], s[36:37], v54, s41, v[52:53]
	v_mad_i64_i32 v[56:57], s[36:37], v56, s41, v[52:53]
	global_load_dword v126, v[54:55], off
	global_load_dword v127, v[56:57], off
	v_or_b32_e32 v49, s25, v1
	v_or_b32_e32 v51, s34, v0
	v_mad_u64_u32 v[54:55], s[36:37], v51, s40, v[2:3]
	v_mad_u64_u32 v[56:57], s[36:37], v49, s40, v[2:3]
	s_add_i32 s36, s34, 4
	s_add_i32 s35, s25, 4
	v_or_b32_e32 v51, s36, v0
	v_or_b32_e32 v49, s35, v1
	s_add_i32 s11, s11, 16
	s_add_i32 s10, s10, 16
	s_add_i32 s24, s24, -16
	v_mov_b32_e32 v142, v54
	v_mov_b32_e32 v143, v56
	v_or_b32_e32 v54, s36, v4
	v_or_b32_e32 v56, s35, v3
	v_mad_i64_i32 v[54:55], s[36:37], v54, s41, v[52:53]
	v_mad_i64_i32 v[56:57], s[36:37], v56, s41, v[52:53]
	global_load_dword v128, v[54:55], off
	global_load_dword v129, v[56:57], off
	v_mad_u64_u32 v[54:55], s[36:37], v51, s40, v[2:3]
	v_mad_u64_u32 v[56:57], s[36:37], v49, s40, v[2:3]
	s_add_i32 s36, s34, 8
	s_add_i32 s35, s25, 8
	v_or_b32_e32 v51, s36, v0
	v_or_b32_e32 v49, s35, v1
	v_mov_b32_e32 v144, v54
	v_mov_b32_e32 v145, v56
	v_or_b32_e32 v54, s36, v4
	v_or_b32_e32 v56, s35, v3
	v_mad_i64_i32 v[54:55], s[36:37], v54, s41, v[52:53]
	v_mad_i64_i32 v[56:57], s[36:37], v56, s41, v[52:53]
	global_load_dword v130, v[54:55], off
	global_load_dword v131, v[56:57], off
	v_mad_u64_u32 v[54:55], s[36:37], v51, s40, v[2:3]
	v_mad_u64_u32 v[56:57], s[36:37], v49, s40, v[2:3]
	s_add_i32 s36, s34, 12
	s_add_i32 s35, s25, 12
	v_or_b32_e32 v51, s36, v0
	v_or_b32_e32 v49, s35, v1
	v_mov_b32_e32 v146, v54
	v_mov_b32_e32 v147, v56
	v_or_b32_e32 v54, s36, v4
	v_or_b32_e32 v56, s35, v3
	v_mad_i64_i32 v[54:55], s[36:37], v54, s41, v[52:53]
	v_mad_i64_i32 v[56:57], s[36:37], v56, s41, v[52:53]
	global_load_dword v132, v[54:55], off
	global_load_dword v133, v[56:57], off
	v_mad_u64_u32 v[54:55], s[36:37], v51, s40, v[2:3]
	v_mad_u64_u32 v[56:57], s[36:37], v49, s40, v[2:3]
	s_add_i32 s36, s34, 16
	s_add_i32 s35, s25, 16
	v_or_b32_e32 v51, s36, v0
	v_or_b32_e32 v49, s35, v1
	v_mov_b32_e32 v148, v54
	v_mov_b32_e32 v149, v56
	v_or_b32_e32 v54, s36, v4
	v_or_b32_e32 v56, s35, v3
	v_mad_i64_i32 v[54:55], s[36:37], v54, s41, v[52:53]
	v_mad_i64_i32 v[56:57], s[36:37], v56, s41, v[52:53]
	global_load_dword v134, v[54:55], off
	global_load_dword v135, v[56:57], off
	v_mad_u64_u32 v[54:55], s[36:37], v51, s40, v[2:3]
	v_mad_u64_u32 v[56:57], s[36:37], v49, s40, v[2:3]
	s_add_i32 s36, s34, 20
	s_add_i32 s35, s25, 20
	v_or_b32_e32 v51, s36, v0
	v_or_b32_e32 v49, s35, v1
	v_mov_b32_e32 v150, v54
	v_mov_b32_e32 v151, v56
	v_or_b32_e32 v54, s36, v4
	v_or_b32_e32 v56, s35, v3
	v_mad_i64_i32 v[54:55], s[36:37], v54, s41, v[52:53]
	v_mad_i64_i32 v[56:57], s[36:37], v56, s41, v[52:53]
	global_load_dword v136, v[54:55], off
	global_load_dword v137, v[56:57], off
	v_mad_u64_u32 v[54:55], s[36:37], v51, s40, v[2:3]
	v_mad_u64_u32 v[56:57], s[36:37], v49, s40, v[2:3]
	s_add_i32 s36, s34, 24
	s_add_i32 s35, s25, 24
	v_or_b32_e32 v51, s36, v0
	v_or_b32_e32 v49, s35, v1
	s_add_i32 s34, s34, 28
	s_add_i32 s25, s25, 28
	s_cmp_lg_u32 s24, 0
	v_mov_b32_e32 v152, v54
	v_mov_b32_e32 v153, v56
	v_or_b32_e32 v54, s36, v4
	v_or_b32_e32 v56, s35, v3
	v_mad_i64_i32 v[54:55], s[36:37], v54, s41, v[52:53]
	v_mad_i64_i32 v[56:57], s[36:37], v56, s41, v[52:53]
	global_load_dword v138, v[54:55], off
	global_load_dword v139, v[56:57], off
	v_mad_u64_u32 v[54:55], s[36:37], v51, s40, v[2:3]
	v_mad_u64_u32 v[56:57], s[36:37], v49, s40, v[2:3]
	v_or_b32_e32 v51, s34, v0
	v_or_b32_e32 v49, s25, v1
	v_mov_b32_e32 v154, v54
	v_mov_b32_e32 v155, v56
	v_or_b32_e32 v54, s34, v4
	v_or_b32_e32 v56, s25, v3
	v_mad_i64_i32 v[54:55], s[34:35], v54, s41, v[52:53]
	v_mad_i64_i32 v[56:57], s[34:35], v56, s41, v[52:53]
	global_load_dword v140, v[54:55], off
	global_load_dword v141, v[56:57], off
	v_mad_u64_u32 v[54:55], s[34:35], v51, s40, v[2:3]
	v_mad_u64_u32 v[56:57], s[34:35], v49, s40, v[2:3]
	v_mov_b32_e32 v156, v54
	v_mov_b32_e32 v157, v56
	s_waitcnt vmcnt(15)
	ds_write_b32 v142, v126
	s_waitcnt vmcnt(14)
	ds_write_b32 v143, v127
	s_waitcnt vmcnt(13)
	ds_write_b32 v144, v128
	s_waitcnt vmcnt(12)
	ds_write_b32 v145, v129
	s_waitcnt vmcnt(11)
	ds_write_b32 v146, v130
	s_waitcnt vmcnt(10)
	ds_write_b32 v147, v131
	s_waitcnt vmcnt(9)
	ds_write_b32 v148, v132
	s_waitcnt vmcnt(8)
	ds_write_b32 v149, v133
	s_waitcnt vmcnt(7)
	ds_write_b32 v150, v134
	s_waitcnt vmcnt(6)
	ds_write_b32 v151, v135
	s_waitcnt vmcnt(5)
	ds_write_b32 v152, v136
	s_waitcnt vmcnt(4)
	ds_write_b32 v153, v137
	s_waitcnt vmcnt(3)
	ds_write_b32 v154, v138
	s_waitcnt vmcnt(2)
	ds_write_b32 v155, v139
	s_waitcnt vmcnt(1)
	ds_write_b32 v156, v140
	s_waitcnt vmcnt(0)
	ds_write_b32 v157, v141
	s_cbranch_scc1 .LBB0_2701
	v_or_b32_e32 v52, v50, v101
	v_cndmask_b32_e64 v3, 0, 1, s[8:9]
	v_mov_b32_e32 v71, 1.0
	v_cmp_ne_u32_e64 s[10:11], 1, v3
	s_andn2_b64 vcc, exec, s[8:9]
	v_ashrrev_i32_e32 v53, 31, v52
	v_mov_b32_e32 v70, 1.0
	s_cbranch_vccnz .LBB0_2704
	v_lshl_add_u64 v[54:55], v[52:53], 2, s[90:91]
	global_load_dword v70, v[54:55], off
